# no grid barrier between in-projection part 0 and the RWKV prep: per-row-panel arrival counters (shared with the gate GEMM's), prep items wait for their panel; write-through P stores
# baseline (speedup 1.0000x reference)
.LBB0_161:
	s_add_u32 s8, s6, 0xfffc0080
	s_addc_u32 s9, s7, -1
	s_add_i32 s62, s35, 0xf0
	v_add_u32_e32 v130, s62, v154
	ds_read_b128 v[146:149], v130
	ds_read_b128 v[150:153], v130 offset:1024
	ds_read_b128 v[158:161], v130 offset:2048
	ds_read_b128 v[162:165], v130 offset:3072
	s_cmp_eq_u32 s70, 12
	s_cselect_b32 s11, s1, s9
	s_cselect_b32 s10, s5, s8
	s_cselect_b32 s9, s13, s61
	s_cselect_b32 s8, s22, s23
	v_lshl_add_u64 v[198:199], s[6:7], 0, v[140:141]
	s_add_i32 m0, s87, 0xc000
	ds_read_b128 v[166:169], v156
	ds_read_b128 v[170:173], v156 offset:1024
	ds_read_b128 v[174:177], v156 offset:2048
	ds_read_b128 v[178:181], v156 offset:3072
	ds_read_b128 v[182:185], v156 offset:4096
	ds_read_b128 v[186:189], v156 offset:5120
	ds_read_b128 v[190:193], v156 offset:6144
	ds_read_b128 v[194:197], v156 offset:7168
	global_load_lds_dwordx4 v[198:199], off
	v_lshl_add_u64 v[198:199], s[6:7], 0, v[142:143]
	s_add_i32 m0, s87, 0xe000
	s_nop 0
	global_load_lds_dwordx4 v[198:199], off
	s_waitcnt lgkmcnt(8)
	s_barrier
	s_waitcnt lgkmcnt(0)
	s_setprio 1
	s_waitcnt lgkmcnt(0)
	v_mfma_f32_16x16x32_bf16 v[126:129], v[146:149], v[166:169], v[126:129]
	v_mfma_f32_16x16x32_bf16 v[122:125], v[158:161], v[166:169], v[122:125]
	v_mfma_f32_16x16x32_bf16 v[110:113], v[146:149], v[174:177], v[110:113]
	v_mfma_f32_16x16x32_bf16 v[106:109], v[158:161], v[174:177], v[106:109]
	v_mfma_f32_16x16x32_bf16 v[94:97], v[146:149], v[182:185], v[94:97]
	v_mfma_f32_16x16x32_bf16 v[90:93], v[158:161], v[182:185], v[90:93]
	v_mfma_f32_16x16x32_bf16 v[78:81], v[146:149], v[190:193], v[78:81]
	v_mfma_f32_16x16x32_bf16 v[74:77], v[158:161], v[190:193], v[74:77]
	v_mfma_f32_16x16x32_bf16 v[126:129], v[150:153], v[170:173], v[126:129]
	v_mfma_f32_16x16x32_bf16 v[122:125], v[162:165], v[170:173], v[122:125]
	v_mfma_f32_16x16x32_bf16 v[110:113], v[150:153], v[178:181], v[110:113]
	v_mfma_f32_16x16x32_bf16 v[106:109], v[162:165], v[178:181], v[106:109]
	v_mfma_f32_16x16x32_bf16 v[94:97], v[150:153], v[186:189], v[94:97]
	v_mfma_f32_16x16x32_bf16 v[90:93], v[162:165], v[186:189], v[90:93]
	v_mfma_f32_16x16x32_bf16 v[78:81], v[150:153], v[194:197], v[78:81]
	v_mfma_f32_16x16x32_bf16 v[74:77], v[162:165], v[194:197], v[74:77]
	s_setprio 0
	s_barrier
	s_add_i32 s64, s74, 0xf0
	s_add_i32 s62, s62, s86
	v_add_u32_e32 v130, s64, v154
	v_lshl_add_u64 v[218:219], s[8:9], 0, v[136:137]
	s_mov_b32 m0, s62
	ds_read_b128 v[198:201], v130
	ds_read_b128 v[202:205], v130 offset:1024
	ds_read_b128 v[228:231], v130 offset:2048
	ds_read_b128 v[232:235], v130 offset:3072
	global_load_lds_dwordx4 v[218:219], off
	v_lshl_add_u64 v[224:225], s[8:9], 0, v[138:139]
	s_add_i32 m0, s62, 0x2000
	s_nop 0
	global_load_lds_dwordx4 v[224:225], off
	s_barrier
	s_waitcnt lgkmcnt(0)
	s_setprio 1
	s_waitcnt lgkmcnt(0)
	v_mfma_f32_16x16x32_bf16 v[118:121], v[198:201], v[166:169], v[118:121]
	v_mfma_f32_16x16x32_bf16 v[114:117], v[228:231], v[166:169], v[114:117]
	v_mfma_f32_16x16x32_bf16 v[102:105], v[198:201], v[174:177], v[102:105]
	v_mfma_f32_16x16x32_bf16 v[98:101], v[228:231], v[174:177], v[98:101]
	v_mfma_f32_16x16x32_bf16 v[86:89], v[198:201], v[182:185], v[86:89]
	v_mfma_f32_16x16x32_bf16 v[82:85], v[228:231], v[182:185], v[82:85]
	v_mfma_f32_16x16x32_bf16 v[70:73], v[198:201], v[190:193], v[70:73]
	v_mfma_f32_16x16x32_bf16 v[66:69], v[228:231], v[190:193], v[66:69]
	v_mfma_f32_16x16x32_bf16 v[118:121], v[202:205], v[170:173], v[118:121]
	v_mfma_f32_16x16x32_bf16 v[114:117], v[232:235], v[170:173], v[114:117]
	v_mfma_f32_16x16x32_bf16 v[102:105], v[202:205], v[178:181], v[102:105]
	v_mfma_f32_16x16x32_bf16 v[98:101], v[232:235], v[178:181], v[98:101]
	v_mfma_f32_16x16x32_bf16 v[86:89], v[202:205], v[186:189], v[86:89]
	v_mfma_f32_16x16x32_bf16 v[82:85], v[232:235], v[186:189], v[82:85]
	v_mfma_f32_16x16x32_bf16 v[70:73], v[202:205], v[194:197], v[70:73]
	v_mfma_f32_16x16x32_bf16 v[66:69], v[232:235], v[194:197], v[66:69]
	s_setprio 0
	s_mov_b32 m0, s87
	v_lshl_add_u64 v[236:237], s[10:11], 0, v[136:137]
	s_barrier
	ds_read_b128 v[166:169], v156 offset:16384
	ds_read_b128 v[170:173], v156 offset:17408
	ds_read_b128 v[174:177], v156 offset:18432
	ds_read_b128 v[178:181], v156 offset:19456
	ds_read_b128 v[182:185], v156 offset:20480
	ds_read_b128 v[186:189], v156 offset:21504
	ds_read_b128 v[190:193], v156 offset:22528
	ds_read_b128 v[194:197], v156 offset:23552
	global_load_lds_dwordx4 v[236:237], off
	v_lshl_add_u64 v[238:239], s[10:11], 0, v[138:139]
	s_mov_b32 m0, s50
	s_nop 0
	global_load_lds_dwordx4 v[238:239], off
	s_barrier
	s_waitcnt lgkmcnt(0)
	s_setprio 1
	s_waitcnt lgkmcnt(0)
	v_mfma_f32_16x16x32_bf16 v[62:65], v[146:149], v[166:169], v[62:65]
	v_mfma_f32_16x16x32_bf16 v[58:61], v[158:161], v[166:169], v[58:61]
	v_mfma_f32_16x16x32_bf16 v[46:49], v[146:149], v[174:177], v[46:49]
	v_mfma_f32_16x16x32_bf16 v[42:45], v[158:161], v[174:177], v[42:45]
	v_mfma_f32_16x16x32_bf16 v[30:33], v[146:149], v[182:185], v[30:33]
	v_mfma_f32_16x16x32_bf16 v[26:29], v[158:161], v[182:185], v[26:29]
	v_mfma_f32_16x16x32_bf16 v[14:17], v[146:149], v[190:193], v[14:17]
	v_mfma_f32_16x16x32_bf16 v[10:13], v[158:161], v[190:193], v[10:13]
	v_mfma_f32_16x16x32_bf16 v[62:65], v[150:153], v[170:173], v[62:65]
	v_mfma_f32_16x16x32_bf16 v[58:61], v[162:165], v[170:173], v[58:61]
	v_mfma_f32_16x16x32_bf16 v[46:49], v[150:153], v[178:181], v[46:49]
	v_mfma_f32_16x16x32_bf16 v[42:45], v[162:165], v[178:181], v[42:45]
	v_mfma_f32_16x16x32_bf16 v[30:33], v[150:153], v[186:189], v[30:33]
	v_mfma_f32_16x16x32_bf16 v[26:29], v[162:165], v[186:189], v[26:29]
	v_mfma_f32_16x16x32_bf16 v[14:17], v[150:153], v[194:197], v[14:17]
	v_mfma_f32_16x16x32_bf16 v[10:13], v[162:165], v[194:197], v[10:13]
	s_setprio 0
	s_barrier
	s_add_u32 s62, s8, 0x40000
	s_addc_u32 s63, s9, 0
	s_add_i32 s64, s64, s86
	v_lshl_add_u64 v[146:147], s[62:63], 0, v[136:137]
	s_mov_b32 m0, s64
	s_nop 0
	global_load_lds_dwordx4 v[146:147], off
	v_lshl_add_u64 v[146:147], s[62:63], 0, v[138:139]
	s_add_i32 m0, s64, 0x2000
	s_nop 0
	global_load_lds_dwordx4 v[146:147], off
	s_waitcnt vmcnt(6)
	s_barrier
	s_setprio 1
	v_mfma_f32_16x16x32_bf16 v[54:57], v[198:201], v[166:169], v[54:57]
	v_mfma_f32_16x16x32_bf16 v[50:53], v[228:231], v[166:169], v[50:53]
	v_mfma_f32_16x16x32_bf16 v[38:41], v[198:201], v[174:177], v[38:41]
	v_mfma_f32_16x16x32_bf16 v[34:37], v[228:231], v[174:177], v[34:37]
	v_mfma_f32_16x16x32_bf16 v[22:25], v[198:201], v[182:185], v[22:25]
	v_mfma_f32_16x16x32_bf16 v[18:21], v[228:231], v[182:185], v[18:21]
	v_mfma_f32_16x16x32_bf16 v[6:9], v[198:201], v[190:193], v[6:9]
	v_mfma_f32_16x16x32_bf16 v[2:5], v[228:231], v[190:193], v[2:5]
	v_mfma_f32_16x16x32_bf16 v[54:57], v[202:205], v[170:173], v[54:57]
	v_mfma_f32_16x16x32_bf16 v[50:53], v[232:235], v[170:173], v[50:53]
	v_mfma_f32_16x16x32_bf16 v[38:41], v[202:205], v[178:181], v[38:41]
	v_mfma_f32_16x16x32_bf16 v[34:37], v[232:235], v[178:181], v[34:37]
	v_mfma_f32_16x16x32_bf16 v[22:25], v[202:205], v[186:189], v[22:25]
	v_mfma_f32_16x16x32_bf16 v[18:21], v[232:235], v[186:189], v[18:21]
	v_mfma_f32_16x16x32_bf16 v[6:9], v[202:205], v[194:197], v[6:9]
	v_mfma_f32_16x16x32_bf16 v[2:5], v[232:235], v[194:197], v[2:5]
	s_setprio 0
	s_add_i32 s62, s75, 0xf0
	v_add_u32_e32 v130, s62, v154
	s_barrier
	ds_read_b128 v[146:149], v130
	ds_read_b128 v[150:153], v130 offset:1024
	ds_read_b128 v[158:161], v130 offset:2048
	ds_read_b128 v[162:165], v130 offset:3072
	s_add_u32 s10, s10, 0x40000
	s_addc_u32 s11, s11, 0
	s_mov_b32 m0, s51
	v_lshl_add_u64 v[198:199], s[10:11], 0, v[136:137]
	ds_read_b128 v[166:169], v156 offset:32768
	ds_read_b128 v[170:173], v156 offset:33792
	ds_read_b128 v[174:177], v156 offset:34816
	ds_read_b128 v[178:181], v156 offset:35840
	ds_read_b128 v[182:185], v156 offset:36864
	ds_read_b128 v[186:189], v156 offset:37888
	ds_read_b128 v[190:193], v156 offset:38912
	ds_read_b128 v[194:197], v156 offset:39936
	global_load_lds_dwordx4 v[198:199], off
	v_lshl_add_u64 v[198:199], s[10:11], 0, v[138:139]
	s_mov_b32 m0, s52
	s_nop 0
	global_load_lds_dwordx4 v[198:199], off
	s_waitcnt lgkmcnt(8)
	s_barrier
	s_waitcnt lgkmcnt(0)
	s_setprio 1
	s_waitcnt lgkmcnt(0)
	v_mfma_f32_16x16x32_bf16 v[126:129], v[146:149], v[166:169], v[126:129]
	v_mfma_f32_16x16x32_bf16 v[122:125], v[158:161], v[166:169], v[122:125]
	v_mfma_f32_16x16x32_bf16 v[110:113], v[146:149], v[174:177], v[110:113]
	v_mfma_f32_16x16x32_bf16 v[106:109], v[158:161], v[174:177], v[106:109]
	v_mfma_f32_16x16x32_bf16 v[94:97], v[146:149], v[182:185], v[94:97]
	v_mfma_f32_16x16x32_bf16 v[90:93], v[158:161], v[182:185], v[90:93]
	v_mfma_f32_16x16x32_bf16 v[78:81], v[146:149], v[190:193], v[78:81]
	v_mfma_f32_16x16x32_bf16 v[74:77], v[158:161], v[190:193], v[74:77]
	v_mfma_f32_16x16x32_bf16 v[126:129], v[150:153], v[170:173], v[126:129]
	v_mfma_f32_16x16x32_bf16 v[122:125], v[162:165], v[170:173], v[122:125]
	v_mfma_f32_16x16x32_bf16 v[110:113], v[150:153], v[178:181], v[110:113]
	v_mfma_f32_16x16x32_bf16 v[106:109], v[162:165], v[178:181], v[106:109]
	v_mfma_f32_16x16x32_bf16 v[94:97], v[150:153], v[186:189], v[94:97]
	v_mfma_f32_16x16x32_bf16 v[90:93], v[162:165], v[186:189], v[90:93]
	v_mfma_f32_16x16x32_bf16 v[78:81], v[150:153], v[194:197], v[78:81]
	v_mfma_f32_16x16x32_bf16 v[74:77], v[162:165], v[194:197], v[74:77]
	s_setprio 0
	s_barrier
	s_add_i32 s10, s33, 0xf0
	s_add_i32 s11, s62, s86
	v_add_u32_e32 v130, s10, v154
	v_lshl_add_u64 v[218:219], v[218:219], 0, s[68:69]
	s_mov_b32 m0, s11
	ds_read_b128 v[198:201], v130
	ds_read_b128 v[202:205], v130 offset:1024
	ds_read_b128 v[228:231], v130 offset:2048
	ds_read_b128 v[232:235], v130 offset:3072
	global_load_lds_dwordx4 v[218:219], off
	v_lshl_add_u64 v[218:219], v[224:225], 0, s[68:69]
	s_add_i32 m0, s11, 0x2000
	s_nop 0
	global_load_lds_dwordx4 v[218:219], off
	s_barrier
	s_waitcnt lgkmcnt(0)
	s_setprio 1
	s_waitcnt lgkmcnt(0)
	v_mfma_f32_16x16x32_bf16 v[118:121], v[198:201], v[166:169], v[118:121]
	v_mfma_f32_16x16x32_bf16 v[114:117], v[228:231], v[166:169], v[114:117]
	v_mfma_f32_16x16x32_bf16 v[102:105], v[198:201], v[174:177], v[102:105]
	v_mfma_f32_16x16x32_bf16 v[98:101], v[228:231], v[174:177], v[98:101]
	v_mfma_f32_16x16x32_bf16 v[86:89], v[198:201], v[182:185], v[86:89]
	v_mfma_f32_16x16x32_bf16 v[82:85], v[228:231], v[182:185], v[82:85]
	v_mfma_f32_16x16x32_bf16 v[70:73], v[198:201], v[190:193], v[70:73]
	v_mfma_f32_16x16x32_bf16 v[66:69], v[228:231], v[190:193], v[66:69]
	v_mfma_f32_16x16x32_bf16 v[118:121], v[202:205], v[170:173], v[118:121]
	v_mfma_f32_16x16x32_bf16 v[114:117], v[232:235], v[170:173], v[114:117]
	v_mfma_f32_16x16x32_bf16 v[102:105], v[202:205], v[178:181], v[102:105]
	v_mfma_f32_16x16x32_bf16 v[98:101], v[232:235], v[178:181], v[98:101]
	v_mfma_f32_16x16x32_bf16 v[86:89], v[202:205], v[186:189], v[86:89]
	v_mfma_f32_16x16x32_bf16 v[82:85], v[232:235], v[186:189], v[82:85]
	v_mfma_f32_16x16x32_bf16 v[70:73], v[202:205], v[194:197], v[70:73]
	v_mfma_f32_16x16x32_bf16 v[66:69], v[232:235], v[194:197], v[66:69]
	s_setprio 0
	s_mov_b32 m0, s54
	v_lshl_add_u64 v[218:219], v[236:237], 0, s[68:69]
	s_barrier
	ds_read_b128 v[166:169], v156 offset:49152
	ds_read_b128 v[170:173], v156 offset:50176
	ds_read_b128 v[174:177], v156 offset:51200
	ds_read_b128 v[178:181], v156 offset:52224
	ds_read_b128 v[182:185], v156 offset:53248
	ds_read_b128 v[186:189], v156 offset:54272
	ds_read_b128 v[190:193], v156 offset:55296
	ds_read_b128 v[194:197], v156 offset:56320
	global_load_lds_dwordx4 v[218:219], off
	v_lshl_add_u64 v[218:219], v[238:239], 0, s[68:69]
	s_mov_b32 m0, s55
	s_nop 0
	global_load_lds_dwordx4 v[218:219], off
	s_barrier
	s_waitcnt lgkmcnt(0)
	s_setprio 1
	s_waitcnt lgkmcnt(0)
	v_mfma_f32_16x16x32_bf16 v[62:65], v[146:149], v[166:169], v[62:65]
	v_mfma_f32_16x16x32_bf16 v[58:61], v[158:161], v[166:169], v[58:61]
	v_mfma_f32_16x16x32_bf16 v[46:49], v[146:149], v[174:177], v[46:49]
	v_mfma_f32_16x16x32_bf16 v[42:45], v[158:161], v[174:177], v[42:45]
	v_mfma_f32_16x16x32_bf16 v[30:33], v[146:149], v[182:185], v[30:33]
	v_mfma_f32_16x16x32_bf16 v[26:29], v[158:161], v[182:185], v[26:29]
	v_mfma_f32_16x16x32_bf16 v[14:17], v[146:149], v[190:193], v[14:17]
	v_mfma_f32_16x16x32_bf16 v[10:13], v[158:161], v[190:193], v[10:13]
	v_mfma_f32_16x16x32_bf16 v[62:65], v[150:153], v[170:173], v[62:65]
	v_mfma_f32_16x16x32_bf16 v[58:61], v[162:165], v[170:173], v[58:61]
	v_mfma_f32_16x16x32_bf16 v[46:49], v[150:153], v[178:181], v[46:49]
	v_mfma_f32_16x16x32_bf16 v[42:45], v[162:165], v[178:181], v[42:45]
	v_mfma_f32_16x16x32_bf16 v[30:33], v[150:153], v[186:189], v[30:33]
	v_mfma_f32_16x16x32_bf16 v[26:29], v[162:165], v[186:189], v[26:29]
	v_mfma_f32_16x16x32_bf16 v[14:17], v[150:153], v[194:197], v[14:17]
	v_mfma_f32_16x16x32_bf16 v[10:13], v[162:165], v[194:197], v[10:13]
	s_setprio 0
	s_barrier
	s_add_u32 s8, s8, 0x40080
	s_addc_u32 s9, s9, 0
	s_add_i32 s10, s10, s86
	v_lshl_add_u64 v[146:147], s[8:9], 0, v[136:137]
	s_mov_b32 m0, s10
	s_nop 0
	global_load_lds_dwordx4 v[146:147], off
	v_lshl_add_u64 v[146:147], s[8:9], 0, v[138:139]
	s_add_i32 m0, s10, 0x2000
	s_nop 0
	global_load_lds_dwordx4 v[146:147], off
	s_waitcnt vmcnt(6)
	s_barrier
	s_setprio 1
	v_mfma_f32_16x16x32_bf16 v[54:57], v[198:201], v[166:169], v[54:57]
	v_mfma_f32_16x16x32_bf16 v[50:53], v[228:231], v[166:169], v[50:53]
	v_mfma_f32_16x16x32_bf16 v[38:41], v[198:201], v[174:177], v[38:41]
	v_mfma_f32_16x16x32_bf16 v[34:37], v[228:231], v[174:177], v[34:37]
	v_mfma_f32_16x16x32_bf16 v[22:25], v[198:201], v[182:185], v[22:25]
	v_mfma_f32_16x16x32_bf16 v[18:21], v[228:231], v[182:185], v[18:21]
	v_mfma_f32_16x16x32_bf16 v[6:9], v[198:201], v[190:193], v[6:9]
	v_mfma_f32_16x16x32_bf16 v[2:5], v[228:231], v[190:193], v[2:5]
	v_mfma_f32_16x16x32_bf16 v[54:57], v[202:205], v[170:173], v[54:57]
	v_mfma_f32_16x16x32_bf16 v[50:53], v[232:235], v[170:173], v[50:53]
	v_mfma_f32_16x16x32_bf16 v[38:41], v[202:205], v[178:181], v[38:41]
	v_mfma_f32_16x16x32_bf16 v[34:37], v[232:235], v[178:181], v[34:37]
	v_mfma_f32_16x16x32_bf16 v[22:25], v[202:205], v[186:189], v[22:25]
	v_mfma_f32_16x16x32_bf16 v[18:21], v[232:235], v[186:189], v[18:21]
	v_mfma_f32_16x16x32_bf16 v[6:9], v[202:205], v[194:197], v[6:9]
	v_mfma_f32_16x16x32_bf16 v[2:5], v[232:235], v[194:197], v[2:5]
	s_setprio 0
	s_add_i32 s70, s70, 2
	s_add_u32 s6, s6, 0x100
	s_addc_u32 s7, s7, 0
	s_add_u32 s23, s23, 0x100
	s_addc_u32 s61, s61, 0
	s_cmp_gt_u32 s70, 13
	s_barrier
	s_cbranch_scc0 .LBB0_161
	s_lshl_b32 s13, s4, 8
	s_add_i32 s13, s13, s53
	v_lshl_or_b32 v158, s0, 8, v155
	v_or_b32_e32 v148, s13, v1
	v_ashrrev_i32_e32 v149, 31, v148
	v_add_u32_e32 v146, s81, v158
	v_lshlrev_b64 v[150:151], 11, v[148:149]
	v_cmp_gt_i32_e64 s[0:1], s37, v148
	v_cmp_lt_i32_e64 s[10:11], s38, v146
	s_and_saveexec_b64 s[4:5], s[10:11]
	s_xor_b64 s[4:5], exec, s[4:5]
	s_cbranch_execz .LBB0_166
	v_cmp_gt_u32_e32 vcc, s39, v146
	s_and_saveexec_b64 s[6:7], vcc
	s_cbranch_execz .LBB0_165
	v_mul_f32_e32 v130, 0xbfb8aa3b, v126
	v_exp_f32_e32 v130, v130
	s_nop 0
	v_add_f32_e32 v130, 1.0, v130
	v_div_scale_f32 v147, s[8:9], v130, v130, v126
	v_rcp_f32_e32 v149, v147
	s_nop 0
	v_fma_f32 v152, -v147, v149, 1.0
	v_fmac_f32_e32 v149, v152, v149
	v_div_scale_f32 v152, vcc, v126, v130, v126
	v_mul_f32_e32 v153, v152, v149
	v_fma_f32 v157, -v147, v153, v152
	v_fmac_f32_e32 v153, v157, v149
	v_fma_f32 v147, -v147, v153, v152
	v_div_fmas_f32 v147, v147, v149, v153
	v_div_fixup_f32 v130, v147, v130, v126
	v_mul_f32_e32 v147, 0xbfb8aa3b, v127
	v_exp_f32_e32 v147, v147
	s_nop 0
	v_add_f32_e32 v147, 1.0, v147
	v_div_scale_f32 v149, s[8:9], v147, v147, v127
	v_rcp_f32_e32 v152, v149
	s_nop 0
	v_fma_f32 v153, -v149, v152, 1.0
	v_fmac_f32_e32 v152, v153, v152
	v_div_scale_f32 v153, vcc, v127, v147, v127
	v_mul_f32_e32 v157, v153, v152
	v_fma_f32 v159, -v149, v157, v153
	v_fmac_f32_e32 v157, v159, v152
	v_fma_f32 v149, -v149, v157, v153
	v_div_fmas_f32 v149, v149, v152, v157
	v_div_fixup_f32 v147, v149, v147, v127
	v_cvt_pk_bf16_f32 v152, v130, v147
	v_mul_f32_e32 v130, 0xbfb8aa3b, v128
	v_exp_f32_e32 v130, v130
	s_nop 0
	v_add_f32_e32 v130, 1.0, v130
	v_div_scale_f32 v147, s[8:9], v130, v130, v128
	v_rcp_f32_e32 v149, v147
	s_nop 0
	v_fma_f32 v153, -v147, v149, 1.0
	v_fmac_f32_e32 v149, v153, v149
	v_div_scale_f32 v153, vcc, v128, v130, v128
	v_mul_f32_e32 v157, v153, v149
	v_fma_f32 v159, -v147, v157, v153
	v_fmac_f32_e32 v157, v159, v149
	v_fma_f32 v147, -v147, v157, v153
	v_div_fmas_f32 v147, v147, v149, v157
	v_div_fixup_f32 v130, v147, v130, v128
	v_mul_f32_e32 v147, 0xbfb8aa3b, v129
	v_exp_f32_e32 v147, v147
	s_nop 0
	v_add_f32_e32 v147, 1.0, v147
	v_div_scale_f32 v149, s[8:9], v147, v147, v129
	v_rcp_f32_e32 v153, v149
	s_nop 0
	v_fma_f32 v157, -v149, v153, 1.0
	v_fmac_f32_e32 v153, v157, v153
	v_div_scale_f32 v157, vcc, v129, v147, v129
	v_mul_f32_e32 v159, v157, v153
	v_fma_f32 v160, -v149, v159, v157
	v_fmac_f32_e32 v159, v160, v153
	v_fma_f32 v149, -v149, v159, v157
	v_div_fmas_f32 v149, v149, v153, v159
	v_div_fixup_f32 v147, v149, v147, v129
	v_cvt_pk_bf16_f32 v153, v130, v147
	v_lshl_add_u64 v[160:161], s[30:31], 0, v[150:151]
	v_mov_b32_e32 v147, v131
	v_lshl_add_u64 v[160:161], v[146:147], 1, v[160:161]
	v_add_co_u32_e32 v160, vcc, 0xfffff000, v160
	s_nop 1
	v_addc_co_u32_e32 v161, vcc, -1, v161, vcc
	global_store_dwordx2 v[160:161], v[152:153], off offset:-256 sc1

.LBB0_166:
	s_or_saveexec_b64 s[4:5], s[4:5]
	s_ashr_i32 s6, s13, 7
	s_and_b32 s61, s6, -2
	v_mad_i64_i32 v[152:153], s[6:7], v148, s36, 0
	v_bitop3_b32 v157, s13, v207, v1 bitop3:0xc8
	v_lshl_add_u64 v[152:153], s[28:29], 0, v[152:153]
	v_ashrrev_i32_e32 v147, 31, v146
	v_add_u32_e32 v149, 0xfffff980, v146
	s_xor_b64 exec, exec, s[4:5]
	s_cbranch_execz .LBB0_170
	v_cmp_gt_u32_e32 vcc, s91, v149
	v_lshl_add_u64 v[160:161], v[146:147], 2, v[152:153]
	s_and_b64 s[8:9], vcc, s[0:1]
	global_store_dwordx4 v[160:161], v[126:129], off sc1
	s_and_saveexec_b64 s[6:7], s[8:9]
	s_cbranch_execz .LBB0_169
	s_or_b32 s8, s61, s80
	v_cmp_gt_u32_e32 vcc, s40, v146
	v_lshl_or_b32 v162, s8, 8, v157
	v_ashrrev_i32_e32 v163, 31, v162
	v_cndmask_b32_e32 v130, v208, v209, vcc
	v_lshl_add_u64 v[160:161], s[16:17], 0, v[130:131]
	v_lshlrev_b64 v[162:163], 9, v[162:163]
	v_cndmask_b32_e32 v130, v210, v211, vcc
	v_lshl_add_u64 v[160:161], v[160:161], 0, v[162:163]
	v_add_u32_e32 v162, v130, v146
	v_ashrrev_i32_e32 v163, 31, v162
	v_lshl_add_u64 v[160:161], v[162:163], 2, v[160:161]
	global_store_dwordx4 v[160:161], v[126:129], off sc1

.LBB0_170:
	s_or_b64 exec, exec, s[4:5]
	v_add3_u32 v126, s81, v158, 16
	v_cmp_lt_i32_e64 s[8:9], s38, v126
	s_and_saveexec_b64 s[4:5], s[8:9]
	s_xor_b64 s[4:5], exec, s[4:5]
	s_mov_b32 s64, s44
	s_cbranch_execz .LBB0_174
	v_cmp_gt_u32_e32 vcc, s39, v126
	s_and_saveexec_b64 s[6:7], vcc
	s_cbranch_execz .LBB0_173
	v_mul_f32_e32 v127, 0xbfb8aa3b, v122
	v_exp_f32_e32 v127, v127
	s_nop 0
	v_add_f32_e32 v127, 1.0, v127
	v_div_scale_f32 v128, s[22:23], v127, v127, v122
	v_rcp_f32_e32 v129, v128
	s_nop 0
	v_fma_f32 v130, -v128, v129, 1.0
	v_fmac_f32_e32 v129, v130, v129
	v_div_scale_f32 v130, vcc, v122, v127, v122
	v_mul_f32_e32 v158, v130, v129
	v_fma_f32 v159, -v128, v158, v130
	v_fmac_f32_e32 v158, v159, v129
	v_fma_f32 v128, -v128, v158, v130
	v_div_fmas_f32 v128, v128, v129, v158
	v_div_fixup_f32 v127, v128, v127, v122
	v_mul_f32_e32 v128, 0xbfb8aa3b, v123
	v_exp_f32_e32 v128, v128
	s_nop 0
	v_add_f32_e32 v128, 1.0, v128
	v_div_scale_f32 v129, s[22:23], v128, v128, v123
	v_rcp_f32_e32 v130, v129
	s_nop 0
	v_fma_f32 v158, -v129, v130, 1.0
	v_fmac_f32_e32 v130, v158, v130
	v_div_scale_f32 v158, vcc, v123, v128, v123
	v_mul_f32_e32 v159, v158, v130
	v_fma_f32 v160, -v129, v159, v158
	v_fmac_f32_e32 v159, v160, v130
	v_fma_f32 v129, -v129, v159, v158
	v_div_fmas_f32 v129, v129, v130, v159
	v_div_fixup_f32 v128, v129, v128, v123
	v_cvt_pk_bf16_f32 v128, v127, v128
	v_mul_f32_e32 v127, 0xbfb8aa3b, v124
	v_exp_f32_e32 v127, v127
	s_nop 0
	v_add_f32_e32 v127, 1.0, v127
	v_div_scale_f32 v129, s[22:23], v127, v127, v124
	v_rcp_f32_e32 v130, v129
	s_nop 0
	v_fma_f32 v158, -v129, v130, 1.0
	v_fmac_f32_e32 v130, v158, v130
	v_div_scale_f32 v158, vcc, v124, v127, v124
	v_mul_f32_e32 v159, v158, v130
	v_fma_f32 v160, -v129, v159, v158
	v_fmac_f32_e32 v159, v160, v130
	v_fma_f32 v129, -v129, v159, v158
	v_div_fmas_f32 v129, v129, v130, v159
	v_div_fixup_f32 v127, v129, v127, v124
	v_mul_f32_e32 v129, 0xbfb8aa3b, v125
	v_exp_f32_e32 v129, v129
	s_nop 0
	v_add_f32_e32 v129, 1.0, v129
	v_div_scale_f32 v130, s[22:23], v129, v129, v125
	v_rcp_f32_e32 v158, v130
	s_nop 0
	v_fma_f32 v159, -v130, v158, 1.0
	v_fmac_f32_e32 v158, v159, v158
	v_div_scale_f32 v159, vcc, v125, v129, v125
	v_mul_f32_e32 v160, v159, v158
	v_fma_f32 v161, -v130, v160, v159
	v_fmac_f32_e32 v160, v161, v158
	v_fma_f32 v130, -v130, v160, v159
	v_div_fmas_f32 v130, v130, v158, v160
	v_div_fixup_f32 v129, v130, v129, v125
	v_cvt_pk_bf16_f32 v129, v127, v129
	v_lshl_add_u64 v[158:159], s[30:31], 0, v[150:151]
	v_mov_b32_e32 v127, v131
	v_lshl_add_u64 v[158:159], v[126:127], 1, v[158:159]
	v_add_co_u32_e32 v158, vcc, 0xfffff000, v158
	s_nop 1
	v_addc_co_u32_e32 v159, vcc, -1, v159, vcc
	global_store_dwordx2 v[158:159], v[128:129], off offset:-256 sc1

.LBB0_174:
	s_or_saveexec_b64 s[4:5], s[4:5]
	v_ashrrev_i32_e32 v127, 31, v126
	v_add_u32_e32 v128, 0xfffff980, v126
	s_xor_b64 exec, exec, s[4:5]
	s_cbranch_execz .LBB0_178
	v_cmp_gt_u32_e32 vcc, s91, v128
	v_lshl_add_u64 v[158:159], v[126:127], 2, v[152:153]
	s_and_b64 s[22:23], vcc, s[0:1]
	global_store_dwordx4 v[158:159], v[122:125], off sc1
	s_and_saveexec_b64 s[6:7], s[22:23]
	s_cbranch_execz .LBB0_177
	s_or_b32 s22, s61, s80
	v_cmp_gt_u32_e32 vcc, s40, v126
	v_lshl_or_b32 v160, s22, 8, v157
	v_ashrrev_i32_e32 v161, 31, v160
	v_cndmask_b32_e32 v130, v208, v209, vcc
	v_lshl_add_u64 v[158:159], s[16:17], 0, v[130:131]
	v_lshlrev_b64 v[160:161], 9, v[160:161]
	v_cndmask_b32_e32 v129, v210, v211, vcc
	v_lshl_add_u64 v[158:159], v[158:159], 0, v[160:161]
	v_add_u32_e32 v160, v129, v126
	v_ashrrev_i32_e32 v161, 31, v160
	v_lshl_add_u64 v[158:159], v[160:161], 2, v[158:159]
	global_store_dwordx4 v[158:159], v[122:125], off sc1

.LBB0_178:
	s_or_b64 exec, exec, s[4:5]
	v_add_u32_e32 v122, 0x80, v146
	v_cmp_lt_i32_e64 s[6:7], s38, v122
	s_and_saveexec_b64 s[4:5], s[6:7]
	s_xor_b64 s[4:5], exec, s[4:5]
	s_cbranch_execz .LBB0_182
	v_cmp_gt_u32_e32 vcc, s39, v122
	s_and_saveexec_b64 s[70:71], vcc
	s_cbranch_execz .LBB0_181
	v_mul_f32_e32 v123, 0xbfb8aa3b, v118
	v_exp_f32_e32 v123, v123
	s_nop 0
	v_add_f32_e32 v123, 1.0, v123
	v_div_scale_f32 v124, s[22:23], v123, v123, v118
	v_rcp_f32_e32 v125, v124
	s_nop 0
	v_fma_f32 v129, -v124, v125, 1.0
	v_fmac_f32_e32 v125, v129, v125
	v_div_scale_f32 v129, vcc, v118, v123, v118
	v_mul_f32_e32 v130, v129, v125
	v_fma_f32 v158, -v124, v130, v129
	v_fmac_f32_e32 v130, v158, v125
	v_fma_f32 v124, -v124, v130, v129
	v_div_fmas_f32 v124, v124, v125, v130
	v_div_fixup_f32 v123, v124, v123, v118
	v_mul_f32_e32 v124, 0xbfb8aa3b, v119
	v_exp_f32_e32 v124, v124
	s_nop 0
	v_add_f32_e32 v124, 1.0, v124
	v_div_scale_f32 v125, s[22:23], v124, v124, v119
	v_rcp_f32_e32 v129, v125
	s_nop 0
	v_fma_f32 v130, -v125, v129, 1.0
	v_fmac_f32_e32 v129, v130, v129
	v_div_scale_f32 v130, vcc, v119, v124, v119
	v_mul_f32_e32 v158, v130, v129
	v_fma_f32 v159, -v125, v158, v130
	v_fmac_f32_e32 v158, v159, v129
	v_fma_f32 v125, -v125, v158, v130
	v_div_fmas_f32 v125, v125, v129, v158
	v_div_fixup_f32 v124, v125, v124, v119
	v_cvt_pk_bf16_f32 v124, v123, v124
	v_mul_f32_e32 v123, 0xbfb8aa3b, v120
	v_exp_f32_e32 v123, v123
	s_nop 0
	v_add_f32_e32 v123, 1.0, v123
	v_div_scale_f32 v125, s[22:23], v123, v123, v120
	v_rcp_f32_e32 v129, v125
	s_nop 0
	v_fma_f32 v130, -v125, v129, 1.0
	v_fmac_f32_e32 v129, v130, v129
	v_div_scale_f32 v130, vcc, v120, v123, v120
	v_mul_f32_e32 v158, v130, v129
	v_fma_f32 v159, -v125, v158, v130
	v_fmac_f32_e32 v158, v159, v129
	v_fma_f32 v125, -v125, v158, v130
	v_div_fmas_f32 v125, v125, v129, v158
	v_div_fixup_f32 v123, v125, v123, v120
	v_mul_f32_e32 v125, 0xbfb8aa3b, v121
	v_exp_f32_e32 v125, v125
	s_nop 0
	v_add_f32_e32 v125, 1.0, v125
	v_div_scale_f32 v129, s[22:23], v125, v125, v121
	v_rcp_f32_e32 v130, v129
	s_nop 0
	v_fma_f32 v158, -v129, v130, 1.0
	v_fmac_f32_e32 v130, v158, v130
	v_div_scale_f32 v158, vcc, v121, v125, v121
	v_mul_f32_e32 v159, v158, v130
	v_fma_f32 v160, -v129, v159, v158
	v_fmac_f32_e32 v159, v160, v130
	v_fma_f32 v129, -v129, v159, v158
	v_div_fmas_f32 v129, v129, v130, v159
	v_div_fixup_f32 v125, v129, v125, v121
	v_cvt_pk_bf16_f32 v125, v123, v125
	v_lshl_add_u64 v[158:159], s[30:31], 0, v[150:151]
	v_mov_b32_e32 v123, v131
	v_lshl_add_u64 v[158:159], v[122:123], 1, v[158:159]
	v_add_co_u32_e32 v158, vcc, 0xfffff000, v158
	s_nop 1
	v_addc_co_u32_e32 v159, vcc, -1, v159, vcc
	global_store_dwordx2 v[158:159], v[124:125], off offset:-256 sc1

.LBB0_182:
	s_or_saveexec_b64 s[4:5], s[4:5]
	v_ashrrev_i32_e32 v123, 31, v122
	v_add_u32_e32 v124, 0xfffff980, v122
	s_xor_b64 exec, exec, s[4:5]
	s_cbranch_execz .LBB0_186
	v_cmp_gt_u32_e32 vcc, s91, v124
	v_lshl_add_u64 v[158:159], v[122:123], 2, v[152:153]
	s_and_b64 s[62:63], vcc, s[0:1]
	global_store_dwordx4 v[158:159], v[118:121], off sc1
	s_and_saveexec_b64 s[22:23], s[62:63]
	s_cbranch_execz .LBB0_185
	s_or_b32 s62, s61, s80
	v_cmp_gt_u32_e32 vcc, s40, v122
	v_lshl_or_b32 v160, s62, 8, v157
	v_ashrrev_i32_e32 v161, 31, v160
	v_cndmask_b32_e32 v130, v208, v209, vcc
	v_lshl_add_u64 v[158:159], s[16:17], 0, v[130:131]
	v_lshlrev_b64 v[160:161], 9, v[160:161]
	v_cndmask_b32_e32 v125, v210, v211, vcc
	v_lshl_add_u64 v[158:159], v[158:159], 0, v[160:161]
	v_add_u32_e32 v160, v125, v122
	v_ashrrev_i32_e32 v161, 31, v160
	v_lshl_add_u64 v[158:159], v[160:161], 2, v[158:159]
	global_store_dwordx4 v[158:159], v[118:121], off sc1

.LBB0_186:
	s_or_b64 exec, exec, s[4:5]
	v_add_u32_e32 v118, 0x90, v146
	v_cmp_lt_i32_e64 s[4:5], s38, v118
	s_and_saveexec_b64 s[22:23], s[4:5]
	s_xor_b64 s[70:71], exec, s[22:23]
	s_cbranch_execz .LBB0_190
	v_cmp_gt_u32_e32 vcc, s39, v118
	s_and_saveexec_b64 s[78:79], vcc
	s_cbranch_execz .LBB0_189
	v_mul_f32_e32 v119, 0xbfb8aa3b, v114
	v_exp_f32_e32 v119, v119
	v_lshl_add_u64 v[150:151], s[30:31], 0, v[150:151]
	v_add_f32_e32 v119, 1.0, v119
	v_div_scale_f32 v120, s[22:23], v119, v119, v114
	v_rcp_f32_e32 v121, v120
	s_nop 0
	v_fma_f32 v125, -v120, v121, 1.0
	v_fmac_f32_e32 v121, v125, v121
	v_div_scale_f32 v125, vcc, v114, v119, v114
	v_mul_f32_e32 v129, v125, v121
	v_fma_f32 v130, -v120, v129, v125
	v_fmac_f32_e32 v129, v130, v121
	v_fma_f32 v120, -v120, v129, v125
	v_div_fmas_f32 v120, v120, v121, v129
	v_div_fixup_f32 v119, v120, v119, v114
	v_mul_f32_e32 v120, 0xbfb8aa3b, v115
	v_exp_f32_e32 v120, v120
	s_nop 0
	v_add_f32_e32 v120, 1.0, v120
	v_div_scale_f32 v121, s[22:23], v120, v120, v115
	v_rcp_f32_e32 v125, v121
	s_nop 0
	v_fma_f32 v129, -v121, v125, 1.0
	v_fmac_f32_e32 v125, v129, v125
	v_div_scale_f32 v129, vcc, v115, v120, v115
	v_mul_f32_e32 v130, v129, v125
	v_fma_f32 v152, -v121, v130, v129
	v_fmac_f32_e32 v130, v152, v125
	v_fma_f32 v121, -v121, v130, v129
	v_div_fmas_f32 v121, v121, v125, v130
	v_div_fixup_f32 v120, v121, v120, v115
	v_cvt_pk_bf16_f32 v120, v119, v120
	v_mul_f32_e32 v119, 0xbfb8aa3b, v116
	v_exp_f32_e32 v119, v119
	s_nop 0
	v_add_f32_e32 v119, 1.0, v119
	v_div_scale_f32 v121, s[22:23], v119, v119, v116
	v_rcp_f32_e32 v125, v121
	s_nop 0
	v_fma_f32 v129, -v121, v125, 1.0
	v_fmac_f32_e32 v125, v129, v125
	v_div_scale_f32 v129, vcc, v116, v119, v116
	v_mul_f32_e32 v130, v129, v125
	v_fma_f32 v152, -v121, v130, v129
	v_fmac_f32_e32 v130, v152, v125
	v_fma_f32 v121, -v121, v130, v129
	v_div_fmas_f32 v121, v121, v125, v130
	v_div_fixup_f32 v119, v121, v119, v116
	v_mul_f32_e32 v121, 0xbfb8aa3b, v117
	v_exp_f32_e32 v121, v121
	s_nop 0
	v_add_f32_e32 v121, 1.0, v121
	v_div_scale_f32 v125, s[22:23], v121, v121, v117
	v_rcp_f32_e32 v129, v125
	s_nop 0
	v_fma_f32 v130, -v125, v129, 1.0
	v_fmac_f32_e32 v129, v130, v129
	v_div_scale_f32 v130, vcc, v117, v121, v117
	v_mul_f32_e32 v152, v130, v129
	v_fma_f32 v153, -v125, v152, v130
	v_fmac_f32_e32 v152, v153, v129
	v_fma_f32 v125, -v125, v152, v130
	v_div_fmas_f32 v125, v125, v129, v152
	v_div_fixup_f32 v121, v125, v121, v117
	v_cvt_pk_bf16_f32 v121, v119, v121
	v_mov_b32_e32 v119, v131
	v_lshl_add_u64 v[150:151], v[118:119], 1, v[150:151]
	v_add_co_u32_e32 v150, vcc, 0xfffff000, v150
	s_nop 1
	v_addc_co_u32_e32 v151, vcc, -1, v151, vcc
	global_store_dwordx2 v[150:151], v[120:121], off offset:-256 sc1

.LBB0_190:
	s_or_saveexec_b64 s[22:23], s[70:71]
	v_ashrrev_i32_e32 v119, 31, v118
	v_add_u32_e32 v120, 0xfffff980, v118
	s_xor_b64 exec, exec, s[22:23]
	s_cbranch_execz .LBB0_194
	v_cmp_gt_u32_e32 vcc, s91, v120
	v_lshl_add_u64 v[150:151], v[118:119], 2, v[152:153]
	s_and_b64 s[62:63], vcc, s[0:1]
	global_store_dwordx4 v[150:151], v[114:117], off sc1
	s_and_saveexec_b64 s[0:1], s[62:63]
	s_cbranch_execz .LBB0_193
	s_or_b32 s62, s61, s80
	v_cmp_gt_u32_e32 vcc, s40, v118
	v_lshl_or_b32 v152, s62, 8, v157
	v_ashrrev_i32_e32 v153, 31, v152
	v_cndmask_b32_e32 v130, v208, v209, vcc
	v_lshl_add_u64 v[150:151], s[16:17], 0, v[130:131]
	v_lshlrev_b64 v[152:153], 9, v[152:153]
	v_cndmask_b32_e32 v121, v210, v211, vcc
	v_lshl_add_u64 v[150:151], v[150:151], 0, v[152:153]
	v_add_u32_e32 v152, v121, v118
	v_ashrrev_i32_e32 v153, 31, v152
	v_lshl_add_u64 v[150:151], v[152:153], 2, v[150:151]
	global_store_dwordx4 v[150:151], v[114:117], off sc1

.LBB0_194:
	s_or_b64 exec, exec, s[22:23]
	v_or_b32_e32 v116, 16, v148
	v_ashrrev_i32_e32 v117, 31, v116
	v_lshlrev_b64 v[114:115], 11, v[116:117]
	v_cmp_gt_i32_e64 s[0:1], s37, v116
	s_and_saveexec_b64 s[22:23], s[10:11]
	s_xor_b64 s[70:71], exec, s[22:23]
	s_cbranch_execz .LBB0_198
	v_cmp_gt_u32_e32 vcc, s39, v146
	s_and_saveexec_b64 s[78:79], vcc
	s_cbranch_execz .LBB0_197
	v_mul_f32_e32 v117, 0xbfb8aa3b, v110
	v_exp_f32_e32 v117, v117
	s_nop 0
	v_add_f32_e32 v117, 1.0, v117
	v_div_scale_f32 v121, s[22:23], v117, v117, v110
	v_rcp_f32_e32 v125, v121
	s_nop 0
	v_fma_f32 v129, -v121, v125, 1.0
	v_fmac_f32_e32 v125, v129, v125
	v_div_scale_f32 v129, vcc, v110, v117, v110
	v_mul_f32_e32 v130, v129, v125
	v_fma_f32 v150, -v121, v130, v129
	v_fmac_f32_e32 v130, v150, v125
	v_fma_f32 v121, -v121, v130, v129
	v_div_fmas_f32 v121, v121, v125, v130
	v_div_fixup_f32 v117, v121, v117, v110
	v_mul_f32_e32 v121, 0xbfb8aa3b, v111
	v_exp_f32_e32 v121, v121
	s_nop 0
	v_add_f32_e32 v121, 1.0, v121
	v_div_scale_f32 v125, s[22:23], v121, v121, v111
	v_rcp_f32_e32 v129, v125
	s_nop 0
	v_fma_f32 v130, -v125, v129, 1.0
	v_fmac_f32_e32 v129, v130, v129
	v_div_scale_f32 v130, vcc, v111, v121, v111
	v_mul_f32_e32 v150, v130, v129
	v_fma_f32 v151, -v125, v150, v130
	v_fmac_f32_e32 v150, v151, v129
	v_fma_f32 v125, -v125, v150, v130
	v_div_fmas_f32 v125, v125, v129, v150
	v_div_fixup_f32 v121, v125, v121, v111
	v_cvt_pk_bf16_f32 v150, v117, v121
	v_mul_f32_e32 v117, 0xbfb8aa3b, v112
	v_exp_f32_e32 v117, v117
	s_nop 0
	v_add_f32_e32 v117, 1.0, v117
	v_div_scale_f32 v121, s[22:23], v117, v117, v112
	v_rcp_f32_e32 v125, v121
	s_nop 0
	v_fma_f32 v129, -v121, v125, 1.0
	v_fmac_f32_e32 v125, v129, v125
	v_div_scale_f32 v129, vcc, v112, v117, v112
	v_mul_f32_e32 v130, v129, v125
	v_fma_f32 v151, -v121, v130, v129
	v_fmac_f32_e32 v130, v151, v125
	v_fma_f32 v121, -v121, v130, v129
	v_div_fmas_f32 v121, v121, v125, v130
	v_div_fixup_f32 v117, v121, v117, v112
	v_mul_f32_e32 v121, 0xbfb8aa3b, v113
	v_exp_f32_e32 v121, v121
	s_nop 0
	v_add_f32_e32 v121, 1.0, v121
	v_div_scale_f32 v125, s[22:23], v121, v121, v113
	v_rcp_f32_e32 v129, v125
	s_nop 0
	v_fma_f32 v130, -v125, v129, 1.0
	v_fmac_f32_e32 v129, v130, v129
	v_div_scale_f32 v130, vcc, v113, v121, v113
	v_mul_f32_e32 v151, v130, v129
	v_fma_f32 v152, -v125, v151, v130
	v_fmac_f32_e32 v151, v152, v129
	v_fma_f32 v125, -v125, v151, v130
	v_lshl_add_u64 v[152:153], s[30:31], 0, v[114:115]
	v_mov_b32_e32 v130, v146
	v_lshl_add_u64 v[152:153], v[130:131], 1, v[152:153]
	v_div_fmas_f32 v125, v125, v129, v151
	v_add_co_u32_e32 v152, vcc, 0xfffff000, v152
	v_div_fixup_f32 v121, v125, v121, v113
	s_nop 0
	v_addc_co_u32_e32 v153, vcc, -1, v153, vcc
	v_cvt_pk_bf16_f32 v151, v117, v121
	global_store_dwordx2 v[152:153], v[150:151], off offset:-256 sc1

.LBB0_198:
	s_or_saveexec_b64 s[22:23], s[70:71]
	v_mad_i64_i32 v[116:117], s[62:63], v116, s36, 0
	v_bitop3_b32 v121, v148, s42, 16 bitop3:0xc8
	v_lshl_add_u64 v[116:117], s[28:29], 0, v[116:117]
	s_xor_b64 exec, exec, s[22:23]
	s_cbranch_execz .LBB0_211
	v_cmp_gt_u32_e32 vcc, s91, v149
	v_lshl_add_u64 v[150:151], v[146:147], 2, v[116:117]
	s_and_b64 s[62:63], vcc, s[0:1]
	global_store_dwordx4 v[150:151], v[110:113], off sc1
	s_and_saveexec_b64 s[70:71], s[62:63]
	s_cbranch_execz .LBB0_201
	s_or_b32 s62, s61, s80
	v_cmp_gt_u32_e32 vcc, s40, v146
	v_lshl_or_b32 v152, s62, 8, v121
	v_ashrrev_i32_e32 v153, 31, v152
	v_cndmask_b32_e32 v130, v208, v209, vcc
	v_lshl_add_u64 v[150:151], s[16:17], 0, v[130:131]
	v_lshlrev_b64 v[152:153], 9, v[152:153]
	v_cndmask_b32_e32 v125, v210, v211, vcc
	v_lshl_add_u64 v[150:151], v[150:151], 0, v[152:153]
	v_add_u32_e32 v152, v125, v146
	v_ashrrev_i32_e32 v153, 31, v152
	v_lshl_add_u64 v[150:151], v[152:153], 2, v[150:151]
	global_store_dwordx4 v[150:151], v[110:113], off sc1

.LBB0_203:
	v_cmp_gt_u32_e32 vcc, s91, v128
	v_lshl_add_u64 v[110:111], v[126:127], 2, v[116:117]
	s_and_b64 s[62:63], vcc, s[0:1]
	global_store_dwordx4 v[110:111], v[106:109], off sc1
	s_and_saveexec_b64 s[70:71], s[62:63]
	s_cbranch_execz .LBB0_205
	s_or_b32 s62, s61, s80
	v_cmp_gt_u32_e32 vcc, s40, v126
	v_lshl_or_b32 v112, s62, 8, v121
	v_ashrrev_i32_e32 v113, 31, v112
	v_cndmask_b32_e32 v130, v208, v209, vcc
	v_lshl_add_u64 v[110:111], s[16:17], 0, v[130:131]
	v_lshlrev_b64 v[112:113], 9, v[112:113]
	v_lshl_add_u64 v[110:111], v[110:111], 0, v[112:113]
	v_cndmask_b32_e32 v112, v210, v211, vcc
	v_add_u32_e32 v112, v112, v126
	v_ashrrev_i32_e32 v113, 31, v112
	v_lshl_add_u64 v[110:111], v[112:113], 2, v[110:111]
	global_store_dwordx4 v[110:111], v[106:109], off sc1

.LBB0_207:
	v_cmp_gt_u32_e32 vcc, s91, v124
	v_lshl_add_u64 v[106:107], v[122:123], 2, v[116:117]
	s_and_b64 s[62:63], vcc, s[0:1]
	global_store_dwordx4 v[106:107], v[102:105], off sc1
	s_and_saveexec_b64 s[70:71], s[62:63]
	s_cbranch_execz .LBB0_209
	s_or_b32 s62, s61, s80
	v_cmp_gt_u32_e32 vcc, s40, v122
	v_lshl_or_b32 v108, s62, 8, v121
	v_ashrrev_i32_e32 v109, 31, v108
	v_cndmask_b32_e32 v130, v208, v209, vcc
	v_lshl_add_u64 v[106:107], s[16:17], 0, v[130:131]
	v_lshlrev_b64 v[108:109], 9, v[108:109]
	v_lshl_add_u64 v[106:107], v[106:107], 0, v[108:109]
	v_cndmask_b32_e32 v108, v210, v211, vcc
	v_add_u32_e32 v108, v108, v122
	v_ashrrev_i32_e32 v109, 31, v108
	v_lshl_add_u64 v[106:107], v[108:109], 2, v[106:107]
	global_store_dwordx4 v[106:107], v[102:105], off sc1

.LBB0_212:
	v_cmp_gt_u32_e32 vcc, s39, v126
	s_and_saveexec_b64 s[78:79], vcc
	s_cbranch_execz .LBB0_214
	v_mul_f32_e32 v110, 0xbfb8aa3b, v106
	v_exp_f32_e32 v110, v110
	s_nop 0
	v_add_f32_e32 v110, 1.0, v110
	v_div_scale_f32 v111, s[22:23], v110, v110, v106
	v_rcp_f32_e32 v112, v111
	s_nop 0
	v_fma_f32 v113, -v111, v112, 1.0
	v_fmac_f32_e32 v112, v113, v112
	v_div_scale_f32 v113, vcc, v106, v110, v106
	v_mul_f32_e32 v125, v113, v112
	v_fma_f32 v129, -v111, v125, v113
	v_fmac_f32_e32 v125, v129, v112
	v_fma_f32 v111, -v111, v125, v113
	v_div_fmas_f32 v111, v111, v112, v125
	v_div_fixup_f32 v110, v111, v110, v106
	v_mul_f32_e32 v111, 0xbfb8aa3b, v107
	v_exp_f32_e32 v111, v111
	s_nop 0
	v_add_f32_e32 v111, 1.0, v111
	v_div_scale_f32 v112, s[22:23], v111, v111, v107
	v_rcp_f32_e32 v113, v112
	s_nop 0
	v_fma_f32 v125, -v112, v113, 1.0
	v_fmac_f32_e32 v113, v125, v113
	v_div_scale_f32 v125, vcc, v107, v111, v107
	v_mul_f32_e32 v129, v125, v113
	v_fma_f32 v130, -v112, v129, v125
	v_fmac_f32_e32 v129, v130, v113
	v_fma_f32 v112, -v112, v129, v125
	v_div_fmas_f32 v112, v112, v113, v129
	v_div_fixup_f32 v111, v112, v111, v107
	v_cvt_pk_bf16_f32 v110, v110, v111
	v_mul_f32_e32 v111, 0xbfb8aa3b, v108
	v_exp_f32_e32 v111, v111
	s_nop 0
	v_add_f32_e32 v111, 1.0, v111
	v_div_scale_f32 v112, s[22:23], v111, v111, v108
	v_rcp_f32_e32 v113, v112
	s_nop 0
	v_fma_f32 v125, -v112, v113, 1.0
	v_fmac_f32_e32 v113, v125, v113
	v_div_scale_f32 v125, vcc, v108, v111, v108
	v_mul_f32_e32 v129, v125, v113
	v_fma_f32 v130, -v112, v129, v125
	v_fmac_f32_e32 v129, v130, v113
	v_fma_f32 v112, -v112, v129, v125
	v_div_fmas_f32 v112, v112, v113, v129
	v_div_fixup_f32 v111, v112, v111, v108
	v_mul_f32_e32 v112, 0xbfb8aa3b, v109
	v_exp_f32_e32 v112, v112
	s_nop 0
	v_add_f32_e32 v112, 1.0, v112
	v_div_scale_f32 v113, s[22:23], v112, v112, v109
	v_rcp_f32_e32 v125, v113
	s_nop 0
	v_fma_f32 v129, -v113, v125, 1.0
	v_fmac_f32_e32 v125, v129, v125
	v_div_scale_f32 v129, vcc, v109, v112, v109
	v_mul_f32_e32 v130, v129, v125
	v_fma_f32 v150, -v113, v130, v129
	v_fmac_f32_e32 v130, v150, v125
	v_fma_f32 v113, -v113, v130, v129
	v_div_fmas_f32 v113, v113, v125, v130
	v_div_fixup_f32 v112, v113, v112, v109
	v_cvt_pk_bf16_f32 v111, v111, v112
	v_lshl_add_u64 v[112:113], s[30:31], 0, v[114:115]
	v_mov_b32_e32 v130, v126
	v_lshl_add_u64 v[112:113], v[130:131], 1, v[112:113]
	v_add_co_u32_e32 v112, vcc, 0xfffff000, v112
	s_nop 1
	v_addc_co_u32_e32 v113, vcc, -1, v113, vcc
	global_store_dwordx2 v[112:113], v[110:111], off offset:-256 sc1

.LBB0_216:
	v_cmp_gt_u32_e32 vcc, s39, v122
	s_and_saveexec_b64 s[78:79], vcc
	s_cbranch_execz .LBB0_218
	v_mul_f32_e32 v106, 0xbfb8aa3b, v102
	v_exp_f32_e32 v106, v106
	v_mov_b32_e32 v130, v122
	v_add_f32_e32 v106, 1.0, v106
	v_div_scale_f32 v107, s[22:23], v106, v106, v102
	v_rcp_f32_e32 v108, v107
	s_nop 0
	v_fma_f32 v109, -v107, v108, 1.0
	v_fmac_f32_e32 v108, v109, v108
	v_div_scale_f32 v109, vcc, v102, v106, v102
	v_mul_f32_e32 v110, v109, v108
	v_fma_f32 v111, -v107, v110, v109
	v_fmac_f32_e32 v110, v111, v108
	v_fma_f32 v107, -v107, v110, v109
	v_div_fmas_f32 v107, v107, v108, v110
	v_div_fixup_f32 v106, v107, v106, v102
	v_mul_f32_e32 v107, 0xbfb8aa3b, v103
	v_exp_f32_e32 v107, v107
	s_nop 0
	v_add_f32_e32 v107, 1.0, v107
	v_div_scale_f32 v108, s[22:23], v107, v107, v103
	v_rcp_f32_e32 v109, v108
	s_nop 0
	v_fma_f32 v110, -v108, v109, 1.0
	v_fmac_f32_e32 v109, v110, v109
	v_div_scale_f32 v110, vcc, v103, v107, v103
	v_mul_f32_e32 v111, v110, v109
	v_fma_f32 v112, -v108, v111, v110
	v_fmac_f32_e32 v111, v112, v109
	v_fma_f32 v108, -v108, v111, v110
	v_div_fmas_f32 v108, v108, v109, v111
	v_div_fixup_f32 v107, v108, v107, v103
	v_cvt_pk_bf16_f32 v106, v106, v107
	v_mul_f32_e32 v107, 0xbfb8aa3b, v104
	v_exp_f32_e32 v107, v107
	s_nop 0
	v_add_f32_e32 v107, 1.0, v107
	v_div_scale_f32 v108, s[22:23], v107, v107, v104
	v_rcp_f32_e32 v109, v108
	s_nop 0
	v_fma_f32 v110, -v108, v109, 1.0
	v_fmac_f32_e32 v109, v110, v109
	v_div_scale_f32 v110, vcc, v104, v107, v104
	v_mul_f32_e32 v111, v110, v109
	v_fma_f32 v112, -v108, v111, v110
	v_fmac_f32_e32 v111, v112, v109
	v_fma_f32 v108, -v108, v111, v110
	v_div_fmas_f32 v108, v108, v109, v111
	v_div_fixup_f32 v107, v108, v107, v104
	v_mul_f32_e32 v108, 0xbfb8aa3b, v105
	v_exp_f32_e32 v108, v108
	s_nop 0
	v_add_f32_e32 v108, 1.0, v108
	v_div_scale_f32 v109, s[22:23], v108, v108, v105
	v_rcp_f32_e32 v110, v109
	s_nop 0
	v_fma_f32 v111, -v109, v110, 1.0
	v_fmac_f32_e32 v110, v111, v110
	v_div_scale_f32 v111, vcc, v105, v108, v105
	v_mul_f32_e32 v112, v111, v110
	v_fma_f32 v113, -v109, v112, v111
	v_fmac_f32_e32 v112, v113, v110
	v_fma_f32 v109, -v109, v112, v111
	v_div_fmas_f32 v109, v109, v110, v112
	v_div_fixup_f32 v108, v109, v108, v105
	v_cvt_pk_bf16_f32 v107, v107, v108
	v_lshl_add_u64 v[108:109], s[30:31], 0, v[114:115]
	v_lshl_add_u64 v[108:109], v[130:131], 1, v[108:109]
	v_add_co_u32_e32 v108, vcc, 0xfffff000, v108
	s_nop 1
	v_addc_co_u32_e32 v109, vcc, -1, v109, vcc
	global_store_dwordx2 v[108:109], v[106:107], off offset:-256 sc1

.LBB0_220:
	v_cmp_gt_u32_e32 vcc, s39, v118
	s_and_saveexec_b64 s[78:79], vcc
	s_cbranch_execz .LBB0_222
	v_mul_f32_e32 v102, 0xbfb8aa3b, v98
	v_exp_f32_e32 v102, v102
	v_mov_b32_e32 v130, v118
	v_add_f32_e32 v102, 1.0, v102
	v_div_scale_f32 v103, s[22:23], v102, v102, v98
	v_rcp_f32_e32 v104, v103
	s_nop 0
	v_fma_f32 v105, -v103, v104, 1.0
	v_fmac_f32_e32 v104, v105, v104
	v_div_scale_f32 v105, vcc, v98, v102, v98
	v_mul_f32_e32 v106, v105, v104
	v_fma_f32 v107, -v103, v106, v105
	v_fmac_f32_e32 v106, v107, v104
	v_fma_f32 v103, -v103, v106, v105
	v_div_fmas_f32 v103, v103, v104, v106
	v_div_fixup_f32 v102, v103, v102, v98
	v_mul_f32_e32 v103, 0xbfb8aa3b, v99
	v_exp_f32_e32 v103, v103
	s_nop 0
	v_add_f32_e32 v103, 1.0, v103
	v_div_scale_f32 v104, s[22:23], v103, v103, v99
	v_rcp_f32_e32 v105, v104
	s_nop 0
	v_fma_f32 v106, -v104, v105, 1.0
	v_fmac_f32_e32 v105, v106, v105
	v_div_scale_f32 v106, vcc, v99, v103, v99
	v_mul_f32_e32 v107, v106, v105
	v_fma_f32 v108, -v104, v107, v106
	v_fmac_f32_e32 v107, v108, v105
	v_fma_f32 v104, -v104, v107, v106
	v_div_fmas_f32 v104, v104, v105, v107
	v_div_fixup_f32 v103, v104, v103, v99
	v_cvt_pk_bf16_f32 v102, v102, v103
	v_mul_f32_e32 v103, 0xbfb8aa3b, v100
	v_exp_f32_e32 v103, v103
	s_nop 0
	v_add_f32_e32 v103, 1.0, v103
	v_div_scale_f32 v104, s[22:23], v103, v103, v100
	v_rcp_f32_e32 v105, v104
	s_nop 0
	v_fma_f32 v106, -v104, v105, 1.0
	v_fmac_f32_e32 v105, v106, v105
	v_div_scale_f32 v106, vcc, v100, v103, v100
	v_mul_f32_e32 v107, v106, v105
	v_fma_f32 v108, -v104, v107, v106
	v_fmac_f32_e32 v107, v108, v105
	v_fma_f32 v104, -v104, v107, v106
	v_div_fmas_f32 v104, v104, v105, v107
	v_div_fixup_f32 v103, v104, v103, v100
	v_mul_f32_e32 v104, 0xbfb8aa3b, v101
	v_exp_f32_e32 v104, v104
	s_nop 0
	v_add_f32_e32 v104, 1.0, v104
	v_div_scale_f32 v105, s[22:23], v104, v104, v101
	v_rcp_f32_e32 v106, v105
	s_nop 0
	v_fma_f32 v107, -v105, v106, 1.0
	v_fmac_f32_e32 v106, v107, v106
	v_div_scale_f32 v107, vcc, v101, v104, v101
	v_mul_f32_e32 v108, v107, v106
	v_fma_f32 v109, -v105, v108, v107
	v_fmac_f32_e32 v108, v109, v106
	v_fma_f32 v105, -v105, v108, v107
	v_div_fmas_f32 v105, v105, v106, v108
	v_div_fixup_f32 v104, v105, v104, v101
	v_cvt_pk_bf16_f32 v103, v103, v104
	v_lshl_add_u64 v[104:105], s[30:31], 0, v[114:115]
	v_lshl_add_u64 v[104:105], v[130:131], 1, v[104:105]
	v_add_co_u32_e32 v104, vcc, 0xfffff000, v104
	s_nop 1
	v_addc_co_u32_e32 v105, vcc, -1, v105, vcc
	global_store_dwordx2 v[104:105], v[102:103], off offset:-256 sc1

.LBB0_223:
	v_cmp_gt_u32_e32 vcc, s91, v120
	v_lshl_add_u64 v[102:103], v[118:119], 2, v[116:117]
	s_and_b64 s[62:63], vcc, s[0:1]
	global_store_dwordx4 v[102:103], v[98:101], off sc1
	s_and_saveexec_b64 s[0:1], s[62:63]
	s_cbranch_execz .LBB0_225
	s_or_b32 s62, s61, s80
	v_cmp_gt_u32_e32 vcc, s40, v118
	v_lshl_or_b32 v104, s62, 8, v121
	v_ashrrev_i32_e32 v105, 31, v104
	v_cndmask_b32_e32 v130, v208, v209, vcc
	v_lshl_add_u64 v[102:103], s[16:17], 0, v[130:131]
	v_lshlrev_b64 v[104:105], 9, v[104:105]
	v_lshl_add_u64 v[102:103], v[102:103], 0, v[104:105]
	v_cndmask_b32_e32 v104, v210, v211, vcc
	v_add_u32_e32 v104, v104, v118
	v_ashrrev_i32_e32 v105, 31, v104
	v_lshl_add_u64 v[102:103], v[104:105], 2, v[102:103]
	global_store_dwordx4 v[102:103], v[98:101], off sc1

.LBB0_226:
	s_or_b64 exec, exec, s[22:23]
	v_or_b32_e32 v100, 32, v148
	v_ashrrev_i32_e32 v101, 31, v100
	v_lshlrev_b64 v[98:99], 11, v[100:101]
	v_cmp_gt_i32_e64 s[0:1], s37, v100
	s_and_saveexec_b64 s[22:23], s[10:11]
	s_xor_b64 s[70:71], exec, s[22:23]
	s_cbranch_execz .LBB0_230
	v_cmp_gt_u32_e32 vcc, s39, v146
	s_and_saveexec_b64 s[78:79], vcc
	s_cbranch_execz .LBB0_229
	v_mul_f32_e32 v101, 0xbfb8aa3b, v94
	v_exp_f32_e32 v101, v101
	v_mov_b32_e32 v130, v146
	v_add_f32_e32 v101, 1.0, v101
	v_div_scale_f32 v102, s[22:23], v101, v101, v94
	v_rcp_f32_e32 v103, v102
	s_nop 0
	v_fma_f32 v104, -v102, v103, 1.0
	v_fmac_f32_e32 v103, v104, v103
	v_div_scale_f32 v104, vcc, v94, v101, v94
	v_mul_f32_e32 v105, v104, v103
	v_fma_f32 v106, -v102, v105, v104
	v_fmac_f32_e32 v105, v106, v103
	v_fma_f32 v102, -v102, v105, v104
	v_div_fmas_f32 v102, v102, v103, v105
	v_div_fixup_f32 v101, v102, v101, v94
	v_mul_f32_e32 v102, 0xbfb8aa3b, v95
	v_exp_f32_e32 v102, v102
	s_nop 0
	v_add_f32_e32 v102, 1.0, v102
	v_div_scale_f32 v103, s[22:23], v102, v102, v95
	v_rcp_f32_e32 v104, v103
	s_nop 0
	v_fma_f32 v105, -v103, v104, 1.0
	v_fmac_f32_e32 v104, v105, v104
	v_div_scale_f32 v105, vcc, v95, v102, v95
	v_mul_f32_e32 v106, v105, v104
	v_fma_f32 v107, -v103, v106, v105
	v_fmac_f32_e32 v106, v107, v104
	v_fma_f32 v103, -v103, v106, v105
	v_div_fmas_f32 v103, v103, v104, v106
	v_div_fixup_f32 v102, v103, v102, v95
	v_cvt_pk_bf16_f32 v102, v101, v102
	v_mul_f32_e32 v101, 0xbfb8aa3b, v96
	v_exp_f32_e32 v101, v101
	s_nop 0
	v_add_f32_e32 v101, 1.0, v101
	v_div_scale_f32 v103, s[22:23], v101, v101, v96
	v_rcp_f32_e32 v104, v103
	s_nop 0
	v_fma_f32 v105, -v103, v104, 1.0
	v_fmac_f32_e32 v104, v105, v104
	v_div_scale_f32 v105, vcc, v96, v101, v96
	v_mul_f32_e32 v106, v105, v104
	v_fma_f32 v107, -v103, v106, v105
	v_fmac_f32_e32 v106, v107, v104
	v_fma_f32 v103, -v103, v106, v105
	v_div_fmas_f32 v103, v103, v104, v106
	v_div_fixup_f32 v101, v103, v101, v96
	v_mul_f32_e32 v103, 0xbfb8aa3b, v97
	v_exp_f32_e32 v103, v103
	s_nop 0
	v_add_f32_e32 v103, 1.0, v103
	v_div_scale_f32 v104, s[22:23], v103, v103, v97
	v_rcp_f32_e32 v105, v104
	s_nop 0
	v_fma_f32 v106, -v104, v105, 1.0
	v_fmac_f32_e32 v105, v106, v105
	v_div_scale_f32 v106, vcc, v97, v103, v97
	v_mul_f32_e32 v107, v106, v105
	v_fma_f32 v108, -v104, v107, v106
	v_fmac_f32_e32 v107, v108, v105
	v_fma_f32 v104, -v104, v107, v106
	v_div_fmas_f32 v104, v104, v105, v107
	v_div_fixup_f32 v103, v104, v103, v97
	v_lshl_add_u64 v[104:105], s[30:31], 0, v[98:99]
	v_lshl_add_u64 v[104:105], v[130:131], 1, v[104:105]
	v_add_co_u32_e32 v104, vcc, 0xfffff000, v104
	v_cvt_pk_bf16_f32 v103, v101, v103
	s_nop 1
	v_addc_co_u32_e32 v105, vcc, -1, v105, vcc
	global_store_dwordx2 v[104:105], v[102:103], off offset:-256 sc1

.LBB0_230:
	s_or_saveexec_b64 s[22:23], s[70:71]
	v_mad_i64_i32 v[100:101], s[62:63], v100, s36, 0
	v_bitop3_b32 v102, v148, s43, 32 bitop3:0xc8
	v_lshl_add_u64 v[100:101], s[28:29], 0, v[100:101]
	s_xor_b64 exec, exec, s[22:23]
	s_cbranch_execz .LBB0_243
	v_cmp_gt_u32_e32 vcc, s91, v149
	v_lshl_add_u64 v[104:105], v[146:147], 2, v[100:101]
	s_and_b64 s[62:63], vcc, s[0:1]
	global_store_dwordx4 v[104:105], v[94:97], off sc1
	s_and_saveexec_b64 s[70:71], s[62:63]
	s_cbranch_execz .LBB0_233
	s_or_b32 s62, s61, s80
	v_cmp_gt_u32_e32 vcc, s40, v146
	v_lshl_or_b32 v106, s62, 8, v102
	v_ashrrev_i32_e32 v107, 31, v106
	v_cndmask_b32_e32 v130, v208, v209, vcc
	v_lshl_add_u64 v[104:105], s[16:17], 0, v[130:131]
	v_lshlrev_b64 v[106:107], 9, v[106:107]
	v_cndmask_b32_e32 v103, v210, v211, vcc
	v_lshl_add_u64 v[104:105], v[104:105], 0, v[106:107]
	v_add_u32_e32 v106, v103, v146
	v_ashrrev_i32_e32 v107, 31, v106
	v_lshl_add_u64 v[104:105], v[106:107], 2, v[104:105]
	global_store_dwordx4 v[104:105], v[94:97], off sc1

.LBB0_235:
	v_cmp_gt_u32_e32 vcc, s91, v128
	v_lshl_add_u64 v[94:95], v[126:127], 2, v[100:101]
	s_and_b64 s[62:63], vcc, s[0:1]
	global_store_dwordx4 v[94:95], v[90:93], off sc1
	s_and_saveexec_b64 s[70:71], s[62:63]
	s_cbranch_execz .LBB0_237
	s_or_b32 s62, s61, s80
	v_cmp_gt_u32_e32 vcc, s40, v126
	v_lshl_or_b32 v96, s62, 8, v102
	v_ashrrev_i32_e32 v97, 31, v96
	v_cndmask_b32_e32 v130, v208, v209, vcc
	v_lshl_add_u64 v[94:95], s[16:17], 0, v[130:131]
	v_lshlrev_b64 v[96:97], 9, v[96:97]
	v_lshl_add_u64 v[94:95], v[94:95], 0, v[96:97]
	v_cndmask_b32_e32 v96, v210, v211, vcc
	v_add_u32_e32 v96, v96, v126
	v_ashrrev_i32_e32 v97, 31, v96
	v_lshl_add_u64 v[94:95], v[96:97], 2, v[94:95]
	global_store_dwordx4 v[94:95], v[90:93], off sc1

.LBB0_239:
	v_cmp_gt_u32_e32 vcc, s91, v124
	v_lshl_add_u64 v[90:91], v[122:123], 2, v[100:101]
	s_and_b64 s[62:63], vcc, s[0:1]
	global_store_dwordx4 v[90:91], v[86:89], off sc1
	s_and_saveexec_b64 s[70:71], s[62:63]
	s_cbranch_execz .LBB0_241
	s_or_b32 s62, s61, s80
	v_cmp_gt_u32_e32 vcc, s40, v122
	v_lshl_or_b32 v92, s62, 8, v102
	v_ashrrev_i32_e32 v93, 31, v92
	v_cndmask_b32_e32 v130, v208, v209, vcc
	v_lshl_add_u64 v[90:91], s[16:17], 0, v[130:131]
	v_lshlrev_b64 v[92:93], 9, v[92:93]
	v_lshl_add_u64 v[90:91], v[90:91], 0, v[92:93]
	v_cndmask_b32_e32 v92, v210, v211, vcc
	v_add_u32_e32 v92, v92, v122
	v_ashrrev_i32_e32 v93, 31, v92
	v_lshl_add_u64 v[90:91], v[92:93], 2, v[90:91]
	global_store_dwordx4 v[90:91], v[86:89], off sc1

.LBB0_244:
	v_cmp_gt_u32_e32 vcc, s39, v126
	s_and_saveexec_b64 s[78:79], vcc
	s_cbranch_execz .LBB0_246
	v_mul_f32_e32 v94, 0xbfb8aa3b, v90
	v_exp_f32_e32 v94, v94
	v_mov_b32_e32 v130, v126
	v_add_f32_e32 v94, 1.0, v94
	v_div_scale_f32 v95, s[22:23], v94, v94, v90
	v_rcp_f32_e32 v96, v95
	s_nop 0
	v_fma_f32 v97, -v95, v96, 1.0
	v_fmac_f32_e32 v96, v97, v96
	v_div_scale_f32 v97, vcc, v90, v94, v90
	v_mul_f32_e32 v103, v97, v96
	v_fma_f32 v104, -v95, v103, v97
	v_fmac_f32_e32 v103, v104, v96
	v_fma_f32 v95, -v95, v103, v97
	v_div_fmas_f32 v95, v95, v96, v103
	v_div_fixup_f32 v94, v95, v94, v90
	v_mul_f32_e32 v95, 0xbfb8aa3b, v91
	v_exp_f32_e32 v95, v95
	s_nop 0
	v_add_f32_e32 v95, 1.0, v95
	v_div_scale_f32 v96, s[22:23], v95, v95, v91
	v_rcp_f32_e32 v97, v96
	s_nop 0
	v_fma_f32 v103, -v96, v97, 1.0
	v_fmac_f32_e32 v97, v103, v97
	v_div_scale_f32 v103, vcc, v91, v95, v91
	v_mul_f32_e32 v104, v103, v97
	v_fma_f32 v105, -v96, v104, v103
	v_fmac_f32_e32 v104, v105, v97
	v_fma_f32 v96, -v96, v104, v103
	v_div_fmas_f32 v96, v96, v97, v104
	v_div_fixup_f32 v95, v96, v95, v91
	v_cvt_pk_bf16_f32 v94, v94, v95
	v_mul_f32_e32 v95, 0xbfb8aa3b, v92
	v_exp_f32_e32 v95, v95
	s_nop 0
	v_add_f32_e32 v95, 1.0, v95
	v_div_scale_f32 v96, s[22:23], v95, v95, v92
	v_rcp_f32_e32 v97, v96
	s_nop 0
	v_fma_f32 v103, -v96, v97, 1.0
	v_fmac_f32_e32 v97, v103, v97
	v_div_scale_f32 v103, vcc, v92, v95, v92
	v_mul_f32_e32 v104, v103, v97
	v_fma_f32 v105, -v96, v104, v103
	v_fmac_f32_e32 v104, v105, v97
	v_fma_f32 v96, -v96, v104, v103
	v_div_fmas_f32 v96, v96, v97, v104
	v_div_fixup_f32 v95, v96, v95, v92
	v_mul_f32_e32 v96, 0xbfb8aa3b, v93
	v_exp_f32_e32 v96, v96
	s_nop 0
	v_add_f32_e32 v96, 1.0, v96
	v_div_scale_f32 v97, s[22:23], v96, v96, v93
	v_rcp_f32_e32 v103, v97
	s_nop 0
	v_fma_f32 v104, -v97, v103, 1.0
	v_fmac_f32_e32 v103, v104, v103
	v_div_scale_f32 v104, vcc, v93, v96, v93
	v_mul_f32_e32 v105, v104, v103
	v_fma_f32 v106, -v97, v105, v104
	v_fmac_f32_e32 v105, v106, v103
	v_fma_f32 v97, -v97, v105, v104
	v_div_fmas_f32 v97, v97, v103, v105
	v_div_fixup_f32 v96, v97, v96, v93
	v_cvt_pk_bf16_f32 v95, v95, v96
	v_lshl_add_u64 v[96:97], s[30:31], 0, v[98:99]
	v_lshl_add_u64 v[96:97], v[130:131], 1, v[96:97]
	v_add_co_u32_e32 v96, vcc, 0xfffff000, v96
	s_nop 1
	v_addc_co_u32_e32 v97, vcc, -1, v97, vcc
	global_store_dwordx2 v[96:97], v[94:95], off offset:-256 sc1

.LBB0_248:
	v_cmp_gt_u32_e32 vcc, s39, v122
	s_and_saveexec_b64 s[78:79], vcc
	s_cbranch_execz .LBB0_250
	v_mul_f32_e32 v90, 0xbfb8aa3b, v86
	v_exp_f32_e32 v90, v90
	v_mov_b32_e32 v130, v122
	v_add_f32_e32 v90, 1.0, v90
	v_div_scale_f32 v91, s[22:23], v90, v90, v86
	v_rcp_f32_e32 v92, v91
	s_nop 0
	v_fma_f32 v93, -v91, v92, 1.0
	v_fmac_f32_e32 v92, v93, v92
	v_div_scale_f32 v93, vcc, v86, v90, v86
	v_mul_f32_e32 v94, v93, v92
	v_fma_f32 v95, -v91, v94, v93
	v_fmac_f32_e32 v94, v95, v92
	v_fma_f32 v91, -v91, v94, v93
	v_div_fmas_f32 v91, v91, v92, v94
	v_div_fixup_f32 v90, v91, v90, v86
	v_mul_f32_e32 v91, 0xbfb8aa3b, v87
	v_exp_f32_e32 v91, v91
	s_nop 0
	v_add_f32_e32 v91, 1.0, v91
	v_div_scale_f32 v92, s[22:23], v91, v91, v87
	v_rcp_f32_e32 v93, v92
	s_nop 0
	v_fma_f32 v94, -v92, v93, 1.0
	v_fmac_f32_e32 v93, v94, v93
	v_div_scale_f32 v94, vcc, v87, v91, v87
	v_mul_f32_e32 v95, v94, v93
	v_fma_f32 v96, -v92, v95, v94
	v_fmac_f32_e32 v95, v96, v93
	v_fma_f32 v92, -v92, v95, v94
	v_div_fmas_f32 v92, v92, v93, v95
	v_div_fixup_f32 v91, v92, v91, v87
	v_cvt_pk_bf16_f32 v90, v90, v91
	v_mul_f32_e32 v91, 0xbfb8aa3b, v88
	v_exp_f32_e32 v91, v91
	s_nop 0
	v_add_f32_e32 v91, 1.0, v91
	v_div_scale_f32 v92, s[22:23], v91, v91, v88
	v_rcp_f32_e32 v93, v92
	s_nop 0
	v_fma_f32 v94, -v92, v93, 1.0
	v_fmac_f32_e32 v93, v94, v93
	v_div_scale_f32 v94, vcc, v88, v91, v88
	v_mul_f32_e32 v95, v94, v93
	v_fma_f32 v96, -v92, v95, v94
	v_fmac_f32_e32 v95, v96, v93
	v_fma_f32 v92, -v92, v95, v94
	v_div_fmas_f32 v92, v92, v93, v95
	v_div_fixup_f32 v91, v92, v91, v88
	v_mul_f32_e32 v92, 0xbfb8aa3b, v89
	v_exp_f32_e32 v92, v92
	s_nop 0
	v_add_f32_e32 v92, 1.0, v92
	v_div_scale_f32 v93, s[22:23], v92, v92, v89
	v_rcp_f32_e32 v94, v93
	s_nop 0
	v_fma_f32 v95, -v93, v94, 1.0
	v_fmac_f32_e32 v94, v95, v94
	v_div_scale_f32 v95, vcc, v89, v92, v89
	v_mul_f32_e32 v96, v95, v94
	v_fma_f32 v97, -v93, v96, v95
	v_fmac_f32_e32 v96, v97, v94
	v_fma_f32 v93, -v93, v96, v95
	v_div_fmas_f32 v93, v93, v94, v96
	v_div_fixup_f32 v92, v93, v92, v89
	v_cvt_pk_bf16_f32 v91, v91, v92
	v_lshl_add_u64 v[92:93], s[30:31], 0, v[98:99]
	v_lshl_add_u64 v[92:93], v[130:131], 1, v[92:93]
	v_add_co_u32_e32 v92, vcc, 0xfffff000, v92
	s_nop 1
	v_addc_co_u32_e32 v93, vcc, -1, v93, vcc
	global_store_dwordx2 v[92:93], v[90:91], off offset:-256 sc1

.LBB0_252:
	v_cmp_gt_u32_e32 vcc, s39, v118
	s_and_saveexec_b64 s[78:79], vcc
	s_cbranch_execz .LBB0_254
	v_mul_f32_e32 v86, 0xbfb8aa3b, v82
	v_exp_f32_e32 v86, v86
	v_mov_b32_e32 v130, v118
	v_add_f32_e32 v86, 1.0, v86
	v_div_scale_f32 v87, s[22:23], v86, v86, v82
	v_rcp_f32_e32 v88, v87
	s_nop 0
	v_fma_f32 v89, -v87, v88, 1.0
	v_fmac_f32_e32 v88, v89, v88
	v_div_scale_f32 v89, vcc, v82, v86, v82
	v_mul_f32_e32 v90, v89, v88
	v_fma_f32 v91, -v87, v90, v89
	v_fmac_f32_e32 v90, v91, v88
	v_fma_f32 v87, -v87, v90, v89
	v_div_fmas_f32 v87, v87, v88, v90
	v_div_fixup_f32 v86, v87, v86, v82
	v_mul_f32_e32 v87, 0xbfb8aa3b, v83
	v_exp_f32_e32 v87, v87
	s_nop 0
	v_add_f32_e32 v87, 1.0, v87
	v_div_scale_f32 v88, s[22:23], v87, v87, v83
	v_rcp_f32_e32 v89, v88
	s_nop 0
	v_fma_f32 v90, -v88, v89, 1.0
	v_fmac_f32_e32 v89, v90, v89
	v_div_scale_f32 v90, vcc, v83, v87, v83
	v_mul_f32_e32 v91, v90, v89
	v_fma_f32 v92, -v88, v91, v90
	v_fmac_f32_e32 v91, v92, v89
	v_fma_f32 v88, -v88, v91, v90
	v_div_fmas_f32 v88, v88, v89, v91
	v_div_fixup_f32 v87, v88, v87, v83
	v_cvt_pk_bf16_f32 v86, v86, v87
	v_mul_f32_e32 v87, 0xbfb8aa3b, v84
	v_exp_f32_e32 v87, v87
	s_nop 0
	v_add_f32_e32 v87, 1.0, v87
	v_div_scale_f32 v88, s[22:23], v87, v87, v84
	v_rcp_f32_e32 v89, v88
	s_nop 0
	v_fma_f32 v90, -v88, v89, 1.0
	v_fmac_f32_e32 v89, v90, v89
	v_div_scale_f32 v90, vcc, v84, v87, v84
	v_mul_f32_e32 v91, v90, v89
	v_fma_f32 v92, -v88, v91, v90
	v_fmac_f32_e32 v91, v92, v89
	v_fma_f32 v88, -v88, v91, v90
	v_div_fmas_f32 v88, v88, v89, v91
	v_div_fixup_f32 v87, v88, v87, v84
	v_mul_f32_e32 v88, 0xbfb8aa3b, v85
	v_exp_f32_e32 v88, v88
	s_nop 0
	v_add_f32_e32 v88, 1.0, v88
	v_div_scale_f32 v89, s[22:23], v88, v88, v85
	v_rcp_f32_e32 v90, v89
	s_nop 0
	v_fma_f32 v91, -v89, v90, 1.0
	v_fmac_f32_e32 v90, v91, v90
	v_div_scale_f32 v91, vcc, v85, v88, v85
	v_mul_f32_e32 v92, v91, v90
	v_fma_f32 v93, -v89, v92, v91
	v_fmac_f32_e32 v92, v93, v90
	v_fma_f32 v89, -v89, v92, v91
	v_div_fmas_f32 v89, v89, v90, v92
	v_div_fixup_f32 v88, v89, v88, v85
	v_cvt_pk_bf16_f32 v87, v87, v88
	v_lshl_add_u64 v[88:89], s[30:31], 0, v[98:99]
	v_lshl_add_u64 v[88:89], v[130:131], 1, v[88:89]
	v_add_co_u32_e32 v88, vcc, 0xfffff000, v88
	s_nop 1
	v_addc_co_u32_e32 v89, vcc, -1, v89, vcc
	global_store_dwordx2 v[88:89], v[86:87], off offset:-256 sc1

.LBB0_255:
	v_cmp_gt_u32_e32 vcc, s91, v120
	v_lshl_add_u64 v[86:87], v[118:119], 2, v[100:101]
	s_and_b64 s[62:63], vcc, s[0:1]
	global_store_dwordx4 v[86:87], v[82:85], off sc1
	s_and_saveexec_b64 s[0:1], s[62:63]
	s_cbranch_execz .LBB0_257
	s_or_b32 s62, s61, s80
	v_cmp_gt_u32_e32 vcc, s40, v118
	v_lshl_or_b32 v88, s62, 8, v102
	v_ashrrev_i32_e32 v89, 31, v88
	v_cndmask_b32_e32 v130, v208, v209, vcc
	v_lshl_add_u64 v[86:87], s[16:17], 0, v[130:131]
	v_lshlrev_b64 v[88:89], 9, v[88:89]
	v_lshl_add_u64 v[86:87], v[86:87], 0, v[88:89]
	v_cndmask_b32_e32 v88, v210, v211, vcc
	v_add_u32_e32 v88, v88, v118
	v_ashrrev_i32_e32 v89, 31, v88
	v_lshl_add_u64 v[86:87], v[88:89], 2, v[86:87]
	global_store_dwordx4 v[86:87], v[82:85], off sc1

.LBB0_258:
	s_or_b64 exec, exec, s[22:23]
	v_or_b32_e32 v84, 48, v148
	v_ashrrev_i32_e32 v85, 31, v84
	v_lshlrev_b64 v[82:83], 11, v[84:85]
	v_cmp_gt_i32_e64 s[0:1], s37, v84
	s_and_saveexec_b64 s[22:23], s[10:11]
	s_xor_b64 s[70:71], exec, s[22:23]
	s_cbranch_execz .LBB0_262
	v_cmp_gt_u32_e32 vcc, s39, v146
	s_and_saveexec_b64 s[78:79], vcc
	s_cbranch_execz .LBB0_261
	v_mul_f32_e32 v85, 0xbfb8aa3b, v78
	v_exp_f32_e32 v85, v85
	v_mov_b32_e32 v130, v146
	v_add_f32_e32 v85, 1.0, v85
	v_div_scale_f32 v86, s[22:23], v85, v85, v78
	v_rcp_f32_e32 v87, v86
	s_nop 0
	v_fma_f32 v88, -v86, v87, 1.0
	v_fmac_f32_e32 v87, v88, v87
	v_div_scale_f32 v88, vcc, v78, v85, v78
	v_mul_f32_e32 v89, v88, v87
	v_fma_f32 v90, -v86, v89, v88
	v_fmac_f32_e32 v89, v90, v87
	v_fma_f32 v86, -v86, v89, v88
	v_div_fmas_f32 v86, v86, v87, v89
	v_div_fixup_f32 v85, v86, v85, v78
	v_mul_f32_e32 v86, 0xbfb8aa3b, v79
	v_exp_f32_e32 v86, v86
	s_nop 0
	v_add_f32_e32 v86, 1.0, v86
	v_div_scale_f32 v87, s[22:23], v86, v86, v79
	v_rcp_f32_e32 v88, v87
	s_nop 0
	v_fma_f32 v89, -v87, v88, 1.0
	v_fmac_f32_e32 v88, v89, v88
	v_div_scale_f32 v89, vcc, v79, v86, v79
	v_mul_f32_e32 v90, v89, v88
	v_fma_f32 v91, -v87, v90, v89
	v_fmac_f32_e32 v90, v91, v88
	v_fma_f32 v87, -v87, v90, v89
	v_div_fmas_f32 v87, v87, v88, v90
	v_div_fixup_f32 v86, v87, v86, v79
	v_cvt_pk_bf16_f32 v86, v85, v86
	v_mul_f32_e32 v85, 0xbfb8aa3b, v80
	v_exp_f32_e32 v85, v85
	s_nop 0
	v_add_f32_e32 v85, 1.0, v85
	v_div_scale_f32 v87, s[22:23], v85, v85, v80
	v_rcp_f32_e32 v88, v87
	s_nop 0
	v_fma_f32 v89, -v87, v88, 1.0
	v_fmac_f32_e32 v88, v89, v88
	v_div_scale_f32 v89, vcc, v80, v85, v80
	v_mul_f32_e32 v90, v89, v88
	v_fma_f32 v91, -v87, v90, v89
	v_fmac_f32_e32 v90, v91, v88
	v_fma_f32 v87, -v87, v90, v89
	v_div_fmas_f32 v87, v87, v88, v90
	v_div_fixup_f32 v85, v87, v85, v80
	v_mul_f32_e32 v87, 0xbfb8aa3b, v81
	v_exp_f32_e32 v87, v87
	s_nop 0
	v_add_f32_e32 v87, 1.0, v87
	v_div_scale_f32 v88, s[22:23], v87, v87, v81
	v_rcp_f32_e32 v89, v88
	s_nop 0
	v_fma_f32 v90, -v88, v89, 1.0
	v_fmac_f32_e32 v89, v90, v89
	v_div_scale_f32 v90, vcc, v81, v87, v81
	v_mul_f32_e32 v91, v90, v89
	v_fma_f32 v92, -v88, v91, v90
	v_fmac_f32_e32 v91, v92, v89
	v_fma_f32 v88, -v88, v91, v90
	v_div_fmas_f32 v88, v88, v89, v91
	v_div_fixup_f32 v87, v88, v87, v81
	v_lshl_add_u64 v[88:89], s[30:31], 0, v[82:83]
	v_lshl_add_u64 v[88:89], v[130:131], 1, v[88:89]
	v_add_co_u32_e32 v88, vcc, 0xfffff000, v88
	v_cvt_pk_bf16_f32 v87, v85, v87
	s_nop 1
	v_addc_co_u32_e32 v89, vcc, -1, v89, vcc
	global_store_dwordx2 v[88:89], v[86:87], off offset:-256 sc1

.LBB0_262:
	s_or_saveexec_b64 s[22:23], s[70:71]
	v_mad_i64_i32 v[84:85], s[62:63], v84, s36, 0
	v_bitop3_b32 v86, v148, s90, 48 bitop3:0xc8
	v_lshl_add_u64 v[84:85], s[28:29], 0, v[84:85]
	s_xor_b64 exec, exec, s[22:23]
	s_cbranch_execz .LBB0_275
	v_cmp_gt_u32_e32 vcc, s91, v149
	v_lshl_add_u64 v[88:89], v[146:147], 2, v[84:85]
	s_and_b64 s[62:63], vcc, s[0:1]
	global_store_dwordx4 v[88:89], v[78:81], off sc1
	s_and_saveexec_b64 s[70:71], s[62:63]
	s_cbranch_execz .LBB0_265
	s_or_b32 s62, s61, s80
	v_cmp_gt_u32_e32 vcc, s40, v146
	v_lshl_or_b32 v90, s62, 8, v86
	v_ashrrev_i32_e32 v91, 31, v90
	v_cndmask_b32_e32 v130, v208, v209, vcc
	v_lshl_add_u64 v[88:89], s[16:17], 0, v[130:131]
	v_lshlrev_b64 v[90:91], 9, v[90:91]
	v_cndmask_b32_e32 v87, v210, v211, vcc
	v_lshl_add_u64 v[88:89], v[88:89], 0, v[90:91]
	v_add_u32_e32 v90, v87, v146
	v_ashrrev_i32_e32 v91, 31, v90
	v_lshl_add_u64 v[88:89], v[90:91], 2, v[88:89]
	global_store_dwordx4 v[88:89], v[78:81], off sc1

.LBB0_267:
	v_cmp_gt_u32_e32 vcc, s91, v128
	v_lshl_add_u64 v[78:79], v[126:127], 2, v[84:85]
	s_and_b64 s[62:63], vcc, s[0:1]
	global_store_dwordx4 v[78:79], v[74:77], off sc1
	s_and_saveexec_b64 s[70:71], s[62:63]
	s_cbranch_execz .LBB0_269
	s_or_b32 s62, s61, s80
	v_cmp_gt_u32_e32 vcc, s40, v126
	v_lshl_or_b32 v80, s62, 8, v86
	v_ashrrev_i32_e32 v81, 31, v80
	v_cndmask_b32_e32 v130, v208, v209, vcc
	v_lshl_add_u64 v[78:79], s[16:17], 0, v[130:131]
	v_lshlrev_b64 v[80:81], 9, v[80:81]
	v_lshl_add_u64 v[78:79], v[78:79], 0, v[80:81]
	v_cndmask_b32_e32 v80, v210, v211, vcc
	v_add_u32_e32 v80, v80, v126
	v_ashrrev_i32_e32 v81, 31, v80
	v_lshl_add_u64 v[78:79], v[80:81], 2, v[78:79]
	global_store_dwordx4 v[78:79], v[74:77], off sc1

.LBB0_271:
	v_cmp_gt_u32_e32 vcc, s91, v124
	v_lshl_add_u64 v[74:75], v[122:123], 2, v[84:85]
	s_and_b64 s[62:63], vcc, s[0:1]
	global_store_dwordx4 v[74:75], v[70:73], off sc1
	s_and_saveexec_b64 s[70:71], s[62:63]
	s_cbranch_execz .LBB0_273
	s_or_b32 s62, s61, s80
	v_cmp_gt_u32_e32 vcc, s40, v122
	v_lshl_or_b32 v76, s62, 8, v86
	v_ashrrev_i32_e32 v77, 31, v76
	v_cndmask_b32_e32 v130, v208, v209, vcc
	v_lshl_add_u64 v[74:75], s[16:17], 0, v[130:131]
	v_lshlrev_b64 v[76:77], 9, v[76:77]
	v_lshl_add_u64 v[74:75], v[74:75], 0, v[76:77]
	v_cndmask_b32_e32 v76, v210, v211, vcc
	v_add_u32_e32 v76, v76, v122
	v_ashrrev_i32_e32 v77, 31, v76
	v_lshl_add_u64 v[74:75], v[76:77], 2, v[74:75]
	global_store_dwordx4 v[74:75], v[70:73], off sc1

.LBB0_276:
	v_cmp_gt_u32_e32 vcc, s39, v126
	s_and_saveexec_b64 s[78:79], vcc
	s_cbranch_execz .LBB0_278
	v_mul_f32_e32 v78, 0xbfb8aa3b, v74
	v_exp_f32_e32 v78, v78
	v_mov_b32_e32 v130, v126
	v_add_f32_e32 v78, 1.0, v78
	v_div_scale_f32 v79, s[22:23], v78, v78, v74
	v_rcp_f32_e32 v80, v79
	s_nop 0
	v_fma_f32 v81, -v79, v80, 1.0
	v_fmac_f32_e32 v80, v81, v80
	v_div_scale_f32 v81, vcc, v74, v78, v74
	v_mul_f32_e32 v87, v81, v80
	v_fma_f32 v88, -v79, v87, v81
	v_fmac_f32_e32 v87, v88, v80
	v_fma_f32 v79, -v79, v87, v81
	v_div_fmas_f32 v79, v79, v80, v87
	v_div_fixup_f32 v78, v79, v78, v74
	v_mul_f32_e32 v79, 0xbfb8aa3b, v75
	v_exp_f32_e32 v79, v79
	s_nop 0
	v_add_f32_e32 v79, 1.0, v79
	v_div_scale_f32 v80, s[22:23], v79, v79, v75
	v_rcp_f32_e32 v81, v80
	s_nop 0
	v_fma_f32 v87, -v80, v81, 1.0
	v_fmac_f32_e32 v81, v87, v81
	v_div_scale_f32 v87, vcc, v75, v79, v75
	v_mul_f32_e32 v88, v87, v81
	v_fma_f32 v89, -v80, v88, v87
	v_fmac_f32_e32 v88, v89, v81
	v_fma_f32 v80, -v80, v88, v87
	v_div_fmas_f32 v80, v80, v81, v88
	v_div_fixup_f32 v79, v80, v79, v75
	v_cvt_pk_bf16_f32 v78, v78, v79
	v_mul_f32_e32 v79, 0xbfb8aa3b, v76
	v_exp_f32_e32 v79, v79
	s_nop 0
	v_add_f32_e32 v79, 1.0, v79
	v_div_scale_f32 v80, s[22:23], v79, v79, v76
	v_rcp_f32_e32 v81, v80
	s_nop 0
	v_fma_f32 v87, -v80, v81, 1.0
	v_fmac_f32_e32 v81, v87, v81
	v_div_scale_f32 v87, vcc, v76, v79, v76
	v_mul_f32_e32 v88, v87, v81
	v_fma_f32 v89, -v80, v88, v87
	v_fmac_f32_e32 v88, v89, v81
	v_fma_f32 v80, -v80, v88, v87
	v_div_fmas_f32 v80, v80, v81, v88
	v_div_fixup_f32 v79, v80, v79, v76
	v_mul_f32_e32 v80, 0xbfb8aa3b, v77
	v_exp_f32_e32 v80, v80
	s_nop 0
	v_add_f32_e32 v80, 1.0, v80
	v_div_scale_f32 v81, s[22:23], v80, v80, v77
	v_rcp_f32_e32 v87, v81
	s_nop 0
	v_fma_f32 v88, -v81, v87, 1.0
	v_fmac_f32_e32 v87, v88, v87
	v_div_scale_f32 v88, vcc, v77, v80, v77
	v_mul_f32_e32 v89, v88, v87
	v_fma_f32 v90, -v81, v89, v88
	v_fmac_f32_e32 v89, v90, v87
	v_fma_f32 v81, -v81, v89, v88
	v_div_fmas_f32 v81, v81, v87, v89
	v_div_fixup_f32 v80, v81, v80, v77
	v_cvt_pk_bf16_f32 v79, v79, v80
	v_lshl_add_u64 v[80:81], s[30:31], 0, v[82:83]
	v_lshl_add_u64 v[80:81], v[130:131], 1, v[80:81]
	v_add_co_u32_e32 v80, vcc, 0xfffff000, v80
	s_nop 1
	v_addc_co_u32_e32 v81, vcc, -1, v81, vcc
	global_store_dwordx2 v[80:81], v[78:79], off offset:-256 sc1

.LBB0_280:
	v_cmp_gt_u32_e32 vcc, s39, v122
	s_and_saveexec_b64 s[78:79], vcc
	s_cbranch_execz .LBB0_282
	v_mul_f32_e32 v74, 0xbfb8aa3b, v70
	v_exp_f32_e32 v74, v74
	v_mov_b32_e32 v130, v122
	v_add_f32_e32 v74, 1.0, v74
	v_div_scale_f32 v75, s[22:23], v74, v74, v70
	v_rcp_f32_e32 v76, v75
	s_nop 0
	v_fma_f32 v77, -v75, v76, 1.0
	v_fmac_f32_e32 v76, v77, v76
	v_div_scale_f32 v77, vcc, v70, v74, v70
	v_mul_f32_e32 v78, v77, v76
	v_fma_f32 v79, -v75, v78, v77
	v_fmac_f32_e32 v78, v79, v76
	v_fma_f32 v75, -v75, v78, v77
	v_div_fmas_f32 v75, v75, v76, v78
	v_div_fixup_f32 v74, v75, v74, v70
	v_mul_f32_e32 v75, 0xbfb8aa3b, v71
	v_exp_f32_e32 v75, v75
	s_nop 0
	v_add_f32_e32 v75, 1.0, v75
	v_div_scale_f32 v76, s[22:23], v75, v75, v71
	v_rcp_f32_e32 v77, v76
	s_nop 0
	v_fma_f32 v78, -v76, v77, 1.0
	v_fmac_f32_e32 v77, v78, v77
	v_div_scale_f32 v78, vcc, v71, v75, v71
	v_mul_f32_e32 v79, v78, v77
	v_fma_f32 v80, -v76, v79, v78
	v_fmac_f32_e32 v79, v80, v77
	v_fma_f32 v76, -v76, v79, v78
	v_div_fmas_f32 v76, v76, v77, v79
	v_div_fixup_f32 v75, v76, v75, v71
	v_cvt_pk_bf16_f32 v74, v74, v75
	v_mul_f32_e32 v75, 0xbfb8aa3b, v72
	v_exp_f32_e32 v75, v75
	s_nop 0
	v_add_f32_e32 v75, 1.0, v75
	v_div_scale_f32 v76, s[22:23], v75, v75, v72
	v_rcp_f32_e32 v77, v76
	s_nop 0
	v_fma_f32 v78, -v76, v77, 1.0
	v_fmac_f32_e32 v77, v78, v77
	v_div_scale_f32 v78, vcc, v72, v75, v72
	v_mul_f32_e32 v79, v78, v77
	v_fma_f32 v80, -v76, v79, v78
	v_fmac_f32_e32 v79, v80, v77
	v_fma_f32 v76, -v76, v79, v78
	v_div_fmas_f32 v76, v76, v77, v79
	v_div_fixup_f32 v75, v76, v75, v72
	v_mul_f32_e32 v76, 0xbfb8aa3b, v73
	v_exp_f32_e32 v76, v76
	s_nop 0
	v_add_f32_e32 v76, 1.0, v76
	v_div_scale_f32 v77, s[22:23], v76, v76, v73
	v_rcp_f32_e32 v78, v77
	s_nop 0
	v_fma_f32 v79, -v77, v78, 1.0
	v_fmac_f32_e32 v78, v79, v78
	v_div_scale_f32 v79, vcc, v73, v76, v73
	v_mul_f32_e32 v80, v79, v78
	v_fma_f32 v81, -v77, v80, v79
	v_fmac_f32_e32 v80, v81, v78
	v_fma_f32 v77, -v77, v80, v79
	v_div_fmas_f32 v77, v77, v78, v80
	v_div_fixup_f32 v76, v77, v76, v73
	v_cvt_pk_bf16_f32 v75, v75, v76
	v_lshl_add_u64 v[76:77], s[30:31], 0, v[82:83]
	v_lshl_add_u64 v[76:77], v[130:131], 1, v[76:77]
	v_add_co_u32_e32 v76, vcc, 0xfffff000, v76
	s_nop 1
	v_addc_co_u32_e32 v77, vcc, -1, v77, vcc
	global_store_dwordx2 v[76:77], v[74:75], off offset:-256 sc1

.LBB0_284:
	v_cmp_gt_u32_e32 vcc, s39, v118
	s_and_saveexec_b64 s[78:79], vcc
	s_cbranch_execz .LBB0_286
	v_mul_f32_e32 v70, 0xbfb8aa3b, v66
	v_exp_f32_e32 v70, v70
	v_mov_b32_e32 v130, v118
	v_add_f32_e32 v70, 1.0, v70
	v_div_scale_f32 v71, s[22:23], v70, v70, v66
	v_rcp_f32_e32 v72, v71
	s_nop 0
	v_fma_f32 v73, -v71, v72, 1.0
	v_fmac_f32_e32 v72, v73, v72
	v_div_scale_f32 v73, vcc, v66, v70, v66
	v_mul_f32_e32 v74, v73, v72
	v_fma_f32 v75, -v71, v74, v73
	v_fmac_f32_e32 v74, v75, v72
	v_fma_f32 v71, -v71, v74, v73
	v_div_fmas_f32 v71, v71, v72, v74
	v_div_fixup_f32 v70, v71, v70, v66
	v_mul_f32_e32 v71, 0xbfb8aa3b, v67
	v_exp_f32_e32 v71, v71
	s_nop 0
	v_add_f32_e32 v71, 1.0, v71
	v_div_scale_f32 v72, s[22:23], v71, v71, v67
	v_rcp_f32_e32 v73, v72
	s_nop 0
	v_fma_f32 v74, -v72, v73, 1.0
	v_fmac_f32_e32 v73, v74, v73
	v_div_scale_f32 v74, vcc, v67, v71, v67
	v_mul_f32_e32 v75, v74, v73
	v_fma_f32 v76, -v72, v75, v74
	v_fmac_f32_e32 v75, v76, v73
	v_fma_f32 v72, -v72, v75, v74
	v_div_fmas_f32 v72, v72, v73, v75
	v_div_fixup_f32 v71, v72, v71, v67
	v_cvt_pk_bf16_f32 v70, v70, v71
	v_mul_f32_e32 v71, 0xbfb8aa3b, v68
	v_exp_f32_e32 v71, v71
	s_nop 0
	v_add_f32_e32 v71, 1.0, v71
	v_div_scale_f32 v72, s[22:23], v71, v71, v68
	v_rcp_f32_e32 v73, v72
	s_nop 0
	v_fma_f32 v74, -v72, v73, 1.0
	v_fmac_f32_e32 v73, v74, v73
	v_div_scale_f32 v74, vcc, v68, v71, v68
	v_mul_f32_e32 v75, v74, v73
	v_fma_f32 v76, -v72, v75, v74
	v_fmac_f32_e32 v75, v76, v73
	v_fma_f32 v72, -v72, v75, v74
	v_div_fmas_f32 v72, v72, v73, v75
	v_div_fixup_f32 v71, v72, v71, v68
	v_mul_f32_e32 v72, 0xbfb8aa3b, v69
	v_exp_f32_e32 v72, v72
	s_nop 0
	v_add_f32_e32 v72, 1.0, v72
	v_div_scale_f32 v73, s[22:23], v72, v72, v69
	v_rcp_f32_e32 v74, v73
	s_nop 0
	v_fma_f32 v75, -v73, v74, 1.0
	v_fmac_f32_e32 v74, v75, v74
	v_div_scale_f32 v75, vcc, v69, v72, v69
	v_mul_f32_e32 v76, v75, v74
	v_fma_f32 v77, -v73, v76, v75
	v_fmac_f32_e32 v76, v77, v74
	v_fma_f32 v73, -v73, v76, v75
	v_div_fmas_f32 v73, v73, v74, v76
	v_div_fixup_f32 v72, v73, v72, v69
	v_cvt_pk_bf16_f32 v71, v71, v72
	v_lshl_add_u64 v[72:73], s[30:31], 0, v[82:83]
	v_lshl_add_u64 v[72:73], v[130:131], 1, v[72:73]
	v_add_co_u32_e32 v72, vcc, 0xfffff000, v72
	s_nop 1
	v_addc_co_u32_e32 v73, vcc, -1, v73, vcc
	global_store_dwordx2 v[72:73], v[70:71], off offset:-256 sc1

.LBB0_287:
	v_cmp_gt_u32_e32 vcc, s91, v120
	v_lshl_add_u64 v[70:71], v[118:119], 2, v[84:85]
	s_and_b64 s[62:63], vcc, s[0:1]
	global_store_dwordx4 v[70:71], v[66:69], off sc1
	s_and_saveexec_b64 s[0:1], s[62:63]
	s_cbranch_execz .LBB0_289
	s_or_b32 s61, s61, s80
	v_cmp_gt_u32_e32 vcc, s40, v118
	v_lshl_or_b32 v72, s61, 8, v86
	v_ashrrev_i32_e32 v73, 31, v72
	v_cndmask_b32_e32 v130, v208, v209, vcc
	v_lshl_add_u64 v[70:71], s[16:17], 0, v[130:131]
	v_lshlrev_b64 v[72:73], 9, v[72:73]
	v_lshl_add_u64 v[70:71], v[70:71], 0, v[72:73]
	v_cndmask_b32_e32 v72, v210, v211, vcc
	v_add_u32_e32 v72, v72, v118
	v_ashrrev_i32_e32 v73, 31, v72
	v_lshl_add_u64 v[70:71], v[72:73], 2, v[70:71]
	global_store_dwordx4 v[70:71], v[66:69], off sc1

.LBB0_290:
	s_or_b64 exec, exec, s[22:23]
	s_add_i32 s61, s13, 0x80
	v_or_b32_e32 v66, s61, v1
	v_ashrrev_i32_e32 v67, 31, v66
	v_lshlrev_b64 v[68:69], 11, v[66:67]
	v_cmp_gt_i32_e64 s[0:1], s37, v66
	s_and_saveexec_b64 s[22:23], s[10:11]
	s_xor_b64 s[70:71], exec, s[22:23]
	s_cbranch_execz .LBB0_294
	v_cmp_gt_u32_e32 vcc, s39, v146
	s_and_saveexec_b64 s[78:79], vcc
	s_cbranch_execz .LBB0_293
	v_mul_f32_e32 v67, 0xbfb8aa3b, v62
	v_exp_f32_e32 v67, v67
	v_mov_b32_e32 v130, v146
	v_add_f32_e32 v67, 1.0, v67
	v_div_scale_f32 v70, s[22:23], v67, v67, v62
	v_rcp_f32_e32 v71, v70
	s_nop 0
	v_fma_f32 v72, -v70, v71, 1.0
	v_fmac_f32_e32 v71, v72, v71
	v_div_scale_f32 v72, vcc, v62, v67, v62
	v_mul_f32_e32 v73, v72, v71
	v_fma_f32 v74, -v70, v73, v72
	v_fmac_f32_e32 v73, v74, v71
	v_fma_f32 v70, -v70, v73, v72
	v_div_fmas_f32 v70, v70, v71, v73
	v_div_fixup_f32 v67, v70, v67, v62
	v_mul_f32_e32 v70, 0xbfb8aa3b, v63
	v_exp_f32_e32 v70, v70
	s_nop 0
	v_add_f32_e32 v70, 1.0, v70
	v_div_scale_f32 v71, s[22:23], v70, v70, v63
	v_rcp_f32_e32 v72, v71
	s_nop 0
	v_fma_f32 v73, -v71, v72, 1.0
	v_fmac_f32_e32 v72, v73, v72
	v_div_scale_f32 v73, vcc, v63, v70, v63
	v_mul_f32_e32 v74, v73, v72
	v_fma_f32 v75, -v71, v74, v73
	v_fmac_f32_e32 v74, v75, v72
	v_fma_f32 v71, -v71, v74, v73
	v_div_fmas_f32 v71, v71, v72, v74
	v_div_fixup_f32 v70, v71, v70, v63
	v_cvt_pk_bf16_f32 v70, v67, v70
	v_mul_f32_e32 v67, 0xbfb8aa3b, v64
	v_exp_f32_e32 v67, v67
	s_nop 0
	v_add_f32_e32 v67, 1.0, v67
	v_div_scale_f32 v71, s[22:23], v67, v67, v64
	v_rcp_f32_e32 v72, v71
	s_nop 0
	v_fma_f32 v73, -v71, v72, 1.0
	v_fmac_f32_e32 v72, v73, v72
	v_div_scale_f32 v73, vcc, v64, v67, v64
	v_mul_f32_e32 v74, v73, v72
	v_fma_f32 v75, -v71, v74, v73
	v_fmac_f32_e32 v74, v75, v72
	v_fma_f32 v71, -v71, v74, v73
	v_div_fmas_f32 v71, v71, v72, v74
	v_div_fixup_f32 v67, v71, v67, v64
	v_mul_f32_e32 v71, 0xbfb8aa3b, v65
	v_exp_f32_e32 v71, v71
	s_nop 0
	v_add_f32_e32 v71, 1.0, v71
	v_div_scale_f32 v72, s[22:23], v71, v71, v65
	v_rcp_f32_e32 v73, v72
	s_nop 0
	v_fma_f32 v74, -v72, v73, 1.0
	v_fmac_f32_e32 v73, v74, v73
	v_div_scale_f32 v74, vcc, v65, v71, v65
	v_mul_f32_e32 v75, v74, v73
	v_fma_f32 v76, -v72, v75, v74
	v_fmac_f32_e32 v75, v76, v73
	v_fma_f32 v72, -v72, v75, v74
	v_div_fmas_f32 v72, v72, v73, v75
	v_div_fixup_f32 v71, v72, v71, v65
	v_lshl_add_u64 v[72:73], s[30:31], 0, v[68:69]
	v_lshl_add_u64 v[72:73], v[130:131], 1, v[72:73]
	v_add_co_u32_e32 v72, vcc, 0xfffff000, v72
	v_cvt_pk_bf16_f32 v71, v67, v71
	s_nop 1
	v_addc_co_u32_e32 v73, vcc, -1, v73, vcc
	global_store_dwordx2 v[72:73], v[70:71], off offset:-256 sc1

.LBB0_294:
	s_or_saveexec_b64 s[22:23], s[70:71]
	s_ashr_i32 s13, s61, 7
	v_mad_i64_i32 v[70:71], s[62:63], v66, s36, 0
	s_and_b32 s13, s13, -2
	v_bitop3_b32 v67, s61, v207, v1 bitop3:0xc8
	v_lshl_add_u64 v[70:71], s[28:29], 0, v[70:71]
	s_xor_b64 exec, exec, s[22:23]
	s_cbranch_execz .LBB0_307
	v_cmp_gt_u32_e32 vcc, s91, v149
	v_lshl_add_u64 v[72:73], v[146:147], 2, v[70:71]
	s_and_b64 s[62:63], vcc, s[0:1]
	global_store_dwordx4 v[72:73], v[62:65], off sc1
	s_and_saveexec_b64 s[70:71], s[62:63]
	s_cbranch_execz .LBB0_297
	s_or_b32 s61, s13, s80
	v_cmp_gt_u32_e32 vcc, s40, v146
	v_lshl_or_b32 v74, s61, 8, v67
	v_ashrrev_i32_e32 v75, 31, v74
	v_cndmask_b32_e32 v130, v208, v209, vcc
	v_lshl_add_u64 v[72:73], s[16:17], 0, v[130:131]
	v_lshlrev_b64 v[74:75], 9, v[74:75]
	v_lshl_add_u64 v[72:73], v[72:73], 0, v[74:75]
	v_cndmask_b32_e32 v74, v210, v211, vcc
	v_add_u32_e32 v74, v74, v146
	v_ashrrev_i32_e32 v75, 31, v74
	v_lshl_add_u64 v[72:73], v[74:75], 2, v[72:73]
	global_store_dwordx4 v[72:73], v[62:65], off sc1

.LBB0_299:
	v_cmp_gt_u32_e32 vcc, s91, v128
	v_lshl_add_u64 v[62:63], v[126:127], 2, v[70:71]
	s_and_b64 s[62:63], vcc, s[0:1]
	global_store_dwordx4 v[62:63], v[58:61], off sc1
	s_and_saveexec_b64 s[70:71], s[62:63]
	s_cbranch_execz .LBB0_301
	s_or_b32 s61, s13, s80
	v_cmp_gt_u32_e32 vcc, s40, v126
	v_lshl_or_b32 v64, s61, 8, v67
	v_ashrrev_i32_e32 v65, 31, v64
	v_cndmask_b32_e32 v130, v208, v209, vcc
	v_lshl_add_u64 v[62:63], s[16:17], 0, v[130:131]
	v_lshlrev_b64 v[64:65], 9, v[64:65]
	v_lshl_add_u64 v[62:63], v[62:63], 0, v[64:65]
	v_cndmask_b32_e32 v64, v210, v211, vcc
	v_add_u32_e32 v64, v64, v126
	v_ashrrev_i32_e32 v65, 31, v64
	v_lshl_add_u64 v[62:63], v[64:65], 2, v[62:63]
	global_store_dwordx4 v[62:63], v[58:61], off sc1

.LBB0_303:
	v_cmp_gt_u32_e32 vcc, s91, v124
	v_lshl_add_u64 v[58:59], v[122:123], 2, v[70:71]
	s_and_b64 s[62:63], vcc, s[0:1]
	global_store_dwordx4 v[58:59], v[54:57], off sc1
	s_and_saveexec_b64 s[70:71], s[62:63]
	s_cbranch_execz .LBB0_305
	s_or_b32 s61, s13, s80
	v_cmp_gt_u32_e32 vcc, s40, v122
	v_lshl_or_b32 v60, s61, 8, v67
	v_ashrrev_i32_e32 v61, 31, v60
	v_cndmask_b32_e32 v130, v208, v209, vcc
	v_lshl_add_u64 v[58:59], s[16:17], 0, v[130:131]
	v_lshlrev_b64 v[60:61], 9, v[60:61]
	v_lshl_add_u64 v[58:59], v[58:59], 0, v[60:61]
	v_cndmask_b32_e32 v60, v210, v211, vcc
	v_add_u32_e32 v60, v60, v122
	v_ashrrev_i32_e32 v61, 31, v60
	v_lshl_add_u64 v[58:59], v[60:61], 2, v[58:59]
	global_store_dwordx4 v[58:59], v[54:57], off sc1

.LBB0_308:
	v_cmp_gt_u32_e32 vcc, s39, v126
	s_and_saveexec_b64 s[78:79], vcc
	s_cbranch_execz .LBB0_310
	v_mul_f32_e32 v62, 0xbfb8aa3b, v58
	v_exp_f32_e32 v62, v62
	v_mov_b32_e32 v130, v126
	v_add_f32_e32 v62, 1.0, v62
	v_div_scale_f32 v63, s[22:23], v62, v62, v58
	v_rcp_f32_e32 v64, v63
	s_nop 0
	v_fma_f32 v65, -v63, v64, 1.0
	v_fmac_f32_e32 v64, v65, v64
	v_div_scale_f32 v65, vcc, v58, v62, v58
	v_mul_f32_e32 v72, v65, v64
	v_fma_f32 v73, -v63, v72, v65
	v_fmac_f32_e32 v72, v73, v64
	v_fma_f32 v63, -v63, v72, v65
	v_div_fmas_f32 v63, v63, v64, v72
	v_div_fixup_f32 v62, v63, v62, v58
	v_mul_f32_e32 v63, 0xbfb8aa3b, v59
	v_exp_f32_e32 v63, v63
	s_nop 0
	v_add_f32_e32 v63, 1.0, v63
	v_div_scale_f32 v64, s[22:23], v63, v63, v59
	v_rcp_f32_e32 v65, v64
	s_nop 0
	v_fma_f32 v72, -v64, v65, 1.0
	v_fmac_f32_e32 v65, v72, v65
	v_div_scale_f32 v72, vcc, v59, v63, v59
	v_mul_f32_e32 v73, v72, v65
	v_fma_f32 v74, -v64, v73, v72
	v_fmac_f32_e32 v73, v74, v65
	v_fma_f32 v64, -v64, v73, v72
	v_div_fmas_f32 v64, v64, v65, v73
	v_div_fixup_f32 v63, v64, v63, v59
	v_cvt_pk_bf16_f32 v62, v62, v63
	v_mul_f32_e32 v63, 0xbfb8aa3b, v60
	v_exp_f32_e32 v63, v63
	s_nop 0
	v_add_f32_e32 v63, 1.0, v63
	v_div_scale_f32 v64, s[22:23], v63, v63, v60
	v_rcp_f32_e32 v65, v64
	s_nop 0
	v_fma_f32 v72, -v64, v65, 1.0
	v_fmac_f32_e32 v65, v72, v65
	v_div_scale_f32 v72, vcc, v60, v63, v60
	v_mul_f32_e32 v73, v72, v65
	v_fma_f32 v74, -v64, v73, v72
	v_fmac_f32_e32 v73, v74, v65
	v_fma_f32 v64, -v64, v73, v72
	v_div_fmas_f32 v64, v64, v65, v73
	v_div_fixup_f32 v63, v64, v63, v60
	v_mul_f32_e32 v64, 0xbfb8aa3b, v61
	v_exp_f32_e32 v64, v64
	s_nop 0
	v_add_f32_e32 v64, 1.0, v64
	v_div_scale_f32 v65, s[22:23], v64, v64, v61
	v_rcp_f32_e32 v72, v65
	s_nop 0
	v_fma_f32 v73, -v65, v72, 1.0
	v_fmac_f32_e32 v72, v73, v72
	v_div_scale_f32 v73, vcc, v61, v64, v61
	v_mul_f32_e32 v74, v73, v72
	v_fma_f32 v75, -v65, v74, v73
	v_fmac_f32_e32 v74, v75, v72
	v_fma_f32 v65, -v65, v74, v73
	v_div_fmas_f32 v65, v65, v72, v74
	v_div_fixup_f32 v64, v65, v64, v61
	v_cvt_pk_bf16_f32 v63, v63, v64
	v_lshl_add_u64 v[64:65], s[30:31], 0, v[68:69]
	v_lshl_add_u64 v[64:65], v[130:131], 1, v[64:65]
	v_add_co_u32_e32 v64, vcc, 0xfffff000, v64
	s_nop 1
	v_addc_co_u32_e32 v65, vcc, -1, v65, vcc
	global_store_dwordx2 v[64:65], v[62:63], off offset:-256 sc1

.LBB0_312:
	v_cmp_gt_u32_e32 vcc, s39, v122
	s_and_saveexec_b64 s[78:79], vcc
	s_cbranch_execz .LBB0_314
	v_mul_f32_e32 v58, 0xbfb8aa3b, v54
	v_exp_f32_e32 v58, v58
	v_mov_b32_e32 v130, v122
	v_add_f32_e32 v58, 1.0, v58
	v_div_scale_f32 v59, s[22:23], v58, v58, v54
	v_rcp_f32_e32 v60, v59
	s_nop 0
	v_fma_f32 v61, -v59, v60, 1.0
	v_fmac_f32_e32 v60, v61, v60
	v_div_scale_f32 v61, vcc, v54, v58, v54
	v_mul_f32_e32 v62, v61, v60
	v_fma_f32 v63, -v59, v62, v61
	v_fmac_f32_e32 v62, v63, v60
	v_fma_f32 v59, -v59, v62, v61
	v_div_fmas_f32 v59, v59, v60, v62
	v_div_fixup_f32 v58, v59, v58, v54
	v_mul_f32_e32 v59, 0xbfb8aa3b, v55
	v_exp_f32_e32 v59, v59
	s_nop 0
	v_add_f32_e32 v59, 1.0, v59
	v_div_scale_f32 v60, s[22:23], v59, v59, v55
	v_rcp_f32_e32 v61, v60
	s_nop 0
	v_fma_f32 v62, -v60, v61, 1.0
	v_fmac_f32_e32 v61, v62, v61
	v_div_scale_f32 v62, vcc, v55, v59, v55
	v_mul_f32_e32 v63, v62, v61
	v_fma_f32 v64, -v60, v63, v62
	v_fmac_f32_e32 v63, v64, v61
	v_fma_f32 v60, -v60, v63, v62
	v_div_fmas_f32 v60, v60, v61, v63
	v_div_fixup_f32 v59, v60, v59, v55
	v_cvt_pk_bf16_f32 v58, v58, v59
	v_mul_f32_e32 v59, 0xbfb8aa3b, v56
	v_exp_f32_e32 v59, v59
	s_nop 0
	v_add_f32_e32 v59, 1.0, v59
	v_div_scale_f32 v60, s[22:23], v59, v59, v56
	v_rcp_f32_e32 v61, v60
	s_nop 0
	v_fma_f32 v62, -v60, v61, 1.0
	v_fmac_f32_e32 v61, v62, v61
	v_div_scale_f32 v62, vcc, v56, v59, v56
	v_mul_f32_e32 v63, v62, v61
	v_fma_f32 v64, -v60, v63, v62
	v_fmac_f32_e32 v63, v64, v61
	v_fma_f32 v60, -v60, v63, v62
	v_div_fmas_f32 v60, v60, v61, v63
	v_div_fixup_f32 v59, v60, v59, v56
	v_mul_f32_e32 v60, 0xbfb8aa3b, v57
	v_exp_f32_e32 v60, v60
	s_nop 0
	v_add_f32_e32 v60, 1.0, v60
	v_div_scale_f32 v61, s[22:23], v60, v60, v57
	v_rcp_f32_e32 v62, v61
	s_nop 0
	v_fma_f32 v63, -v61, v62, 1.0
	v_fmac_f32_e32 v62, v63, v62
	v_div_scale_f32 v63, vcc, v57, v60, v57
	v_mul_f32_e32 v64, v63, v62
	v_fma_f32 v65, -v61, v64, v63
	v_fmac_f32_e32 v64, v65, v62
	v_fma_f32 v61, -v61, v64, v63
	v_div_fmas_f32 v61, v61, v62, v64
	v_div_fixup_f32 v60, v61, v60, v57
	v_cvt_pk_bf16_f32 v59, v59, v60
	v_lshl_add_u64 v[60:61], s[30:31], 0, v[68:69]
	v_lshl_add_u64 v[60:61], v[130:131], 1, v[60:61]
	v_add_co_u32_e32 v60, vcc, 0xfffff000, v60
	s_nop 1
	v_addc_co_u32_e32 v61, vcc, -1, v61, vcc
	global_store_dwordx2 v[60:61], v[58:59], off offset:-256 sc1

.LBB0_316:
	v_cmp_gt_u32_e32 vcc, s39, v118
	s_and_saveexec_b64 s[78:79], vcc
	s_cbranch_execz .LBB0_318
	v_mul_f32_e32 v54, 0xbfb8aa3b, v50
	v_exp_f32_e32 v54, v54
	v_mov_b32_e32 v130, v118
	v_add_f32_e32 v54, 1.0, v54
	v_div_scale_f32 v55, s[22:23], v54, v54, v50
	v_rcp_f32_e32 v56, v55
	s_nop 0
	v_fma_f32 v57, -v55, v56, 1.0
	v_fmac_f32_e32 v56, v57, v56
	v_div_scale_f32 v57, vcc, v50, v54, v50
	v_mul_f32_e32 v58, v57, v56
	v_fma_f32 v59, -v55, v58, v57
	v_fmac_f32_e32 v58, v59, v56
	v_fma_f32 v55, -v55, v58, v57
	v_div_fmas_f32 v55, v55, v56, v58
	v_div_fixup_f32 v54, v55, v54, v50
	v_mul_f32_e32 v55, 0xbfb8aa3b, v51
	v_exp_f32_e32 v55, v55
	s_nop 0
	v_add_f32_e32 v55, 1.0, v55
	v_div_scale_f32 v56, s[22:23], v55, v55, v51
	v_rcp_f32_e32 v57, v56
	s_nop 0
	v_fma_f32 v58, -v56, v57, 1.0
	v_fmac_f32_e32 v57, v58, v57
	v_div_scale_f32 v58, vcc, v51, v55, v51
	v_mul_f32_e32 v59, v58, v57
	v_fma_f32 v60, -v56, v59, v58
	v_fmac_f32_e32 v59, v60, v57
	v_fma_f32 v56, -v56, v59, v58
	v_div_fmas_f32 v56, v56, v57, v59
	v_div_fixup_f32 v55, v56, v55, v51
	v_cvt_pk_bf16_f32 v54, v54, v55
	v_mul_f32_e32 v55, 0xbfb8aa3b, v52
	v_exp_f32_e32 v55, v55
	s_nop 0
	v_add_f32_e32 v55, 1.0, v55
	v_div_scale_f32 v56, s[22:23], v55, v55, v52
	v_rcp_f32_e32 v57, v56
	s_nop 0
	v_fma_f32 v58, -v56, v57, 1.0
	v_fmac_f32_e32 v57, v58, v57
	v_div_scale_f32 v58, vcc, v52, v55, v52
	v_mul_f32_e32 v59, v58, v57
	v_fma_f32 v60, -v56, v59, v58
	v_fmac_f32_e32 v59, v60, v57
	v_fma_f32 v56, -v56, v59, v58
	v_div_fmas_f32 v56, v56, v57, v59
	v_div_fixup_f32 v55, v56, v55, v52
	v_mul_f32_e32 v56, 0xbfb8aa3b, v53
	v_exp_f32_e32 v56, v56
	s_nop 0
	v_add_f32_e32 v56, 1.0, v56
	v_div_scale_f32 v57, s[22:23], v56, v56, v53
	v_rcp_f32_e32 v58, v57
	s_nop 0
	v_fma_f32 v59, -v57, v58, 1.0
	v_fmac_f32_e32 v58, v59, v58
	v_div_scale_f32 v59, vcc, v53, v56, v53
	v_mul_f32_e32 v60, v59, v58
	v_fma_f32 v61, -v57, v60, v59
	v_fmac_f32_e32 v60, v61, v58
	v_fma_f32 v57, -v57, v60, v59
	v_div_fmas_f32 v57, v57, v58, v60
	v_div_fixup_f32 v56, v57, v56, v53
	v_cvt_pk_bf16_f32 v55, v55, v56
	v_lshl_add_u64 v[56:57], s[30:31], 0, v[68:69]
	v_lshl_add_u64 v[56:57], v[130:131], 1, v[56:57]
	v_add_co_u32_e32 v56, vcc, 0xfffff000, v56
	s_nop 1
	v_addc_co_u32_e32 v57, vcc, -1, v57, vcc
	global_store_dwordx2 v[56:57], v[54:55], off offset:-256 sc1

.LBB0_319:
	v_cmp_gt_u32_e32 vcc, s91, v120
	v_lshl_add_u64 v[54:55], v[118:119], 2, v[70:71]
	s_and_b64 s[62:63], vcc, s[0:1]
	global_store_dwordx4 v[54:55], v[50:53], off sc1
	s_and_saveexec_b64 s[0:1], s[62:63]
	s_cbranch_execz .LBB0_321
	s_or_b32 s61, s13, s80
	v_cmp_gt_u32_e32 vcc, s40, v118
	v_lshl_or_b32 v56, s61, 8, v67
	v_ashrrev_i32_e32 v57, 31, v56
	v_cndmask_b32_e32 v130, v208, v209, vcc
	v_lshl_add_u64 v[54:55], s[16:17], 0, v[130:131]
	v_lshlrev_b64 v[56:57], 9, v[56:57]
	v_lshl_add_u64 v[54:55], v[54:55], 0, v[56:57]
	v_cndmask_b32_e32 v56, v210, v211, vcc
	v_add_u32_e32 v56, v56, v118
	v_ashrrev_i32_e32 v57, 31, v56
	v_lshl_add_u64 v[54:55], v[56:57], 2, v[54:55]
	global_store_dwordx4 v[54:55], v[50:53], off sc1

.LBB0_322:
	s_or_b64 exec, exec, s[22:23]
	v_or_b32_e32 v52, 16, v66
	v_ashrrev_i32_e32 v53, 31, v52
	v_lshlrev_b64 v[50:51], 11, v[52:53]
	v_cmp_gt_i32_e64 s[0:1], s37, v52
	s_and_saveexec_b64 s[22:23], s[10:11]
	s_xor_b64 s[70:71], exec, s[22:23]
	s_cbranch_execz .LBB0_326
	v_cmp_gt_u32_e32 vcc, s39, v146
	s_and_saveexec_b64 s[78:79], vcc
	s_cbranch_execz .LBB0_325
	v_mul_f32_e32 v53, 0xbfb8aa3b, v46
	v_exp_f32_e32 v53, v53
	v_mov_b32_e32 v130, v146
	v_add_f32_e32 v53, 1.0, v53
	v_div_scale_f32 v54, s[22:23], v53, v53, v46
	v_rcp_f32_e32 v55, v54
	s_nop 0
	v_fma_f32 v56, -v54, v55, 1.0
	v_fmac_f32_e32 v55, v56, v55
	v_div_scale_f32 v56, vcc, v46, v53, v46
	v_mul_f32_e32 v57, v56, v55
	v_fma_f32 v58, -v54, v57, v56
	v_fmac_f32_e32 v57, v58, v55
	v_fma_f32 v54, -v54, v57, v56
	v_div_fmas_f32 v54, v54, v55, v57
	v_div_fixup_f32 v53, v54, v53, v46
	v_mul_f32_e32 v54, 0xbfb8aa3b, v47
	v_exp_f32_e32 v54, v54
	s_nop 0
	v_add_f32_e32 v54, 1.0, v54
	v_div_scale_f32 v55, s[22:23], v54, v54, v47
	v_rcp_f32_e32 v56, v55
	s_nop 0
	v_fma_f32 v57, -v55, v56, 1.0
	v_fmac_f32_e32 v56, v57, v56
	v_div_scale_f32 v57, vcc, v47, v54, v47
	v_mul_f32_e32 v58, v57, v56
	v_fma_f32 v59, -v55, v58, v57
	v_fmac_f32_e32 v58, v59, v56
	v_fma_f32 v55, -v55, v58, v57
	v_div_fmas_f32 v55, v55, v56, v58
	v_div_fixup_f32 v54, v55, v54, v47
	v_cvt_pk_bf16_f32 v54, v53, v54
	v_mul_f32_e32 v53, 0xbfb8aa3b, v48
	v_exp_f32_e32 v53, v53
	s_nop 0
	v_add_f32_e32 v53, 1.0, v53
	v_div_scale_f32 v55, s[22:23], v53, v53, v48
	v_rcp_f32_e32 v56, v55
	s_nop 0
	v_fma_f32 v57, -v55, v56, 1.0
	v_fmac_f32_e32 v56, v57, v56
	v_div_scale_f32 v57, vcc, v48, v53, v48
	v_mul_f32_e32 v58, v57, v56
	v_fma_f32 v59, -v55, v58, v57
	v_fmac_f32_e32 v58, v59, v56
	v_fma_f32 v55, -v55, v58, v57
	v_div_fmas_f32 v55, v55, v56, v58
	v_div_fixup_f32 v53, v55, v53, v48
	v_mul_f32_e32 v55, 0xbfb8aa3b, v49
	v_exp_f32_e32 v55, v55
	s_nop 0
	v_add_f32_e32 v55, 1.0, v55
	v_div_scale_f32 v56, s[22:23], v55, v55, v49
	v_rcp_f32_e32 v57, v56
	s_nop 0
	v_fma_f32 v58, -v56, v57, 1.0
	v_fmac_f32_e32 v57, v58, v57
	v_div_scale_f32 v58, vcc, v49, v55, v49
	v_mul_f32_e32 v59, v58, v57
	v_fma_f32 v60, -v56, v59, v58
	v_fmac_f32_e32 v59, v60, v57
	v_fma_f32 v56, -v56, v59, v58
	v_div_fmas_f32 v56, v56, v57, v59
	v_div_fixup_f32 v55, v56, v55, v49
	v_lshl_add_u64 v[56:57], s[30:31], 0, v[50:51]
	v_lshl_add_u64 v[56:57], v[130:131], 1, v[56:57]
	v_add_co_u32_e32 v56, vcc, 0xfffff000, v56
	v_cvt_pk_bf16_f32 v55, v53, v55
	s_nop 1
	v_addc_co_u32_e32 v57, vcc, -1, v57, vcc
	global_store_dwordx2 v[56:57], v[54:55], off offset:-256 sc1

.LBB0_326:
	s_or_saveexec_b64 s[22:23], s[70:71]
	v_mad_i64_i32 v[52:53], s[62:63], v52, s36, 0
	v_bitop3_b32 v54, v66, s42, 16 bitop3:0xc8
	v_lshl_add_u64 v[52:53], s[28:29], 0, v[52:53]
	s_xor_b64 exec, exec, s[22:23]
	s_cbranch_execz .LBB0_339
	v_cmp_gt_u32_e32 vcc, s91, v149
	v_lshl_add_u64 v[56:57], v[146:147], 2, v[52:53]
	s_and_b64 s[62:63], vcc, s[0:1]
	global_store_dwordx4 v[56:57], v[46:49], off sc1
	s_and_saveexec_b64 s[70:71], s[62:63]
	s_cbranch_execz .LBB0_329
	s_or_b32 s61, s13, s80
	v_cmp_gt_u32_e32 vcc, s40, v146
	v_lshl_or_b32 v58, s61, 8, v54
	v_ashrrev_i32_e32 v59, 31, v58
	v_cndmask_b32_e32 v130, v208, v209, vcc
	v_lshl_add_u64 v[56:57], s[16:17], 0, v[130:131]
	v_lshlrev_b64 v[58:59], 9, v[58:59]
	v_cndmask_b32_e32 v55, v210, v211, vcc
	v_lshl_add_u64 v[56:57], v[56:57], 0, v[58:59]
	v_add_u32_e32 v58, v55, v146
	v_ashrrev_i32_e32 v59, 31, v58
	v_lshl_add_u64 v[56:57], v[58:59], 2, v[56:57]
	global_store_dwordx4 v[56:57], v[46:49], off sc1

.LBB0_331:
	v_cmp_gt_u32_e32 vcc, s91, v128
	v_lshl_add_u64 v[46:47], v[126:127], 2, v[52:53]
	s_and_b64 s[62:63], vcc, s[0:1]
	global_store_dwordx4 v[46:47], v[42:45], off sc1
	s_and_saveexec_b64 s[70:71], s[62:63]
	s_cbranch_execz .LBB0_333
	s_or_b32 s61, s13, s80
	v_cmp_gt_u32_e32 vcc, s40, v126
	v_lshl_or_b32 v48, s61, 8, v54
	v_ashrrev_i32_e32 v49, 31, v48
	v_cndmask_b32_e32 v130, v208, v209, vcc
	v_lshl_add_u64 v[46:47], s[16:17], 0, v[130:131]
	v_lshlrev_b64 v[48:49], 9, v[48:49]
	v_lshl_add_u64 v[46:47], v[46:47], 0, v[48:49]
	v_cndmask_b32_e32 v48, v210, v211, vcc
	v_add_u32_e32 v48, v48, v126
	v_ashrrev_i32_e32 v49, 31, v48
	v_lshl_add_u64 v[46:47], v[48:49], 2, v[46:47]
	global_store_dwordx4 v[46:47], v[42:45], off sc1

.LBB0_335:
	v_cmp_gt_u32_e32 vcc, s91, v124
	v_lshl_add_u64 v[42:43], v[122:123], 2, v[52:53]
	s_and_b64 s[62:63], vcc, s[0:1]
	global_store_dwordx4 v[42:43], v[38:41], off sc1
	s_and_saveexec_b64 s[70:71], s[62:63]
	s_cbranch_execz .LBB0_337
	s_or_b32 s61, s13, s80
	v_cmp_gt_u32_e32 vcc, s40, v122
	v_lshl_or_b32 v44, s61, 8, v54
	v_ashrrev_i32_e32 v45, 31, v44
	v_cndmask_b32_e32 v130, v208, v209, vcc
	v_lshl_add_u64 v[42:43], s[16:17], 0, v[130:131]
	v_lshlrev_b64 v[44:45], 9, v[44:45]
	v_lshl_add_u64 v[42:43], v[42:43], 0, v[44:45]
	v_cndmask_b32_e32 v44, v210, v211, vcc
	v_add_u32_e32 v44, v44, v122
	v_ashrrev_i32_e32 v45, 31, v44
	v_lshl_add_u64 v[42:43], v[44:45], 2, v[42:43]
	global_store_dwordx4 v[42:43], v[38:41], off sc1

.LBB0_340:
	v_cmp_gt_u32_e32 vcc, s39, v126
	s_and_saveexec_b64 s[78:79], vcc
	s_cbranch_execz .LBB0_342
	v_mul_f32_e32 v46, 0xbfb8aa3b, v42
	v_exp_f32_e32 v46, v46
	v_mov_b32_e32 v130, v126
	v_add_f32_e32 v46, 1.0, v46
	v_div_scale_f32 v47, s[22:23], v46, v46, v42
	v_rcp_f32_e32 v48, v47
	s_nop 0
	v_fma_f32 v49, -v47, v48, 1.0
	v_fmac_f32_e32 v48, v49, v48
	v_div_scale_f32 v49, vcc, v42, v46, v42
	v_mul_f32_e32 v55, v49, v48
	v_fma_f32 v56, -v47, v55, v49
	v_fmac_f32_e32 v55, v56, v48
	v_fma_f32 v47, -v47, v55, v49
	v_div_fmas_f32 v47, v47, v48, v55
	v_div_fixup_f32 v46, v47, v46, v42
	v_mul_f32_e32 v47, 0xbfb8aa3b, v43
	v_exp_f32_e32 v47, v47
	s_nop 0
	v_add_f32_e32 v47, 1.0, v47
	v_div_scale_f32 v48, s[22:23], v47, v47, v43
	v_rcp_f32_e32 v49, v48
	s_nop 0
	v_fma_f32 v55, -v48, v49, 1.0
	v_fmac_f32_e32 v49, v55, v49
	v_div_scale_f32 v55, vcc, v43, v47, v43
	v_mul_f32_e32 v56, v55, v49
	v_fma_f32 v57, -v48, v56, v55
	v_fmac_f32_e32 v56, v57, v49
	v_fma_f32 v48, -v48, v56, v55
	v_div_fmas_f32 v48, v48, v49, v56
	v_div_fixup_f32 v47, v48, v47, v43
	v_cvt_pk_bf16_f32 v46, v46, v47
	v_mul_f32_e32 v47, 0xbfb8aa3b, v44
	v_exp_f32_e32 v47, v47
	s_nop 0
	v_add_f32_e32 v47, 1.0, v47
	v_div_scale_f32 v48, s[22:23], v47, v47, v44
	v_rcp_f32_e32 v49, v48
	s_nop 0
	v_fma_f32 v55, -v48, v49, 1.0
	v_fmac_f32_e32 v49, v55, v49
	v_div_scale_f32 v55, vcc, v44, v47, v44
	v_mul_f32_e32 v56, v55, v49
	v_fma_f32 v57, -v48, v56, v55
	v_fmac_f32_e32 v56, v57, v49
	v_fma_f32 v48, -v48, v56, v55
	v_div_fmas_f32 v48, v48, v49, v56
	v_div_fixup_f32 v47, v48, v47, v44
	v_mul_f32_e32 v48, 0xbfb8aa3b, v45
	v_exp_f32_e32 v48, v48
	s_nop 0
	v_add_f32_e32 v48, 1.0, v48
	v_div_scale_f32 v49, s[22:23], v48, v48, v45
	v_rcp_f32_e32 v55, v49
	s_nop 0
	v_fma_f32 v56, -v49, v55, 1.0
	v_fmac_f32_e32 v55, v56, v55
	v_div_scale_f32 v56, vcc, v45, v48, v45
	v_mul_f32_e32 v57, v56, v55
	v_fma_f32 v58, -v49, v57, v56
	v_fmac_f32_e32 v57, v58, v55
	v_fma_f32 v49, -v49, v57, v56
	v_div_fmas_f32 v49, v49, v55, v57
	v_div_fixup_f32 v48, v49, v48, v45
	v_cvt_pk_bf16_f32 v47, v47, v48
	v_lshl_add_u64 v[48:49], s[30:31], 0, v[50:51]
	v_lshl_add_u64 v[48:49], v[130:131], 1, v[48:49]
	v_add_co_u32_e32 v48, vcc, 0xfffff000, v48
	s_nop 1
	v_addc_co_u32_e32 v49, vcc, -1, v49, vcc
	global_store_dwordx2 v[48:49], v[46:47], off offset:-256 sc1

.LBB0_344:
	v_cmp_gt_u32_e32 vcc, s39, v122
	s_and_saveexec_b64 s[78:79], vcc
	s_cbranch_execz .LBB0_346
	v_mul_f32_e32 v42, 0xbfb8aa3b, v38
	v_exp_f32_e32 v42, v42
	v_mov_b32_e32 v130, v122
	v_add_f32_e32 v42, 1.0, v42
	v_div_scale_f32 v43, s[22:23], v42, v42, v38
	v_rcp_f32_e32 v44, v43
	s_nop 0
	v_fma_f32 v45, -v43, v44, 1.0
	v_fmac_f32_e32 v44, v45, v44
	v_div_scale_f32 v45, vcc, v38, v42, v38
	v_mul_f32_e32 v46, v45, v44
	v_fma_f32 v47, -v43, v46, v45
	v_fmac_f32_e32 v46, v47, v44
	v_fma_f32 v43, -v43, v46, v45
	v_div_fmas_f32 v43, v43, v44, v46
	v_div_fixup_f32 v42, v43, v42, v38
	v_mul_f32_e32 v43, 0xbfb8aa3b, v39
	v_exp_f32_e32 v43, v43
	s_nop 0
	v_add_f32_e32 v43, 1.0, v43
	v_div_scale_f32 v44, s[22:23], v43, v43, v39
	v_rcp_f32_e32 v45, v44
	s_nop 0
	v_fma_f32 v46, -v44, v45, 1.0
	v_fmac_f32_e32 v45, v46, v45
	v_div_scale_f32 v46, vcc, v39, v43, v39
	v_mul_f32_e32 v47, v46, v45
	v_fma_f32 v48, -v44, v47, v46
	v_fmac_f32_e32 v47, v48, v45
	v_fma_f32 v44, -v44, v47, v46
	v_div_fmas_f32 v44, v44, v45, v47
	v_div_fixup_f32 v43, v44, v43, v39
	v_cvt_pk_bf16_f32 v42, v42, v43
	v_mul_f32_e32 v43, 0xbfb8aa3b, v40
	v_exp_f32_e32 v43, v43
	s_nop 0
	v_add_f32_e32 v43, 1.0, v43
	v_div_scale_f32 v44, s[22:23], v43, v43, v40
	v_rcp_f32_e32 v45, v44
	s_nop 0
	v_fma_f32 v46, -v44, v45, 1.0
	v_fmac_f32_e32 v45, v46, v45
	v_div_scale_f32 v46, vcc, v40, v43, v40
	v_mul_f32_e32 v47, v46, v45
	v_fma_f32 v48, -v44, v47, v46
	v_fmac_f32_e32 v47, v48, v45
	v_fma_f32 v44, -v44, v47, v46
	v_div_fmas_f32 v44, v44, v45, v47
	v_div_fixup_f32 v43, v44, v43, v40
	v_mul_f32_e32 v44, 0xbfb8aa3b, v41
	v_exp_f32_e32 v44, v44
	s_nop 0
	v_add_f32_e32 v44, 1.0, v44
	v_div_scale_f32 v45, s[22:23], v44, v44, v41
	v_rcp_f32_e32 v46, v45
	s_nop 0
	v_fma_f32 v47, -v45, v46, 1.0
	v_fmac_f32_e32 v46, v47, v46
	v_div_scale_f32 v47, vcc, v41, v44, v41
	v_mul_f32_e32 v48, v47, v46
	v_fma_f32 v49, -v45, v48, v47
	v_fmac_f32_e32 v48, v49, v46
	v_fma_f32 v45, -v45, v48, v47
	v_div_fmas_f32 v45, v45, v46, v48
	v_div_fixup_f32 v44, v45, v44, v41
	v_cvt_pk_bf16_f32 v43, v43, v44
	v_lshl_add_u64 v[44:45], s[30:31], 0, v[50:51]
	v_lshl_add_u64 v[44:45], v[130:131], 1, v[44:45]
	v_add_co_u32_e32 v44, vcc, 0xfffff000, v44
	s_nop 1
	v_addc_co_u32_e32 v45, vcc, -1, v45, vcc
	global_store_dwordx2 v[44:45], v[42:43], off offset:-256 sc1

.LBB0_348:
	v_cmp_gt_u32_e32 vcc, s39, v118
	s_and_saveexec_b64 s[78:79], vcc
	s_cbranch_execz .LBB0_350
	v_mul_f32_e32 v38, 0xbfb8aa3b, v34
	v_exp_f32_e32 v38, v38
	v_mov_b32_e32 v130, v118
	v_add_f32_e32 v38, 1.0, v38
	v_div_scale_f32 v39, s[22:23], v38, v38, v34
	v_rcp_f32_e32 v40, v39
	s_nop 0
	v_fma_f32 v41, -v39, v40, 1.0
	v_fmac_f32_e32 v40, v41, v40
	v_div_scale_f32 v41, vcc, v34, v38, v34
	v_mul_f32_e32 v42, v41, v40
	v_fma_f32 v43, -v39, v42, v41
	v_fmac_f32_e32 v42, v43, v40
	v_fma_f32 v39, -v39, v42, v41
	v_div_fmas_f32 v39, v39, v40, v42
	v_div_fixup_f32 v38, v39, v38, v34
	v_mul_f32_e32 v39, 0xbfb8aa3b, v35
	v_exp_f32_e32 v39, v39
	s_nop 0
	v_add_f32_e32 v39, 1.0, v39
	v_div_scale_f32 v40, s[22:23], v39, v39, v35
	v_rcp_f32_e32 v41, v40
	s_nop 0
	v_fma_f32 v42, -v40, v41, 1.0
	v_fmac_f32_e32 v41, v42, v41
	v_div_scale_f32 v42, vcc, v35, v39, v35
	v_mul_f32_e32 v43, v42, v41
	v_fma_f32 v44, -v40, v43, v42
	v_fmac_f32_e32 v43, v44, v41
	v_fma_f32 v40, -v40, v43, v42
	v_div_fmas_f32 v40, v40, v41, v43
	v_div_fixup_f32 v39, v40, v39, v35
	v_cvt_pk_bf16_f32 v38, v38, v39
	v_mul_f32_e32 v39, 0xbfb8aa3b, v36
	v_exp_f32_e32 v39, v39
	s_nop 0
	v_add_f32_e32 v39, 1.0, v39
	v_div_scale_f32 v40, s[22:23], v39, v39, v36
	v_rcp_f32_e32 v41, v40
	s_nop 0
	v_fma_f32 v42, -v40, v41, 1.0
	v_fmac_f32_e32 v41, v42, v41
	v_div_scale_f32 v42, vcc, v36, v39, v36
	v_mul_f32_e32 v43, v42, v41
	v_fma_f32 v44, -v40, v43, v42
	v_fmac_f32_e32 v43, v44, v41
	v_fma_f32 v40, -v40, v43, v42
	v_div_fmas_f32 v40, v40, v41, v43
	v_div_fixup_f32 v39, v40, v39, v36
	v_mul_f32_e32 v40, 0xbfb8aa3b, v37
	v_exp_f32_e32 v40, v40
	s_nop 0
	v_add_f32_e32 v40, 1.0, v40
	v_div_scale_f32 v41, s[22:23], v40, v40, v37
	v_rcp_f32_e32 v42, v41
	s_nop 0
	v_fma_f32 v43, -v41, v42, 1.0
	v_fmac_f32_e32 v42, v43, v42
	v_div_scale_f32 v43, vcc, v37, v40, v37
	v_mul_f32_e32 v44, v43, v42
	v_fma_f32 v45, -v41, v44, v43
	v_fmac_f32_e32 v44, v45, v42
	v_fma_f32 v41, -v41, v44, v43
	v_div_fmas_f32 v41, v41, v42, v44
	v_div_fixup_f32 v40, v41, v40, v37
	v_cvt_pk_bf16_f32 v39, v39, v40
	v_lshl_add_u64 v[40:41], s[30:31], 0, v[50:51]
	v_lshl_add_u64 v[40:41], v[130:131], 1, v[40:41]
	v_add_co_u32_e32 v40, vcc, 0xfffff000, v40
	s_nop 1
	v_addc_co_u32_e32 v41, vcc, -1, v41, vcc
	global_store_dwordx2 v[40:41], v[38:39], off offset:-256 sc1

.LBB0_351:
	v_cmp_gt_u32_e32 vcc, s91, v120
	v_lshl_add_u64 v[38:39], v[118:119], 2, v[52:53]
	s_and_b64 s[62:63], vcc, s[0:1]
	global_store_dwordx4 v[38:39], v[34:37], off sc1
	s_and_saveexec_b64 s[0:1], s[62:63]
	s_cbranch_execz .LBB0_353
	s_or_b32 s61, s13, s80
	v_cmp_gt_u32_e32 vcc, s40, v118
	v_lshl_or_b32 v40, s61, 8, v54
	v_ashrrev_i32_e32 v41, 31, v40
	v_cndmask_b32_e32 v130, v208, v209, vcc
	v_lshl_add_u64 v[38:39], s[16:17], 0, v[130:131]
	v_lshlrev_b64 v[40:41], 9, v[40:41]
	v_lshl_add_u64 v[38:39], v[38:39], 0, v[40:41]
	v_cndmask_b32_e32 v40, v210, v211, vcc
	v_add_u32_e32 v40, v40, v118
	v_ashrrev_i32_e32 v41, 31, v40
	v_lshl_add_u64 v[38:39], v[40:41], 2, v[38:39]
	global_store_dwordx4 v[38:39], v[34:37], off sc1

.LBB0_354:
	s_or_b64 exec, exec, s[22:23]
	v_or_b32_e32 v36, 32, v66
	v_ashrrev_i32_e32 v37, 31, v36
	v_lshlrev_b64 v[34:35], 11, v[36:37]
	v_cmp_gt_i32_e64 s[0:1], s37, v36
	s_and_saveexec_b64 s[22:23], s[10:11]
	s_xor_b64 s[70:71], exec, s[22:23]
	s_cbranch_execz .LBB0_358
	v_cmp_gt_u32_e32 vcc, s39, v146
	s_and_saveexec_b64 s[78:79], vcc
	s_cbranch_execz .LBB0_357
	v_mul_f32_e32 v37, 0xbfb8aa3b, v30
	v_exp_f32_e32 v37, v37
	v_mov_b32_e32 v130, v146
	v_add_f32_e32 v37, 1.0, v37
	v_div_scale_f32 v38, s[22:23], v37, v37, v30
	v_rcp_f32_e32 v39, v38
	s_nop 0
	v_fma_f32 v40, -v38, v39, 1.0
	v_fmac_f32_e32 v39, v40, v39
	v_div_scale_f32 v40, vcc, v30, v37, v30
	v_mul_f32_e32 v41, v40, v39
	v_fma_f32 v42, -v38, v41, v40
	v_fmac_f32_e32 v41, v42, v39
	v_fma_f32 v38, -v38, v41, v40
	v_div_fmas_f32 v38, v38, v39, v41
	v_div_fixup_f32 v37, v38, v37, v30
	v_mul_f32_e32 v38, 0xbfb8aa3b, v31
	v_exp_f32_e32 v38, v38
	s_nop 0
	v_add_f32_e32 v38, 1.0, v38
	v_div_scale_f32 v39, s[22:23], v38, v38, v31
	v_rcp_f32_e32 v40, v39
	s_nop 0
	v_fma_f32 v41, -v39, v40, 1.0
	v_fmac_f32_e32 v40, v41, v40
	v_div_scale_f32 v41, vcc, v31, v38, v31
	v_mul_f32_e32 v42, v41, v40
	v_fma_f32 v43, -v39, v42, v41
	v_fmac_f32_e32 v42, v43, v40
	v_fma_f32 v39, -v39, v42, v41
	v_div_fmas_f32 v39, v39, v40, v42
	v_div_fixup_f32 v38, v39, v38, v31
	v_cvt_pk_bf16_f32 v38, v37, v38
	v_mul_f32_e32 v37, 0xbfb8aa3b, v32
	v_exp_f32_e32 v37, v37
	s_nop 0
	v_add_f32_e32 v37, 1.0, v37
	v_div_scale_f32 v39, s[22:23], v37, v37, v32
	v_rcp_f32_e32 v40, v39
	s_nop 0
	v_fma_f32 v41, -v39, v40, 1.0
	v_fmac_f32_e32 v40, v41, v40
	v_div_scale_f32 v41, vcc, v32, v37, v32
	v_mul_f32_e32 v42, v41, v40
	v_fma_f32 v43, -v39, v42, v41
	v_fmac_f32_e32 v42, v43, v40
	v_fma_f32 v39, -v39, v42, v41
	v_div_fmas_f32 v39, v39, v40, v42
	v_div_fixup_f32 v37, v39, v37, v32
	v_mul_f32_e32 v39, 0xbfb8aa3b, v33
	v_exp_f32_e32 v39, v39
	s_nop 0
	v_add_f32_e32 v39, 1.0, v39
	v_div_scale_f32 v40, s[22:23], v39, v39, v33
	v_rcp_f32_e32 v41, v40
	s_nop 0
	v_fma_f32 v42, -v40, v41, 1.0
	v_fmac_f32_e32 v41, v42, v41
	v_div_scale_f32 v42, vcc, v33, v39, v33
	v_mul_f32_e32 v43, v42, v41
	v_fma_f32 v44, -v40, v43, v42
	v_fmac_f32_e32 v43, v44, v41
	v_fma_f32 v40, -v40, v43, v42
	v_div_fmas_f32 v40, v40, v41, v43
	v_div_fixup_f32 v39, v40, v39, v33
	v_lshl_add_u64 v[40:41], s[30:31], 0, v[34:35]
	v_lshl_add_u64 v[40:41], v[130:131], 1, v[40:41]
	v_add_co_u32_e32 v40, vcc, 0xfffff000, v40
	v_cvt_pk_bf16_f32 v39, v37, v39
	s_nop 1
	v_addc_co_u32_e32 v41, vcc, -1, v41, vcc
	global_store_dwordx2 v[40:41], v[38:39], off offset:-256 sc1

.LBB0_358:
	s_or_saveexec_b64 s[22:23], s[70:71]
	v_mad_i64_i32 v[36:37], s[62:63], v36, s36, 0
	v_bitop3_b32 v38, v66, s43, 32 bitop3:0xc8
	v_lshl_add_u64 v[36:37], s[28:29], 0, v[36:37]
	s_xor_b64 exec, exec, s[22:23]
	s_cbranch_execz .LBB0_371
	v_cmp_gt_u32_e32 vcc, s91, v149
	v_lshl_add_u64 v[40:41], v[146:147], 2, v[36:37]
	s_and_b64 s[62:63], vcc, s[0:1]
	global_store_dwordx4 v[40:41], v[30:33], off sc1
	s_and_saveexec_b64 s[70:71], s[62:63]
	s_cbranch_execz .LBB0_361
	s_or_b32 s61, s13, s80
	v_cmp_gt_u32_e32 vcc, s40, v146
	v_lshl_or_b32 v42, s61, 8, v38
	v_ashrrev_i32_e32 v43, 31, v42
	v_cndmask_b32_e32 v130, v208, v209, vcc
	v_lshl_add_u64 v[40:41], s[16:17], 0, v[130:131]
	v_lshlrev_b64 v[42:43], 9, v[42:43]
	v_cndmask_b32_e32 v39, v210, v211, vcc
	v_lshl_add_u64 v[40:41], v[40:41], 0, v[42:43]
	v_add_u32_e32 v42, v39, v146
	v_ashrrev_i32_e32 v43, 31, v42
	v_lshl_add_u64 v[40:41], v[42:43], 2, v[40:41]
	global_store_dwordx4 v[40:41], v[30:33], off sc1

.LBB0_363:
	v_cmp_gt_u32_e32 vcc, s91, v128
	v_lshl_add_u64 v[30:31], v[126:127], 2, v[36:37]
	s_and_b64 s[62:63], vcc, s[0:1]
	global_store_dwordx4 v[30:31], v[26:29], off sc1
	s_and_saveexec_b64 s[70:71], s[62:63]
	s_cbranch_execz .LBB0_365
	s_or_b32 s61, s13, s80
	v_cmp_gt_u32_e32 vcc, s40, v126
	v_lshl_or_b32 v32, s61, 8, v38
	v_ashrrev_i32_e32 v33, 31, v32
	v_cndmask_b32_e32 v130, v208, v209, vcc
	v_lshl_add_u64 v[30:31], s[16:17], 0, v[130:131]
	v_lshlrev_b64 v[32:33], 9, v[32:33]
	v_lshl_add_u64 v[30:31], v[30:31], 0, v[32:33]
	v_cndmask_b32_e32 v32, v210, v211, vcc
	v_add_u32_e32 v32, v32, v126
	v_ashrrev_i32_e32 v33, 31, v32
	v_lshl_add_u64 v[30:31], v[32:33], 2, v[30:31]
	global_store_dwordx4 v[30:31], v[26:29], off sc1

.LBB0_367:
	v_cmp_gt_u32_e32 vcc, s91, v124
	v_lshl_add_u64 v[26:27], v[122:123], 2, v[36:37]
	s_and_b64 s[62:63], vcc, s[0:1]
	global_store_dwordx4 v[26:27], v[22:25], off sc1
	s_and_saveexec_b64 s[70:71], s[62:63]
	s_cbranch_execz .LBB0_369
	s_or_b32 s61, s13, s80
	v_cmp_gt_u32_e32 vcc, s40, v122
	v_lshl_or_b32 v28, s61, 8, v38
	v_ashrrev_i32_e32 v29, 31, v28
	v_cndmask_b32_e32 v130, v208, v209, vcc
	v_lshl_add_u64 v[26:27], s[16:17], 0, v[130:131]
	v_lshlrev_b64 v[28:29], 9, v[28:29]
	v_lshl_add_u64 v[26:27], v[26:27], 0, v[28:29]
	v_cndmask_b32_e32 v28, v210, v211, vcc
	v_add_u32_e32 v28, v28, v122
	v_ashrrev_i32_e32 v29, 31, v28
	v_lshl_add_u64 v[26:27], v[28:29], 2, v[26:27]
	global_store_dwordx4 v[26:27], v[22:25], off sc1

.LBB0_372:
	v_cmp_gt_u32_e32 vcc, s39, v126
	s_and_saveexec_b64 s[78:79], vcc
	s_cbranch_execz .LBB0_374
	v_mul_f32_e32 v30, 0xbfb8aa3b, v26
	v_exp_f32_e32 v30, v30
	v_mov_b32_e32 v130, v126
	v_add_f32_e32 v30, 1.0, v30
	v_div_scale_f32 v31, s[22:23], v30, v30, v26
	v_rcp_f32_e32 v32, v31
	s_nop 0
	v_fma_f32 v33, -v31, v32, 1.0
	v_fmac_f32_e32 v32, v33, v32
	v_div_scale_f32 v33, vcc, v26, v30, v26
	v_mul_f32_e32 v39, v33, v32
	v_fma_f32 v40, -v31, v39, v33
	v_fmac_f32_e32 v39, v40, v32
	v_fma_f32 v31, -v31, v39, v33
	v_div_fmas_f32 v31, v31, v32, v39
	v_div_fixup_f32 v30, v31, v30, v26
	v_mul_f32_e32 v31, 0xbfb8aa3b, v27
	v_exp_f32_e32 v31, v31
	s_nop 0
	v_add_f32_e32 v31, 1.0, v31
	v_div_scale_f32 v32, s[22:23], v31, v31, v27
	v_rcp_f32_e32 v33, v32
	s_nop 0
	v_fma_f32 v39, -v32, v33, 1.0
	v_fmac_f32_e32 v33, v39, v33
	v_div_scale_f32 v39, vcc, v27, v31, v27
	v_mul_f32_e32 v40, v39, v33
	v_fma_f32 v41, -v32, v40, v39
	v_fmac_f32_e32 v40, v41, v33
	v_fma_f32 v32, -v32, v40, v39
	v_div_fmas_f32 v32, v32, v33, v40
	v_div_fixup_f32 v31, v32, v31, v27
	v_cvt_pk_bf16_f32 v30, v30, v31
	v_mul_f32_e32 v31, 0xbfb8aa3b, v28
	v_exp_f32_e32 v31, v31
	s_nop 0
	v_add_f32_e32 v31, 1.0, v31
	v_div_scale_f32 v32, s[22:23], v31, v31, v28
	v_rcp_f32_e32 v33, v32
	s_nop 0
	v_fma_f32 v39, -v32, v33, 1.0
	v_fmac_f32_e32 v33, v39, v33
	v_div_scale_f32 v39, vcc, v28, v31, v28
	v_mul_f32_e32 v40, v39, v33
	v_fma_f32 v41, -v32, v40, v39
	v_fmac_f32_e32 v40, v41, v33
	v_fma_f32 v32, -v32, v40, v39
	v_div_fmas_f32 v32, v32, v33, v40
	v_div_fixup_f32 v31, v32, v31, v28
	v_mul_f32_e32 v32, 0xbfb8aa3b, v29
	v_exp_f32_e32 v32, v32
	s_nop 0
	v_add_f32_e32 v32, 1.0, v32
	v_div_scale_f32 v33, s[22:23], v32, v32, v29
	v_rcp_f32_e32 v39, v33
	s_nop 0
	v_fma_f32 v40, -v33, v39, 1.0
	v_fmac_f32_e32 v39, v40, v39
	v_div_scale_f32 v40, vcc, v29, v32, v29
	v_mul_f32_e32 v41, v40, v39
	v_fma_f32 v42, -v33, v41, v40
	v_fmac_f32_e32 v41, v42, v39
	v_fma_f32 v33, -v33, v41, v40
	v_div_fmas_f32 v33, v33, v39, v41
	v_div_fixup_f32 v32, v33, v32, v29
	v_cvt_pk_bf16_f32 v31, v31, v32
	v_lshl_add_u64 v[32:33], s[30:31], 0, v[34:35]
	v_lshl_add_u64 v[32:33], v[130:131], 1, v[32:33]
	v_add_co_u32_e32 v32, vcc, 0xfffff000, v32
	s_nop 1
	v_addc_co_u32_e32 v33, vcc, -1, v33, vcc
	global_store_dwordx2 v[32:33], v[30:31], off offset:-256 sc1

.LBB0_376:
	v_cmp_gt_u32_e32 vcc, s39, v122
	s_and_saveexec_b64 s[78:79], vcc
	s_cbranch_execz .LBB0_378
	v_mul_f32_e32 v26, 0xbfb8aa3b, v22
	v_exp_f32_e32 v26, v26
	v_mov_b32_e32 v130, v122
	v_add_f32_e32 v26, 1.0, v26
	v_div_scale_f32 v27, s[22:23], v26, v26, v22
	v_rcp_f32_e32 v28, v27
	s_nop 0
	v_fma_f32 v29, -v27, v28, 1.0
	v_fmac_f32_e32 v28, v29, v28
	v_div_scale_f32 v29, vcc, v22, v26, v22
	v_mul_f32_e32 v30, v29, v28
	v_fma_f32 v31, -v27, v30, v29
	v_fmac_f32_e32 v30, v31, v28
	v_fma_f32 v27, -v27, v30, v29
	v_div_fmas_f32 v27, v27, v28, v30
	v_div_fixup_f32 v26, v27, v26, v22
	v_mul_f32_e32 v27, 0xbfb8aa3b, v23
	v_exp_f32_e32 v27, v27
	s_nop 0
	v_add_f32_e32 v27, 1.0, v27
	v_div_scale_f32 v28, s[22:23], v27, v27, v23
	v_rcp_f32_e32 v29, v28
	s_nop 0
	v_fma_f32 v30, -v28, v29, 1.0
	v_fmac_f32_e32 v29, v30, v29
	v_div_scale_f32 v30, vcc, v23, v27, v23
	v_mul_f32_e32 v31, v30, v29
	v_fma_f32 v32, -v28, v31, v30
	v_fmac_f32_e32 v31, v32, v29
	v_fma_f32 v28, -v28, v31, v30
	v_div_fmas_f32 v28, v28, v29, v31
	v_div_fixup_f32 v27, v28, v27, v23
	v_cvt_pk_bf16_f32 v26, v26, v27
	v_mul_f32_e32 v27, 0xbfb8aa3b, v24
	v_exp_f32_e32 v27, v27
	s_nop 0
	v_add_f32_e32 v27, 1.0, v27
	v_div_scale_f32 v28, s[22:23], v27, v27, v24
	v_rcp_f32_e32 v29, v28
	s_nop 0
	v_fma_f32 v30, -v28, v29, 1.0
	v_fmac_f32_e32 v29, v30, v29
	v_div_scale_f32 v30, vcc, v24, v27, v24
	v_mul_f32_e32 v31, v30, v29
	v_fma_f32 v32, -v28, v31, v30
	v_fmac_f32_e32 v31, v32, v29
	v_fma_f32 v28, -v28, v31, v30
	v_div_fmas_f32 v28, v28, v29, v31
	v_div_fixup_f32 v27, v28, v27, v24
	v_mul_f32_e32 v28, 0xbfb8aa3b, v25
	v_exp_f32_e32 v28, v28
	s_nop 0
	v_add_f32_e32 v28, 1.0, v28
	v_div_scale_f32 v29, s[22:23], v28, v28, v25
	v_rcp_f32_e32 v30, v29
	s_nop 0
	v_fma_f32 v31, -v29, v30, 1.0
	v_fmac_f32_e32 v30, v31, v30
	v_div_scale_f32 v31, vcc, v25, v28, v25
	v_mul_f32_e32 v32, v31, v30
	v_fma_f32 v33, -v29, v32, v31
	v_fmac_f32_e32 v32, v33, v30
	v_fma_f32 v29, -v29, v32, v31
	v_div_fmas_f32 v29, v29, v30, v32
	v_div_fixup_f32 v28, v29, v28, v25
	v_cvt_pk_bf16_f32 v27, v27, v28
	v_lshl_add_u64 v[28:29], s[30:31], 0, v[34:35]
	v_lshl_add_u64 v[28:29], v[130:131], 1, v[28:29]
	v_add_co_u32_e32 v28, vcc, 0xfffff000, v28
	s_nop 1
	v_addc_co_u32_e32 v29, vcc, -1, v29, vcc
	global_store_dwordx2 v[28:29], v[26:27], off offset:-256 sc1

.LBB0_380:
	v_cmp_gt_u32_e32 vcc, s39, v118
	s_and_saveexec_b64 s[78:79], vcc
	s_cbranch_execz .LBB0_382
	v_mul_f32_e32 v22, 0xbfb8aa3b, v18
	v_exp_f32_e32 v22, v22
	v_mov_b32_e32 v130, v118
	v_add_f32_e32 v22, 1.0, v22
	v_div_scale_f32 v23, s[22:23], v22, v22, v18
	v_rcp_f32_e32 v24, v23
	s_nop 0
	v_fma_f32 v25, -v23, v24, 1.0
	v_fmac_f32_e32 v24, v25, v24
	v_div_scale_f32 v25, vcc, v18, v22, v18
	v_mul_f32_e32 v26, v25, v24
	v_fma_f32 v27, -v23, v26, v25
	v_fmac_f32_e32 v26, v27, v24
	v_fma_f32 v23, -v23, v26, v25
	v_div_fmas_f32 v23, v23, v24, v26
	v_div_fixup_f32 v22, v23, v22, v18
	v_mul_f32_e32 v23, 0xbfb8aa3b, v19
	v_exp_f32_e32 v23, v23
	s_nop 0
	v_add_f32_e32 v23, 1.0, v23
	v_div_scale_f32 v24, s[22:23], v23, v23, v19
	v_rcp_f32_e32 v25, v24
	s_nop 0
	v_fma_f32 v26, -v24, v25, 1.0
	v_fmac_f32_e32 v25, v26, v25
	v_div_scale_f32 v26, vcc, v19, v23, v19
	v_mul_f32_e32 v27, v26, v25
	v_fma_f32 v28, -v24, v27, v26
	v_fmac_f32_e32 v27, v28, v25
	v_fma_f32 v24, -v24, v27, v26
	v_div_fmas_f32 v24, v24, v25, v27
	v_div_fixup_f32 v23, v24, v23, v19
	v_cvt_pk_bf16_f32 v22, v22, v23
	v_mul_f32_e32 v23, 0xbfb8aa3b, v20
	v_exp_f32_e32 v23, v23
	s_nop 0
	v_add_f32_e32 v23, 1.0, v23
	v_div_scale_f32 v24, s[22:23], v23, v23, v20
	v_rcp_f32_e32 v25, v24
	s_nop 0
	v_fma_f32 v26, -v24, v25, 1.0
	v_fmac_f32_e32 v25, v26, v25
	v_div_scale_f32 v26, vcc, v20, v23, v20
	v_mul_f32_e32 v27, v26, v25
	v_fma_f32 v28, -v24, v27, v26
	v_fmac_f32_e32 v27, v28, v25
	v_fma_f32 v24, -v24, v27, v26
	v_div_fmas_f32 v24, v24, v25, v27
	v_div_fixup_f32 v23, v24, v23, v20
	v_mul_f32_e32 v24, 0xbfb8aa3b, v21
	v_exp_f32_e32 v24, v24
	s_nop 0
	v_add_f32_e32 v24, 1.0, v24
	v_div_scale_f32 v25, s[22:23], v24, v24, v21
	v_rcp_f32_e32 v26, v25
	s_nop 0
	v_fma_f32 v27, -v25, v26, 1.0
	v_fmac_f32_e32 v26, v27, v26
	v_div_scale_f32 v27, vcc, v21, v24, v21
	v_mul_f32_e32 v28, v27, v26
	v_fma_f32 v29, -v25, v28, v27
	v_fmac_f32_e32 v28, v29, v26
	v_fma_f32 v25, -v25, v28, v27
	v_div_fmas_f32 v25, v25, v26, v28
	v_div_fixup_f32 v24, v25, v24, v21
	v_cvt_pk_bf16_f32 v23, v23, v24
	v_lshl_add_u64 v[24:25], s[30:31], 0, v[34:35]
	v_lshl_add_u64 v[24:25], v[130:131], 1, v[24:25]
	v_add_co_u32_e32 v24, vcc, 0xfffff000, v24
	s_nop 1
	v_addc_co_u32_e32 v25, vcc, -1, v25, vcc
	global_store_dwordx2 v[24:25], v[22:23], off offset:-256 sc1

.LBB0_383:
	v_cmp_gt_u32_e32 vcc, s91, v120
	v_lshl_add_u64 v[22:23], v[118:119], 2, v[36:37]
	s_and_b64 s[62:63], vcc, s[0:1]
	global_store_dwordx4 v[22:23], v[18:21], off sc1
	s_and_saveexec_b64 s[0:1], s[62:63]
	s_cbranch_execz .LBB0_385
	s_or_b32 s61, s13, s80
	v_cmp_gt_u32_e32 vcc, s40, v118
	v_lshl_or_b32 v24, s61, 8, v38
	v_ashrrev_i32_e32 v25, 31, v24
	v_cndmask_b32_e32 v130, v208, v209, vcc
	v_lshl_add_u64 v[22:23], s[16:17], 0, v[130:131]
	v_lshlrev_b64 v[24:25], 9, v[24:25]
	v_lshl_add_u64 v[22:23], v[22:23], 0, v[24:25]
	v_cndmask_b32_e32 v24, v210, v211, vcc
	v_add_u32_e32 v24, v24, v118
	v_ashrrev_i32_e32 v25, 31, v24
	v_lshl_add_u64 v[22:23], v[24:25], 2, v[22:23]
	global_store_dwordx4 v[22:23], v[18:21], off sc1

.LBB0_386:
	s_or_b64 exec, exec, s[22:23]
	v_or_b32_e32 v20, 48, v66
	v_ashrrev_i32_e32 v21, 31, v20
	v_lshlrev_b64 v[18:19], 11, v[20:21]
	v_cmp_gt_i32_e64 s[0:1], s37, v20
	s_and_saveexec_b64 s[22:23], s[10:11]
	s_xor_b64 s[10:11], exec, s[22:23]
	s_cbranch_execz .LBB0_390
	v_cmp_gt_u32_e32 vcc, s39, v146
	s_and_saveexec_b64 s[70:71], vcc
	s_cbranch_execz .LBB0_389
	v_mul_f32_e32 v21, 0xbfb8aa3b, v14
	v_exp_f32_e32 v21, v21
	v_mov_b32_e32 v147, v131
	v_add_f32_e32 v21, 1.0, v21
	v_div_scale_f32 v22, s[22:23], v21, v21, v14
	v_rcp_f32_e32 v23, v22
	s_nop 0
	v_fma_f32 v24, -v22, v23, 1.0
	v_fmac_f32_e32 v23, v24, v23
	v_div_scale_f32 v24, vcc, v14, v21, v14
	v_mul_f32_e32 v25, v24, v23
	v_fma_f32 v26, -v22, v25, v24
	v_fmac_f32_e32 v25, v26, v23
	v_fma_f32 v22, -v22, v25, v24
	v_div_fmas_f32 v22, v22, v23, v25
	v_div_fixup_f32 v21, v22, v21, v14
	v_mul_f32_e32 v22, 0xbfb8aa3b, v15
	v_exp_f32_e32 v22, v22
	s_nop 0
	v_add_f32_e32 v22, 1.0, v22
	v_div_scale_f32 v23, s[22:23], v22, v22, v15
	v_rcp_f32_e32 v24, v23
	s_nop 0
	v_fma_f32 v25, -v23, v24, 1.0
	v_fmac_f32_e32 v24, v25, v24
	v_div_scale_f32 v25, vcc, v15, v22, v15
	v_mul_f32_e32 v26, v25, v24
	v_fma_f32 v27, -v23, v26, v25
	v_fmac_f32_e32 v26, v27, v24
	v_fma_f32 v23, -v23, v26, v25
	v_div_fmas_f32 v23, v23, v24, v26
	v_div_fixup_f32 v22, v23, v22, v15
	v_cvt_pk_bf16_f32 v22, v21, v22
	v_mul_f32_e32 v21, 0xbfb8aa3b, v16
	v_exp_f32_e32 v21, v21
	s_nop 0
	v_add_f32_e32 v21, 1.0, v21
	v_div_scale_f32 v23, s[22:23], v21, v21, v16
	v_rcp_f32_e32 v24, v23
	s_nop 0
	v_fma_f32 v25, -v23, v24, 1.0
	v_fmac_f32_e32 v24, v25, v24
	v_div_scale_f32 v25, vcc, v16, v21, v16
	v_mul_f32_e32 v26, v25, v24
	v_fma_f32 v27, -v23, v26, v25
	v_fmac_f32_e32 v26, v27, v24
	v_fma_f32 v23, -v23, v26, v25
	v_div_fmas_f32 v23, v23, v24, v26
	v_div_fixup_f32 v21, v23, v21, v16
	v_mul_f32_e32 v23, 0xbfb8aa3b, v17
	v_exp_f32_e32 v23, v23
	s_nop 0
	v_add_f32_e32 v23, 1.0, v23
	v_div_scale_f32 v24, s[22:23], v23, v23, v17
	v_rcp_f32_e32 v25, v24
	s_nop 0
	v_fma_f32 v26, -v24, v25, 1.0
	v_fmac_f32_e32 v25, v26, v25
	v_div_scale_f32 v26, vcc, v17, v23, v17
	v_mul_f32_e32 v27, v26, v25
	v_fma_f32 v28, -v24, v27, v26
	v_fmac_f32_e32 v27, v28, v25
	v_fma_f32 v24, -v24, v27, v26
	v_div_fmas_f32 v24, v24, v25, v27
	v_div_fixup_f32 v23, v24, v23, v17
	v_lshl_add_u64 v[24:25], s[30:31], 0, v[18:19]
	v_lshl_add_u64 v[24:25], v[146:147], 1, v[24:25]
	v_add_co_u32_e32 v24, vcc, 0xfffff000, v24
	v_cvt_pk_bf16_f32 v23, v21, v23
	s_nop 1
	v_addc_co_u32_e32 v25, vcc, -1, v25, vcc
	global_store_dwordx2 v[24:25], v[22:23], off offset:-256 sc1

.LBB0_390:
	s_or_saveexec_b64 s[10:11], s[10:11]
	v_mad_i64_i32 v[20:21], s[22:23], v20, s36, 0
	v_bitop3_b32 v22, v66, s90, 48 bitop3:0xc8
	v_lshl_add_u64 v[20:21], s[28:29], 0, v[20:21]
	s_xor_b64 exec, exec, s[10:11]
	s_cbranch_execz .LBB0_403
	v_cmp_gt_u32_e32 vcc, s91, v149
	v_lshl_add_u64 v[24:25], v[146:147], 2, v[20:21]
	s_and_b64 s[62:63], vcc, s[0:1]
	global_store_dwordx4 v[24:25], v[14:17], off sc1
	s_and_saveexec_b64 s[22:23], s[62:63]
	s_cbranch_execz .LBB0_393
	s_or_b32 s61, s13, s80
	v_cmp_gt_u32_e32 vcc, s40, v146
	v_lshl_or_b32 v26, s61, 8, v22
	v_ashrrev_i32_e32 v27, 31, v26
	v_cndmask_b32_e32 v130, v208, v209, vcc
	v_lshl_add_u64 v[24:25], s[16:17], 0, v[130:131]
	v_lshlrev_b64 v[26:27], 9, v[26:27]
	v_cndmask_b32_e32 v23, v210, v211, vcc
	v_lshl_add_u64 v[24:25], v[24:25], 0, v[26:27]
	v_add_u32_e32 v26, v23, v146
	v_ashrrev_i32_e32 v27, 31, v26
	v_lshl_add_u64 v[24:25], v[26:27], 2, v[24:25]
	global_store_dwordx4 v[24:25], v[14:17], off sc1

.LBB0_395:
	v_cmp_gt_u32_e32 vcc, s91, v128
	v_lshl_add_u64 v[14:15], v[126:127], 2, v[20:21]
	s_and_b64 s[22:23], vcc, s[0:1]
	global_store_dwordx4 v[14:15], v[10:13], off sc1
	s_and_saveexec_b64 s[10:11], s[22:23]
	s_cbranch_execz .LBB0_397
	s_or_b32 s22, s13, s80
	v_cmp_gt_u32_e32 vcc, s40, v126
	v_lshl_or_b32 v16, s22, 8, v22
	v_ashrrev_i32_e32 v17, 31, v16
	v_cndmask_b32_e32 v130, v208, v209, vcc
	v_lshl_add_u64 v[14:15], s[16:17], 0, v[130:131]
	v_lshlrev_b64 v[16:17], 9, v[16:17]
	v_lshl_add_u64 v[14:15], v[14:15], 0, v[16:17]
	v_cndmask_b32_e32 v16, v210, v211, vcc
	v_add_u32_e32 v16, v16, v126
	v_ashrrev_i32_e32 v17, 31, v16
	v_lshl_add_u64 v[14:15], v[16:17], 2, v[14:15]
	global_store_dwordx4 v[14:15], v[10:13], off sc1

.LBB0_399:
	v_cmp_gt_u32_e32 vcc, s91, v124
	v_lshl_add_u64 v[10:11], v[122:123], 2, v[20:21]
	s_and_b64 s[10:11], vcc, s[0:1]
	global_store_dwordx4 v[10:11], v[6:9], off sc1
	s_and_saveexec_b64 s[8:9], s[10:11]
	s_cbranch_execz .LBB0_401
	s_or_b32 s10, s13, s80
	v_cmp_gt_u32_e32 vcc, s40, v122
	v_lshl_or_b32 v12, s10, 8, v22
	v_ashrrev_i32_e32 v13, 31, v12
	v_cndmask_b32_e32 v130, v208, v209, vcc
	v_lshl_add_u64 v[10:11], s[16:17], 0, v[130:131]
	v_lshlrev_b64 v[12:13], 9, v[12:13]
	v_lshl_add_u64 v[10:11], v[10:11], 0, v[12:13]
	v_cndmask_b32_e32 v12, v210, v211, vcc
	v_add_u32_e32 v12, v12, v122
	v_ashrrev_i32_e32 v13, 31, v12
	v_lshl_add_u64 v[10:11], v[12:13], 2, v[10:11]
	global_store_dwordx4 v[10:11], v[6:9], off sc1

.LBB0_404:
	v_cmp_gt_u32_e32 vcc, s39, v126
	s_and_saveexec_b64 s[10:11], vcc
	s_cbranch_execz .LBB0_406
	v_mul_f32_e32 v14, 0xbfb8aa3b, v10
	v_exp_f32_e32 v14, v14
	v_mov_b32_e32 v127, v131
	v_add_f32_e32 v14, 1.0, v14
	v_div_scale_f32 v15, s[22:23], v14, v14, v10
	v_rcp_f32_e32 v16, v15
	s_nop 0
	v_fma_f32 v17, -v15, v16, 1.0
	v_fmac_f32_e32 v16, v17, v16
	v_div_scale_f32 v17, vcc, v10, v14, v10
	v_mul_f32_e32 v23, v17, v16
	v_fma_f32 v24, -v15, v23, v17
	v_fmac_f32_e32 v23, v24, v16
	v_fma_f32 v15, -v15, v23, v17
	v_div_fmas_f32 v15, v15, v16, v23
	v_div_fixup_f32 v14, v15, v14, v10
	v_mul_f32_e32 v15, 0xbfb8aa3b, v11
	v_exp_f32_e32 v15, v15
	s_nop 0
	v_add_f32_e32 v15, 1.0, v15
	v_div_scale_f32 v16, s[22:23], v15, v15, v11
	v_rcp_f32_e32 v17, v16
	s_nop 0
	v_fma_f32 v23, -v16, v17, 1.0
	v_fmac_f32_e32 v17, v23, v17
	v_div_scale_f32 v23, vcc, v11, v15, v11
	v_mul_f32_e32 v24, v23, v17
	v_fma_f32 v25, -v16, v24, v23
	v_fmac_f32_e32 v24, v25, v17
	v_fma_f32 v16, -v16, v24, v23
	v_div_fmas_f32 v16, v16, v17, v24
	v_div_fixup_f32 v15, v16, v15, v11
	v_cvt_pk_bf16_f32 v14, v14, v15
	v_mul_f32_e32 v15, 0xbfb8aa3b, v12
	v_exp_f32_e32 v15, v15
	s_nop 0
	v_add_f32_e32 v15, 1.0, v15
	v_div_scale_f32 v16, s[22:23], v15, v15, v12
	v_rcp_f32_e32 v17, v16
	s_nop 0
	v_fma_f32 v23, -v16, v17, 1.0
	v_fmac_f32_e32 v17, v23, v17
	v_div_scale_f32 v23, vcc, v12, v15, v12
	v_mul_f32_e32 v24, v23, v17
	v_fma_f32 v25, -v16, v24, v23
	v_fmac_f32_e32 v24, v25, v17
	v_fma_f32 v16, -v16, v24, v23
	v_div_fmas_f32 v16, v16, v17, v24
	v_div_fixup_f32 v15, v16, v15, v12
	v_mul_f32_e32 v16, 0xbfb8aa3b, v13
	v_exp_f32_e32 v16, v16
	s_nop 0
	v_add_f32_e32 v16, 1.0, v16
	v_div_scale_f32 v17, s[22:23], v16, v16, v13
	v_rcp_f32_e32 v23, v17
	s_nop 0
	v_fma_f32 v24, -v17, v23, 1.0
	v_fmac_f32_e32 v23, v24, v23
	v_div_scale_f32 v24, vcc, v13, v16, v13
	v_mul_f32_e32 v25, v24, v23
	v_fma_f32 v26, -v17, v25, v24
	v_fmac_f32_e32 v25, v26, v23
	v_fma_f32 v17, -v17, v25, v24
	v_div_fmas_f32 v17, v17, v23, v25
	v_div_fixup_f32 v16, v17, v16, v13
	v_cvt_pk_bf16_f32 v15, v15, v16
	v_lshl_add_u64 v[16:17], s[30:31], 0, v[18:19]
	v_lshl_add_u64 v[16:17], v[126:127], 1, v[16:17]
	v_add_co_u32_e32 v16, vcc, 0xfffff000, v16
	s_nop 1
	v_addc_co_u32_e32 v17, vcc, -1, v17, vcc
	global_store_dwordx2 v[16:17], v[14:15], off offset:-256 sc1

.LBB0_408:
	v_cmp_gt_u32_e32 vcc, s39, v122
	s_and_saveexec_b64 s[8:9], vcc
	s_cbranch_execz .LBB0_410
	v_mul_f32_e32 v10, 0xbfb8aa3b, v6
	v_exp_f32_e32 v10, v10
	v_mov_b32_e32 v123, v131
	v_add_f32_e32 v10, 1.0, v10
	v_div_scale_f32 v11, s[10:11], v10, v10, v6
	v_rcp_f32_e32 v12, v11
	s_nop 0
	v_fma_f32 v13, -v11, v12, 1.0
	v_fmac_f32_e32 v12, v13, v12
	v_div_scale_f32 v13, vcc, v6, v10, v6
	v_mul_f32_e32 v14, v13, v12
	v_fma_f32 v15, -v11, v14, v13
	v_fmac_f32_e32 v14, v15, v12
	v_fma_f32 v11, -v11, v14, v13
	v_div_fmas_f32 v11, v11, v12, v14
	v_div_fixup_f32 v10, v11, v10, v6
	v_mul_f32_e32 v11, 0xbfb8aa3b, v7
	v_exp_f32_e32 v11, v11
	s_nop 0
	v_add_f32_e32 v11, 1.0, v11
	v_div_scale_f32 v12, s[10:11], v11, v11, v7
	v_rcp_f32_e32 v13, v12
	s_nop 0
	v_fma_f32 v14, -v12, v13, 1.0
	v_fmac_f32_e32 v13, v14, v13
	v_div_scale_f32 v14, vcc, v7, v11, v7
	v_mul_f32_e32 v15, v14, v13
	v_fma_f32 v16, -v12, v15, v14
	v_fmac_f32_e32 v15, v16, v13
	v_fma_f32 v12, -v12, v15, v14
	v_div_fmas_f32 v12, v12, v13, v15
	v_div_fixup_f32 v11, v12, v11, v7
	v_cvt_pk_bf16_f32 v10, v10, v11
	v_mul_f32_e32 v11, 0xbfb8aa3b, v8
	v_exp_f32_e32 v11, v11
	s_nop 0
	v_add_f32_e32 v11, 1.0, v11
	v_div_scale_f32 v12, s[10:11], v11, v11, v8
	v_rcp_f32_e32 v13, v12
	s_nop 0
	v_fma_f32 v14, -v12, v13, 1.0
	v_fmac_f32_e32 v13, v14, v13
	v_div_scale_f32 v14, vcc, v8, v11, v8
	v_mul_f32_e32 v15, v14, v13
	v_fma_f32 v16, -v12, v15, v14
	v_fmac_f32_e32 v15, v16, v13
	v_fma_f32 v12, -v12, v15, v14
	v_div_fmas_f32 v12, v12, v13, v15
	v_div_fixup_f32 v11, v12, v11, v8
	v_mul_f32_e32 v12, 0xbfb8aa3b, v9
	v_exp_f32_e32 v12, v12
	s_nop 0
	v_add_f32_e32 v12, 1.0, v12
	v_div_scale_f32 v13, s[10:11], v12, v12, v9
	v_rcp_f32_e32 v14, v13
	s_nop 0
	v_fma_f32 v15, -v13, v14, 1.0
	v_fmac_f32_e32 v14, v15, v14
	v_div_scale_f32 v15, vcc, v9, v12, v9
	v_mul_f32_e32 v16, v15, v14
	v_fma_f32 v17, -v13, v16, v15
	v_fmac_f32_e32 v16, v17, v14
	v_fma_f32 v13, -v13, v16, v15
	v_div_fmas_f32 v13, v13, v14, v16
	v_div_fixup_f32 v12, v13, v12, v9
	v_cvt_pk_bf16_f32 v11, v11, v12
	v_lshl_add_u64 v[12:13], s[30:31], 0, v[18:19]
	v_lshl_add_u64 v[12:13], v[122:123], 1, v[12:13]
	v_add_co_u32_e32 v12, vcc, 0xfffff000, v12
	s_nop 1
	v_addc_co_u32_e32 v13, vcc, -1, v13, vcc
	global_store_dwordx2 v[12:13], v[10:11], off offset:-256 sc1

.LBB0_412:
	v_cmp_gt_u32_e32 vcc, s39, v118
	s_and_saveexec_b64 s[6:7], vcc
	s_cbranch_execz .LBB0_414
	v_mul_f32_e32 v6, 0xbfb8aa3b, v2
	v_exp_f32_e32 v6, v6
	v_mov_b32_e32 v119, v131
	v_add_f32_e32 v6, 1.0, v6
	v_div_scale_f32 v7, s[8:9], v6, v6, v2
	v_rcp_f32_e32 v8, v7
	s_nop 0
	v_fma_f32 v9, -v7, v8, 1.0
	v_fmac_f32_e32 v8, v9, v8
	v_div_scale_f32 v9, vcc, v2, v6, v2
	v_mul_f32_e32 v10, v9, v8
	v_fma_f32 v11, -v7, v10, v9
	v_fmac_f32_e32 v10, v11, v8
	v_fma_f32 v7, -v7, v10, v9
	v_div_fmas_f32 v7, v7, v8, v10
	v_div_fixup_f32 v6, v7, v6, v2
	v_mul_f32_e32 v7, 0xbfb8aa3b, v3
	v_exp_f32_e32 v7, v7
	s_nop 0
	v_add_f32_e32 v7, 1.0, v7
	v_div_scale_f32 v8, s[8:9], v7, v7, v3
	v_rcp_f32_e32 v9, v8
	s_nop 0
	v_fma_f32 v10, -v8, v9, 1.0
	v_fmac_f32_e32 v9, v10, v9
	v_div_scale_f32 v10, vcc, v3, v7, v3
	v_mul_f32_e32 v11, v10, v9
	v_fma_f32 v12, -v8, v11, v10
	v_fmac_f32_e32 v11, v12, v9
	v_fma_f32 v8, -v8, v11, v10
	v_div_fmas_f32 v8, v8, v9, v11
	v_div_fixup_f32 v7, v8, v7, v3
	v_cvt_pk_bf16_f32 v6, v6, v7
	v_mul_f32_e32 v7, 0xbfb8aa3b, v4
	v_exp_f32_e32 v7, v7
	s_nop 0
	v_add_f32_e32 v7, 1.0, v7
	v_div_scale_f32 v8, s[8:9], v7, v7, v4
	v_rcp_f32_e32 v9, v8
	s_nop 0
	v_fma_f32 v10, -v8, v9, 1.0
	v_fmac_f32_e32 v9, v10, v9
	v_div_scale_f32 v10, vcc, v4, v7, v4
	v_mul_f32_e32 v11, v10, v9
	v_fma_f32 v12, -v8, v11, v10
	v_fmac_f32_e32 v11, v12, v9
	v_fma_f32 v8, -v8, v11, v10
	v_div_fmas_f32 v8, v8, v9, v11
	v_div_fixup_f32 v7, v8, v7, v4
	v_mul_f32_e32 v8, 0xbfb8aa3b, v5
	v_exp_f32_e32 v8, v8
	s_nop 0
	v_add_f32_e32 v8, 1.0, v8
	v_div_scale_f32 v9, s[8:9], v8, v8, v5
	v_rcp_f32_e32 v10, v9
	s_nop 0
	v_fma_f32 v11, -v9, v10, 1.0
	v_fmac_f32_e32 v10, v11, v10
	v_div_scale_f32 v11, vcc, v5, v8, v5
	v_mul_f32_e32 v12, v11, v10
	v_fma_f32 v13, -v9, v12, v11
	v_fmac_f32_e32 v12, v13, v10
	v_fma_f32 v9, -v9, v12, v11
	v_div_fmas_f32 v9, v9, v10, v12
	v_div_fixup_f32 v8, v9, v8, v5
	v_cvt_pk_bf16_f32 v7, v7, v8
	v_lshl_add_u64 v[8:9], s[30:31], 0, v[18:19]
	v_lshl_add_u64 v[8:9], v[118:119], 1, v[8:9]
	v_add_co_u32_e32 v8, vcc, 0xfffff000, v8
	s_nop 1
	v_addc_co_u32_e32 v9, vcc, -1, v9, vcc
	global_store_dwordx2 v[8:9], v[6:7], off offset:-256 sc1

.LBB0_415:
	v_cmp_gt_u32_e32 vcc, s91, v120
	v_lshl_add_u64 v[6:7], v[118:119], 2, v[20:21]
	s_and_b64 s[6:7], vcc, s[0:1]
	global_store_dwordx4 v[6:7], v[2:5], off sc1
	s_and_saveexec_b64 s[0:1], s[6:7]
	s_cbranch_execz .LBB0_156
	s_or_b32 s6, s13, s80
	v_cmp_gt_u32_e32 vcc, s40, v118
	v_lshl_or_b32 v8, s6, 8, v22
	v_ashrrev_i32_e32 v9, 31, v8
	v_cndmask_b32_e32 v130, v208, v209, vcc
	v_lshl_add_u64 v[6:7], s[16:17], 0, v[130:131]
	v_lshlrev_b64 v[8:9], 9, v[8:9]
	v_lshl_add_u64 v[6:7], v[6:7], 0, v[8:9]
	v_cndmask_b32_e32 v8, v210, v211, vcc
	v_add_u32_e32 v8, v8, v118
	v_ashrrev_i32_e32 v9, 31, v8
	v_lshl_add_u64 v[6:7], v[8:9], 2, v[6:7]
	global_store_dwordx4 v[6:7], v[2:5], off sc1
	s_branch .LBB0_156

.La1_done:
	s_waitcnt vmcnt(0)
	s_barrier
	v_readlane_b32 s50, v253, 2
	v_readlane_b32 s51, v253, 3
	s_lshl_b32 s22, s80, 2
	s_add_u32 s22, s22, 16
	s_add_u32 s50, s50, s22
	s_addc_u32 s51, s51, 0
	v_cmp_eq_u32_e32 vcc, 0, v0
	s_and_saveexec_b64 s[52:53], vcc
	v_mov_b32_e32 v1, 1
	global_atomic_add v131, v1, s[50:51]
	s_or_b64 exec, exec, s[52:53]
	v_mov_b32_e32 v238, s20
	v_mov_b32_e32 v239, s21
	v_mov_b32_e32 v1, 0x200f0
	ds_write_b64 v1, v[238:239]
	v_readlane_b32 s60, v254, 32
	v_readlane_b32 s54, v254, 34
	v_readlane_b32 s62, v254, 36
	v_readlane_b32 s70, v254, 38
	v_readlane_b32 s76, v254, 40
	v_readlane_b32 s86, v254, 42
	v_readlane_b32 s94, v254, 44
	v_readlane_b32 s58, v254, 46
	v_readlane_b32 s56, v254, 48
	v_readlane_b32 s61, v254, 33
	v_readlane_b32 s55, v254, 35
	v_readlane_b32 s63, v254, 37
	v_readlane_b32 s71, v254, 39
	v_readlane_b32 s77, v254, 41
	v_readlane_b32 s87, v254, 43
	v_readlane_b32 s95, v254, 45
	v_readlane_b32 s59, v254, 47
	v_readlane_b32 s57, v254, 49
	s_waitcnt lgkmcnt(0)
	s_barrier
	s_branch .La0_after

.LBB0_419:
	s_barrier
	s_and_b32 s0, s2, 7
	s_lshr_b32 s0, s0, 1
	s_lshl_b32 s0, s0, 3
	s_lshr_b32 s1, s2, 3
	s_and_b32 s1, s1, 7
	s_add_u32 s0, s0, s1
	s_lshl_b32 s1, s80, 5
	s_add_u32 s0, s0, s1
	s_add_u32 s0, s0, 64
	s_lshl_b32 s0, s0, 2
	v_readlane_b32 s4, v253, 2
	v_readlane_b32 s5, v253, 3
	s_nop 0
	s_add_u32 s6, s4, s0
	s_addc_u32 s7, s5, 0
	s_lshl_b32 s1, s80, 2
	s_add_u32 s1, s1, 16
	s_add_u32 s4, s4, s1
	s_addc_u32 s5, s5, 0
	v_cmp_eq_u32_e32 vcc, 0, v0
	s_and_saveexec_b64 s[8:9], vcc
	v_mov_b32_e32 v1, 1
	global_atomic_add v131, v1, s[6:7]
	global_atomic_add v131, v1, s[4:5]
	s_or_b64 exec, exec, s[8:9]
.La0_after:
.LBB0_420:
	s_andn2_b64 vcc, exec, s[24:25]
	s_mov_b64 s[0:1], -1
	s_mov_b32 s72, s67
	s_waitcnt vmcnt(0) lgkmcnt(0)
	s_barrier
	s_cbranch_vccnz .LBB0_148
	s_waitcnt vmcnt(0)
	s_barrier
	s_mov_b64 s[0:1], exec
	v_readlane_b32 s4, v253, 0
	v_readlane_b32 s5, v253, 1
	s_and_b64 s[4:5], s[0:1], s[4:5]
	s_mov_b64 exec, s[4:5]
	s_branch .LBB0_147
	s_getreg_b32 s4, hwreg(HW_REG_XCC_ID, 0, 4)
	s_and_b32 s10, s4, 15
	v_readlane_b32 s4, v254, 25
	s_waitcnt vmcnt(0) expcnt(0) lgkmcnt(0)
	s_nop 0
	v_mov_b32_e32 v1, s4
	ds_read_b32 v3, v1
	v_readlane_b32 s4, v254, 23
	s_waitcnt lgkmcnt(0)
	v_cmp_ne_u32_e32 vcc, 0, v3
	v_mov_b32_e32 v1, s4
	ds_read_b32 v2, v1
	s_cbranch_vccnz .LBB0_437
	v_readlane_b32 s6, v253, 5
	v_readlane_b32 s7, v253, 6
	s_load_dwordx2 s[4:5], s[6:7], 0x4
	s_mov_b32 s12, 1
	s_waitcnt lgkmcnt(0)
	s_mul_i32 s11, s4, s65
	s_mul_i32 s11, s11, s5
	s_branch .LBB0_425

.LBB0_480:
	v_cmp_lt_i32_e32 vcc, s90, v2
	s_cbranch_vccnz .LBB0_515
	v_add_u32_e32 v2, 0x80, v2
	v_and_b32_e32 v2, 0xff, v2
	v_lshlrev_b32_e32 v10, 5, v2
	v_add_u32_e32 v4, v10, v98
	s_waitcnt lgkmcnt(0)
	v_mov_b64_e32 v[2:3], s[28:29]
	v_mad_i64_i32 v[2:3], s[10:11], v4, s36, v[2:3]
	v_lshlrev_b32_e32 v130, 2, v100
	v_lshl_add_u64 v[2:3], v[2:3], 0, v[130:131]
	v_add_co_u32_e32 v2, vcc, 0x1000, v2
	s_nop 1
	v_addc_co_u32_e32 v3, vcc, 0, v3, vcc
	v_readfirstlane_b32 s14, v0
	s_cmp_lt_u32 s14, 64
	s_cbranch_scc0 .Ldf3_go
	v_readfirstlane_b32 s14, v10
	s_lshr_b32 s14, s14, 8
	s_lshl_b32 s15, s80, 5
	s_add_u32 s14, s14, s15
	s_add_u32 s14, s14, 64
	s_lshl_b32 s14, s14, 2
	v_readlane_b32 s20, v253, 2
	v_readlane_b32 s21, v253, 3
	s_nop 0
	s_add_u32 s20, s20, s14
	s_addc_u32 s21, s21, 0
	s_mov_b32 s14, 0
.Ldf3_poll:
	global_load_dword v34, v131, s[20:21] sc1
	s_waitcnt vmcnt(0)
	v_readfirstlane_b32 s15, v34
	s_cmpk_ge_u32 s15, 8
	s_cbranch_scc1 .Ldf3_ok
	s_sleep 8
	s_add_u32 s14, s14, 1
	s_cmp_lt_u32 s14, 0x1388
	s_cbranch_scc1 .Ldf3_poll

.Ldf3_go:
	s_barrier
	v_add_u32_e32 v4, v10, v98
	v_mov_b64_e32 v[42:43], s[28:29]
	v_mad_i64_i32 v[42:43], s[10:11], v4, s36, v[42:43]
	v_lshl_add_u64 v[42:43], v[42:43], 0, v[130:131]
	v_add_co_u32_e32 v42, vcc, 0x1000, v42
	s_nop 1
	v_addc_co_u32_e32 v43, vcc, 0, v43, vcc
	global_load_dword v34, v[42:43], off offset:1024
	v_add_u32_e32 v4, v10, v227
	v_mov_b64_e32 v[42:43], s[28:29]
	v_mad_i64_i32 v[42:43], s[10:11], v4, s36, v[42:43]
	v_lshl_add_u64 v[42:43], v[42:43], 0, v[130:131]
	v_add_co_u32_e32 v42, vcc, 0x1000, v42
	s_nop 1
	v_addc_co_u32_e32 v43, vcc, 0, v43, vcc
	global_load_dword v35, v[42:43], off offset:1024
	v_add_u32_e32 v4, v10, v228
	v_mov_b64_e32 v[42:43], s[28:29]
	v_mad_i64_i32 v[42:43], s[10:11], v4, s36, v[42:43]
	v_lshl_add_u64 v[42:43], v[42:43], 0, v[130:131]
	v_add_co_u32_e32 v42, vcc, 0x1000, v42
	s_nop 1
	v_addc_co_u32_e32 v43, vcc, 0, v43, vcc
	global_load_dword v36, v[42:43], off offset:1024
	v_add_u32_e32 v4, v10, v229
	v_mov_b64_e32 v[42:43], s[28:29]
	v_mad_i64_i32 v[42:43], s[10:11], v4, s36, v[42:43]
	v_lshl_add_u64 v[42:43], v[42:43], 0, v[130:131]
	v_add_co_u32_e32 v42, vcc, 0x1000, v42
	s_nop 1
	v_addc_co_u32_e32 v43, vcc, 0, v43, vcc
	global_load_dword v37, v[42:43], off offset:1024
	v_add_u32_e32 v4, v10, v230
	v_mov_b64_e32 v[42:43], s[28:29]
	v_mad_i64_i32 v[42:43], s[10:11], v4, s36, v[42:43]
	v_lshl_add_u64 v[42:43], v[42:43], 0, v[130:131]
	v_add_co_u32_e32 v42, vcc, 0x1000, v42
	s_nop 1
	v_addc_co_u32_e32 v43, vcc, 0, v43, vcc
	global_load_dword v38, v[42:43], off offset:1024
	v_add_u32_e32 v4, v10, v231
	v_mov_b64_e32 v[42:43], s[28:29]
	v_mad_i64_i32 v[42:43], s[10:11], v4, s36, v[42:43]
	v_lshl_add_u64 v[42:43], v[42:43], 0, v[130:131]
	v_add_co_u32_e32 v42, vcc, 0x1000, v42
	s_nop 1
	v_addc_co_u32_e32 v43, vcc, 0, v43, vcc
	global_load_dword v39, v[42:43], off offset:1024
	v_add_u32_e32 v4, v10, v232
	v_mov_b64_e32 v[42:43], s[28:29]
	v_mad_i64_i32 v[42:43], s[10:11], v4, s36, v[42:43]
	v_lshl_add_u64 v[42:43], v[42:43], 0, v[130:131]
	v_add_co_u32_e32 v42, vcc, 0x1000, v42
	s_nop 1
	v_addc_co_u32_e32 v43, vcc, 0, v43, vcc
	global_load_dword v40, v[42:43], off offset:1024
	v_add_u32_e32 v4, v10, v233
	v_mov_b64_e32 v[42:43], s[28:29]
	v_mad_i64_i32 v[42:43], s[10:11], v4, s36, v[42:43]
	v_lshl_add_u64 v[42:43], v[42:43], 0, v[130:131]
	v_add_co_u32_e32 v42, vcc, 0x1000, v42
	s_nop 1
	v_addc_co_u32_e32 v43, vcc, 0, v43, vcc
	global_load_dword v41, v[42:43], off offset:1024
	s_waitcnt vmcnt(7)
	v_mov_b32_e32 v2, v34
	s_and_saveexec_b64 s[10:11], s[4:5]
	s_xor_b64 s[10:11], exec, s[10:11]
	s_cbranch_execz .LBB0_483
	s_waitcnt vmcnt(0)
	v_cvt_pk_bf16_f32 v2, v2, v131
	ds_write_b16 v234, v2 offset:4480

.Ldf_qpoll:
	global_load_dword v2, v131, s[4:5] sc1
	s_waitcnt vmcnt(0)
	v_readfirstlane_b32 s1, v2
	s_cmpk_ge_u32 s1, 0x1a0
	s_cbranch_scc1 .Ldf_qok
	s_sleep 16
	s_add_u32 s6, s6, 1
	s_cmp_lt_u32 s6, 0x1388
	s_cbranch_scc1 .Ldf_qpoll

.Lc2_poll:
	global_load_dword v198, v131, s[8:9] sc1
	global_load_dword v199, v131, s[6:7] sc1
	s_waitcnt vmcnt(0)
	v_readfirstlane_b32 s0, v198
	v_readfirstlane_b32 s1, v199
	s_cmpk_ge_u32 s0, 0x100
	s_cselect_b32 s0, 1, 0
	s_cmpk_ge_u32 s1, 16
	s_cselect_b32 s1, 1, 0
	s_and_b32 s0, s0, s1
	s_cmp_eq_u32 s0, 1
	s_cbranch_scc1 .Lc2_polled
	s_sleep 16
	s_add_u32 s14, s14, 1
	s_cmp_lt_u32 s14, 0x1388
	s_cbranch_scc1 .Lc2_poll
